# GEMM K-loops: first iteration peeled with C=0 on the first MFMA of every accumulator; per-tile accumulator zeroing removed
# speedup vs baseline: 1.0039x; 1.0039x over previous
; #define PG8_STAGE(bufoff, gbase, voff) do { _Pragma("unroll") for (int _i = 0; _i < 2; ++_i) \
;         __builtin_amdgcn_global_load_lds((const unsigned*)((const char*)(gbase) + (voff)[_i]), (LAS unsigned*)(lds + (bufoff) + ldsw + _i * 8192), 16, 0, 0); } while (0)
; #define PG8_LDA(dst, b, h) do { _Pragma("unroll") for (int m = 0; m < 4; ++m) _Pragma("unroll") for (int k = 0; k < 2; ++k) dst[m][k] = *(const LAS bf16x8*)(lds + PG8_SA(b, h) + aoff + m * 2048 + k * 1024); } while (0)
; #define PG8_LDB(dst, b, h) do { _Pragma("unroll") for (int n = 0; n < 2; ++n) _Pragma("unroll") for (int k = 0; k < 2; ++k) dst[n][k] = *(const LAS bf16x8*)(lds + PG8_SB(b, h) + boff + n * 2048 + k * 1024); } while (0)
; #define PG8_MMA(ai, bj, At, Bt) do { __builtin_amdgcn_s_setprio(1); _Pragma("unroll") for (int m = 0; m < 4; ++m) _Pragma("unroll") for (int n = 0; n < 2; ++n) _Pragma("unroll") for (int k = 0; k < 2; ++k) \
;         acc[ai][bj][m][n] = __builtin_amdgcn_mfma_f32_16x16x32_bf16(Bt[n][k], At[m][k], acc[ai][bj][m][n], 0, 0, 0); __builtin_amdgcn_s_setprio(0); } while (0)
; #define PG8_WAIT_V(n) asm volatile("s_waitcnt vmcnt(" #n ")" ::: "memory")
; #define PG8_WAIT_L(n) asm volatile("s_waitcnt lgkmcnt(" #n ")" ::: "memory")
; #define PG8_BAR __builtin_amdgcn_s_barrier()
; #define PG8_SCHED __builtin_amdgcn_sched_barrier(0)
; DI void gemm_phase(LAS unsigned char* lds, const Gemm g, const StaticOrder& S, const Epi& E) {
;     ...
;         for (int t = 0; t < nt; t += 2) {
;             const bool last = (t == nt - 2);
;             const char* a1 = cA + (size_t)(t + 1) * kstep;
;             const char* a2 = last ? nA : cA + (size_t)(t + 2) * kstep; const char* b2 = last ? nB : cB + (size_t)(t + 2) * kstep;
;             const char* a3 = a2 + kstep; const char* b3 = b2 + kstep;
;             PG8_LDB(B0, 0, 0); PG8_LDB(B1, 0, 1); PG8_SCHED; PG8_LDA(At, 0, 0); PG8_STAGE(PG8_SA(1, 1), a1 + hsA, voffA);
;             PG8_WAIT_V(8); PG8_WAIT_L(0); PG8_BAR; PG8_MMA(0, 0, At, B0); PG8_MMA(0, 1, At, B1); PG8_BAR; PG8_SCHED;
.LBB0_176:
	s_ashr_i32 s23, s22, 31
	s_lshl_b64 s[24:25], s[22:23], 20
	s_add_u32 s24, s62, s24
	s_addc_u32 s25, s63, s25
	s_and_b64 s[26:27], s[2:3], exec
	s_cselect_b32 s5, s25, s31
	s_cselect_b32 s23, s24, s30
	s_ashr_i32 s21, s20, 31
	s_lshl_b64 s[26:27], s[20:21], 20
	s_add_u32 s26, s0, s26
	s_addc_u32 s27, s1, s27
	s_and_b64 s[38:39], s[2:3], exec
	s_cselect_b32 s21, s27, s35
	s_cselect_b32 s29, s26, s34
	s_add_u32 s30, s30, 0x80080
	s_addc_u32 s31, s31, 0
	s_add_u32 s54, s34, 0x100
	v_mov_b32_e32 v0, 0
	s_addc_u32 s55, s35, 0
	s_mov_b32 s56, -2
	s_cmp_eq_u32 s4, 10
	s_cselect_b64 vcc, -1, 0
	ds_read_b128 v[152:155], v149
	ds_read_b128 v[156:159], v149 offset:1024
	ds_read_b128 v[160:163], v149 offset:2048
	ds_read_b128 v[170:173], v149 offset:3072
	ds_read_b128 v[174:177], v150
	ds_read_b128 v[178:181], v150 offset:1024
	ds_read_b128 v[182:185], v150 offset:2048
	ds_read_b128 v[186:189], v150 offset:3072
	s_add_u32 s34, s30, 0xfff80080
	s_addc_u32 s35, s31, -1
	s_cmp_eq_u32 s56, 28
	s_cselect_b32 s39, s5, s35
	s_cselect_b32 s38, s23, s34
	s_cselect_b32 s35, s21, s55
	s_cselect_b32 s34, s29, s54
	s_add_i32 m0, s13, 0xc000
	ds_read_b128 v[190:193], v151
	ds_read_b128 v[194:197], v151 offset:1024
	ds_read_b128 v[198:201], v151 offset:2048
	ds_read_b128 v[202:205], v151 offset:3072
	ds_read_b128 v[206:209], v151 offset:4096
	ds_read_b128 v[210:213], v151 offset:5120
	ds_read_b128 v[214:217], v151 offset:6144
	ds_read_b128 v[218:221], v151 offset:7168
	global_load_lds_dwordx4 v136, s[30:31]
	s_add_i32 m0, s13, 0xe000
	s_nop 0
	global_load_lds_dwordx4 v138, s[30:31]
	s_waitcnt vmcnt(8)
	s_waitcnt lgkmcnt(0)
	s_barrier
	s_setprio 1
	s_waitcnt lgkmcnt(0)
	v_mfma_f32_16x16x32_bf16 v[124:127], v[152:155], v[190:193], 0
	v_mfma_f32_16x16x32_bf16 v[124:127], v[156:159], v[194:197], v[124:127]
	v_mfma_f32_16x16x32_bf16 v[120:123], v[170:173], v[194:197], 0
	v_mfma_f32_16x16x32_bf16 v[120:123], v[160:163], v[190:193], v[120:123]
	v_mfma_f32_16x16x32_bf16 v[108:111], v[160:163], v[198:201], 0
	v_mfma_f32_16x16x32_bf16 v[108:111], v[170:173], v[202:205], v[108:111]
	v_mfma_f32_16x16x32_bf16 v[116:119], v[156:159], v[202:205], 0
	v_mfma_f32_16x16x32_bf16 v[116:119], v[152:155], v[198:201], v[116:119]
	v_mfma_f32_16x16x32_bf16 v[100:103], v[152:155], v[206:209], 0
	v_mfma_f32_16x16x32_bf16 v[100:103], v[156:159], v[210:213], v[100:103]
	v_mfma_f32_16x16x32_bf16 v[92:95], v[170:173], v[210:213], 0
	v_mfma_f32_16x16x32_bf16 v[92:95], v[160:163], v[206:209], v[92:95]
	v_mfma_f32_16x16x32_bf16 v[76:79], v[160:163], v[214:217], 0
	v_mfma_f32_16x16x32_bf16 v[76:79], v[170:173], v[218:221], v[76:79]
	v_mfma_f32_16x16x32_bf16 v[84:87], v[156:159], v[218:221], 0
	v_mfma_f32_16x16x32_bf16 v[84:87], v[152:155], v[214:217], v[84:87]
	s_setprio 0
	s_setprio 1
	s_cbranch_vccnz .Lp1pre_skip_1
	v_mfma_f32_16x16x32_bf16 v[112:115], v[174:177], v[190:193], 0
	v_mfma_f32_16x16x32_bf16 v[112:115], v[178:181], v[194:197], v[112:115]
	v_mfma_f32_16x16x32_bf16 v[104:107], v[186:189], v[194:197], 0
	v_mfma_f32_16x16x32_bf16 v[104:107], v[182:185], v[190:193], v[104:107]
	v_mfma_f32_16x16x32_bf16 v[88:91], v[182:185], v[198:201], 0
	v_mfma_f32_16x16x32_bf16 v[88:91], v[186:189], v[202:205], v[88:91]
	v_mfma_f32_16x16x32_bf16 v[96:99], v[178:181], v[202:205], 0
	v_mfma_f32_16x16x32_bf16 v[96:99], v[174:177], v[198:201], v[96:99]
	v_mfma_f32_16x16x32_bf16 v[80:83], v[174:177], v[206:209], 0
	v_mfma_f32_16x16x32_bf16 v[80:83], v[178:181], v[210:213], v[80:83]
	v_mfma_f32_16x16x32_bf16 v[72:75], v[186:189], v[210:213], 0
	v_mfma_f32_16x16x32_bf16 v[72:75], v[182:185], v[206:209], v[72:75]
	v_mfma_f32_16x16x32_bf16 v[64:67], v[182:185], v[214:217], 0
	v_mfma_f32_16x16x32_bf16 v[64:67], v[186:189], v[218:221], v[64:67]
	v_mfma_f32_16x16x32_bf16 v[68:71], v[178:181], v[218:221], 0
	v_mfma_f32_16x16x32_bf16 v[68:71], v[174:177], v[214:217], v[68:71]
; #define PG8_STAGE(bufoff, gbase, voff) do { _Pragma("unroll") for (int _i = 0; _i < 2; ++_i) \
;         __builtin_amdgcn_global_load_lds((const unsigned*)((const char*)(gbase) + (voff)[_i]), (LAS unsigned*)(lds + (bufoff) + ldsw + _i * 8192), 16, 0, 0); } while (0)
; #define PG8_LDA(dst, b, h) do { _Pragma("unroll") for (int m = 0; m < 4; ++m) _Pragma("unroll") for (int k = 0; k < 2; ++k) dst[m][k] = *(const LAS bf16x8*)(lds + PG8_SA(b, h) + aoff + m * 2048 + k * 1024); } while (0)
; #define PG8_LDB(dst, b, h) do { _Pragma("unroll") for (int n = 0; n < 2; ++n) _Pragma("unroll") for (int k = 0; k < 2; ++k) dst[n][k] = *(const LAS bf16x8*)(lds + PG8_SB(b, h) + boff + n * 2048 + k * 1024); } while (0)
; #define PG8_MMA(ai, bj, At, Bt) do { __builtin_amdgcn_s_setprio(1); _Pragma("unroll") for (int m = 0; m < 4; ++m) _Pragma("unroll") for (int n = 0; n < 2; ++n) _Pragma("unroll") for (int k = 0; k < 2; ++k) \
;         acc[ai][bj][m][n] = __builtin_amdgcn_mfma_f32_16x16x32_bf16(Bt[n][k], At[m][k], acc[ai][bj][m][n], 0, 0, 0); __builtin_amdgcn_s_setprio(0); } while (0)
; #define PG8_WAIT_V(n) asm volatile("s_waitcnt vmcnt(" #n ")" ::: "memory")
; #define PG8_WAIT_L(n) asm volatile("s_waitcnt lgkmcnt(" #n ")" ::: "memory")
; #define PG8_BAR __builtin_amdgcn_s_barrier()
; #define PG8_SCHED __builtin_amdgcn_sched_barrier(0)
; DI void gemm_phase(LAS unsigned char* lds, const Gemm g, const StaticOrder& S, const Epi& E) {
;     ...
;             PG8_LDA(At, 0, 1); PG8_STAGE(PG8_SB(0, 0), b2, voffB); PG8_STAGE(PG8_SB(0, 1), b2 + hsB, voffB); PG8_STAGE(PG8_SA(0, 0), a2, voffA);
;             PG8_WAIT_V(8); PG8_WAIT_L(0); PG8_BAR; PG8_MMA(1, 0, At, B0); PG8_MMA(1, 1, At, B1); PG8_BAR; PG8_SCHED;
;             PG8_LDB(B0, 1, 0); PG8_LDB(B1, 1, 1); PG8_SCHED; PG8_LDA(At, 1, 0); PG8_STAGE(PG8_SA(0, 1), a2 + hsA, voffA);
;             PG8_WAIT_V(8); PG8_WAIT_L(0); PG8_BAR; PG8_MMA(0, 0, At, B0); PG8_MMA(0, 1, At, B1); PG8_BAR; PG8_SCHED;
.Lp1pre_skip_1:
	s_setprio 0
	s_barrier
	s_add_i32 s46, s50, s12
	s_add_u32 s98, s34, 0x80
	s_addc_u32 s99, s35, 0
	s_mov_b32 m0, s46
	ds_read_b128 v[190:193], v151 offset:16384
	ds_read_b128 v[194:197], v151 offset:17408
	ds_read_b128 v[198:201], v151 offset:18432
	ds_read_b128 v[202:205], v151 offset:19456
	ds_read_b128 v[206:209], v151 offset:20480
	ds_read_b128 v[210:213], v151 offset:21504
	ds_read_b128 v[214:217], v151 offset:22528
	ds_read_b128 v[218:221], v151 offset:23552
	global_load_lds_dwordx4 v130, s[34:35]
	s_add_i32 m0, s46, 0x2000
	s_add_u32 s46, s34, 0x80000
	s_addc_u32 s47, s35, 0
	s_add_i32 s57, s51, s12
	global_load_lds_dwordx4 v134, s[34:35]
	s_mov_b32 m0, s57
	s_nop 0
	global_load_lds_dwordx4 v130, s[46:47]
	s_add_i32 m0, s57, 0x2000
	s_nop 0
	global_load_lds_dwordx4 v134, s[46:47]
	s_add_u32 s100, s38, 0x80
	s_addc_u32 s101, s39, 0
	s_mov_b32 m0, s13
	s_nop 0
	global_load_lds_dwordx4 v128, s[38:39]
	s_mov_b32 m0, s33
	s_nop 0
	global_load_lds_dwordx4 v132, s[38:39]
	s_waitcnt vmcnt(8)
	s_waitcnt lgkmcnt(0)
	s_barrier
	s_setprio 1
	s_waitcnt lgkmcnt(0)
	v_mfma_f32_16x16x32_bf16 v[60:63], v[152:155], v[190:193], 0
	v_mfma_f32_16x16x32_bf16 v[60:63], v[156:159], v[194:197], v[60:63]
	v_mfma_f32_16x16x32_bf16 v[56:59], v[170:173], v[194:197], 0
	v_mfma_f32_16x16x32_bf16 v[56:59], v[160:163], v[190:193], v[56:59]
	v_mfma_f32_16x16x32_bf16 v[44:47], v[160:163], v[198:201], 0
	v_mfma_f32_16x16x32_bf16 v[44:47], v[170:173], v[202:205], v[44:47]
	v_mfma_f32_16x16x32_bf16 v[52:55], v[156:159], v[202:205], 0
	v_mfma_f32_16x16x32_bf16 v[52:55], v[152:155], v[198:201], v[52:55]
	v_mfma_f32_16x16x32_bf16 v[36:39], v[152:155], v[206:209], 0
	v_mfma_f32_16x16x32_bf16 v[36:39], v[156:159], v[210:213], v[36:39]
	v_mfma_f32_16x16x32_bf16 v[28:31], v[170:173], v[210:213], 0
	v_mfma_f32_16x16x32_bf16 v[28:31], v[160:163], v[206:209], v[28:31]
	v_mfma_f32_16x16x32_bf16 v[12:15], v[160:163], v[214:217], 0
	v_mfma_f32_16x16x32_bf16 v[12:15], v[170:173], v[218:221], v[12:15]
	v_mfma_f32_16x16x32_bf16 v[20:23], v[156:159], v[218:221], 0
	v_mfma_f32_16x16x32_bf16 v[20:23], v[152:155], v[214:217], v[20:23]
	s_setprio 0
	s_setprio 1
	s_cbranch_vccnz .Lp1pre_skip_2
	v_mfma_f32_16x16x32_bf16 v[48:51], v[174:177], v[190:193], 0
	v_mfma_f32_16x16x32_bf16 v[48:51], v[178:181], v[194:197], v[48:51]
	v_mfma_f32_16x16x32_bf16 v[40:43], v[186:189], v[194:197], 0
	v_mfma_f32_16x16x32_bf16 v[40:43], v[182:185], v[190:193], v[40:43]
	v_mfma_f32_16x16x32_bf16 v[24:27], v[182:185], v[198:201], 0
	v_mfma_f32_16x16x32_bf16 v[24:27], v[186:189], v[202:205], v[24:27]
	v_mfma_f32_16x16x32_bf16 v[32:35], v[178:181], v[202:205], 0
	v_mfma_f32_16x16x32_bf16 v[32:35], v[174:177], v[198:201], v[32:35]
	v_mfma_f32_16x16x32_bf16 v[16:19], v[174:177], v[206:209], 0
	v_mfma_f32_16x16x32_bf16 v[16:19], v[178:181], v[210:213], v[16:19]
	v_mfma_f32_16x16x32_bf16 v[8:11], v[186:189], v[210:213], 0
	v_mfma_f32_16x16x32_bf16 v[8:11], v[182:185], v[206:209], v[8:11]
	v_mfma_f32_16x16x32_bf16 v[0:3], v[182:185], v[214:217], 0
	v_mfma_f32_16x16x32_bf16 v[0:3], v[186:189], v[218:221], v[0:3]
	v_mfma_f32_16x16x32_bf16 v[4:7], v[178:181], v[218:221], 0
	v_mfma_f32_16x16x32_bf16 v[4:7], v[174:177], v[214:217], v[4:7]

; #define PG8_STAGE(bufoff, gbase, voff) do { _Pragma("unroll") for (int _i = 0; _i < 2; ++_i) \
;         __builtin_amdgcn_global_load_lds((const unsigned*)((const char*)(gbase) + (voff)[_i]), (LAS unsigned*)(lds + (bufoff) + ldsw + _i * 8192), 16, 0, 0); } while (0)
; #define PG8_LDA(dst, b, h) do { _Pragma("unroll") for (int m = 0; m < 4; ++m) _Pragma("unroll") for (int k = 0; k < 2; ++k) dst[m][k] = *(const LAS bf16x8*)(lds + PG8_SA(b, h) + aoff + m * 2048 + k * 1024); } while (0)
; #define PG8_LDB(dst, b, h) do { _Pragma("unroll") for (int n = 0; n < 2; ++n) _Pragma("unroll") for (int k = 0; k < 2; ++k) dst[n][k] = *(const LAS bf16x8*)(lds + PG8_SB(b, h) + boff + n * 2048 + k * 1024); } while (0)
; #define PG8_MMA(ai, bj, At, Bt) do { __builtin_amdgcn_s_setprio(1); _Pragma("unroll") for (int m = 0; m < 4; ++m) _Pragma("unroll") for (int n = 0; n < 2; ++n) _Pragma("unroll") for (int k = 0; k < 2; ++k) \
;         acc[ai][bj][m][n] = __builtin_amdgcn_mfma_f32_16x16x32_bf16(Bt[n][k], At[m][k], acc[ai][bj][m][n], 0, 0, 0); __builtin_amdgcn_s_setprio(0); } while (0)
; #define PG8_WAIT_V(n) asm volatile("s_waitcnt vmcnt(" #n ")" ::: "memory")
; #define PG8_WAIT_L(n) asm volatile("s_waitcnt lgkmcnt(" #n ")" ::: "memory")
; #define PG8_BAR __builtin_amdgcn_s_barrier()
; #define PG8_SCHED __builtin_amdgcn_sched_barrier(0)
; DI void gemm_phase(LAS unsigned char* lds, const Gemm g, const StaticOrder& S, const Epi& E) {
;     ...
;         for (int t = 0; t < nt; t += 2) {
;             const bool last = (t == nt - 2);
;             const char* a1 = cA + (size_t)(t + 1) * kstep;
;             const char* a2 = last ? nA : cA + (size_t)(t + 2) * kstep; const char* b2 = last ? nB : cB + (size_t)(t + 2) * kstep;
;             const char* a3 = a2 + kstep; const char* b3 = b2 + kstep;
;             PG8_LDB(B0, 0, 0); PG8_LDB(B1, 0, 1); PG8_SCHED; PG8_LDA(At, 0, 0); PG8_STAGE(PG8_SA(1, 1), a1 + hsA, voffA);
;             PG8_WAIT_V(8); PG8_WAIT_L(0); PG8_BAR; PG8_MMA(0, 0, At, B0); PG8_MMA(0, 1, At, B1); PG8_BAR; PG8_SCHED;
.Lp1pre_skip_4:
	s_setprio 0
	s_barrier
	s_add_i32 s56, s56, 2
	s_add_u32 s30, s30, 0x100
	s_addc_u32 s31, s31, 0
	s_add_u32 s54, s54, 0x100
	s_addc_u32 s55, s55, 0
	s_cmp_gt_u32 s56, 29
.LBB0_177:
	ds_read_b128 v[152:155], v149
	ds_read_b128 v[156:159], v149 offset:1024
	ds_read_b128 v[160:163], v149 offset:2048
	ds_read_b128 v[170:173], v149 offset:3072
	ds_read_b128 v[174:177], v150
	ds_read_b128 v[178:181], v150 offset:1024
	ds_read_b128 v[182:185], v150 offset:2048
	ds_read_b128 v[186:189], v150 offset:3072
	s_add_u32 s34, s30, 0xfff80080
	s_addc_u32 s35, s31, -1
	s_cmp_eq_u32 s56, 28
	s_cselect_b32 s39, s5, s35
	s_cselect_b32 s38, s23, s34
	s_cselect_b32 s35, s21, s55
	s_cselect_b32 s34, s29, s54
	s_add_i32 m0, s13, 0xc000
	ds_read_b128 v[190:193], v151
	ds_read_b128 v[194:197], v151 offset:1024
	ds_read_b128 v[198:201], v151 offset:2048
	ds_read_b128 v[202:205], v151 offset:3072
	ds_read_b128 v[206:209], v151 offset:4096
	ds_read_b128 v[210:213], v151 offset:5120
	ds_read_b128 v[214:217], v151 offset:6144
	ds_read_b128 v[218:221], v151 offset:7168
	global_load_lds_dwordx4 v136, s[30:31]
	s_add_i32 m0, s13, 0xe000
	s_nop 0
	global_load_lds_dwordx4 v138, s[30:31]
	s_waitcnt vmcnt(8)
	s_waitcnt lgkmcnt(0)
	s_barrier
	s_setprio 1
	s_waitcnt lgkmcnt(0)
	v_mfma_f32_16x16x32_bf16 v[124:127], v[152:155], v[190:193], v[124:127]
	v_mfma_f32_16x16x32_bf16 v[124:127], v[156:159], v[194:197], v[124:127]
	v_mfma_f32_16x16x32_bf16 v[120:123], v[170:173], v[194:197], v[120:123]
	v_mfma_f32_16x16x32_bf16 v[120:123], v[160:163], v[190:193], v[120:123]
	v_mfma_f32_16x16x32_bf16 v[108:111], v[160:163], v[198:201], v[108:111]
	v_mfma_f32_16x16x32_bf16 v[108:111], v[170:173], v[202:205], v[108:111]
	v_mfma_f32_16x16x32_bf16 v[116:119], v[156:159], v[202:205], v[116:119]
	v_mfma_f32_16x16x32_bf16 v[116:119], v[152:155], v[198:201], v[116:119]
	v_mfma_f32_16x16x32_bf16 v[100:103], v[152:155], v[206:209], v[100:103]
	v_mfma_f32_16x16x32_bf16 v[100:103], v[156:159], v[210:213], v[100:103]
	v_mfma_f32_16x16x32_bf16 v[92:95], v[170:173], v[210:213], v[92:95]
	v_mfma_f32_16x16x32_bf16 v[92:95], v[160:163], v[206:209], v[92:95]
	v_mfma_f32_16x16x32_bf16 v[76:79], v[160:163], v[214:217], v[76:79]
	v_mfma_f32_16x16x32_bf16 v[76:79], v[170:173], v[218:221], v[76:79]
	v_mfma_f32_16x16x32_bf16 v[84:87], v[156:159], v[218:221], v[84:87]
	v_mfma_f32_16x16x32_bf16 v[84:87], v[152:155], v[214:217], v[84:87]
	s_setprio 0
	s_setprio 1
	s_cbranch_vccnz .Lp1_skip_1
	v_mfma_f32_16x16x32_bf16 v[112:115], v[174:177], v[190:193], v[112:115]
	v_mfma_f32_16x16x32_bf16 v[112:115], v[178:181], v[194:197], v[112:115]
	v_mfma_f32_16x16x32_bf16 v[104:107], v[186:189], v[194:197], v[104:107]
	v_mfma_f32_16x16x32_bf16 v[104:107], v[182:185], v[190:193], v[104:107]
	v_mfma_f32_16x16x32_bf16 v[88:91], v[182:185], v[198:201], v[88:91]
	v_mfma_f32_16x16x32_bf16 v[88:91], v[186:189], v[202:205], v[88:91]
	v_mfma_f32_16x16x32_bf16 v[96:99], v[178:181], v[202:205], v[96:99]
	v_mfma_f32_16x16x32_bf16 v[96:99], v[174:177], v[198:201], v[96:99]
	v_mfma_f32_16x16x32_bf16 v[80:83], v[174:177], v[206:209], v[80:83]
	v_mfma_f32_16x16x32_bf16 v[80:83], v[178:181], v[210:213], v[80:83]
	v_mfma_f32_16x16x32_bf16 v[72:75], v[186:189], v[210:213], v[72:75]
	v_mfma_f32_16x16x32_bf16 v[72:75], v[182:185], v[206:209], v[72:75]
	v_mfma_f32_16x16x32_bf16 v[64:67], v[182:185], v[214:217], v[64:67]
	v_mfma_f32_16x16x32_bf16 v[64:67], v[186:189], v[218:221], v[64:67]
	v_mfma_f32_16x16x32_bf16 v[68:71], v[178:181], v[218:221], v[68:71]
	v_mfma_f32_16x16x32_bf16 v[68:71], v[174:177], v[214:217], v[68:71]

; #define PG8_STAGE(bufoff, gbase, voff) do { _Pragma("unroll") for (int _i = 0; _i < 2; ++_i) \
;         __builtin_amdgcn_global_load_lds((const unsigned*)((const char*)(gbase) + (voff)[_i]), (LAS unsigned*)(lds + (bufoff) + ldsw + _i * 8192), 16, 0, 0); } while (0)
; #define PG8_LDA(dst, b, h) do { _Pragma("unroll") for (int m = 0; m < 4; ++m) _Pragma("unroll") for (int k = 0; k < 2; ++k) dst[m][k] = *(const LAS bf16x8*)(lds + PG8_SA(b, h) + aoff + m * 2048 + k * 1024); } while (0)
; #define PG8_LDB(dst, b, h) do { _Pragma("unroll") for (int n = 0; n < 2; ++n) _Pragma("unroll") for (int k = 0; k < 2; ++k) dst[n][k] = *(const LAS bf16x8*)(lds + PG8_SB(b, h) + boff + n * 2048 + k * 1024); } while (0)
; #define PG8_MMA(ai, bj, At, Bt) do { __builtin_amdgcn_s_setprio(1); _Pragma("unroll") for (int m = 0; m < 4; ++m) _Pragma("unroll") for (int n = 0; n < 2; ++n) _Pragma("unroll") for (int k = 0; k < 2; ++k) \
;         acc[ai][bj][m][n] = __builtin_amdgcn_mfma_f32_16x16x32_bf16(Bt[n][k], At[m][k], acc[ai][bj][m][n], 0, 0, 0); __builtin_amdgcn_s_setprio(0); } while (0)
; #define PG8_WAIT_V(n) asm volatile("s_waitcnt vmcnt(" #n ")" ::: "memory")
; #define PG8_WAIT_L(n) asm volatile("s_waitcnt lgkmcnt(" #n ")" ::: "memory")
; #define PG8_BAR __builtin_amdgcn_s_barrier()
; #define PG8_SCHED __builtin_amdgcn_sched_barrier(0)
; DI void gemm_phase(LAS unsigned char* lds, const Gemm g, const StaticOrder& S, const Epi& E) {
;     ...
;         for (int t = 0; t < nt; t += 2) {
;             const bool last = (t == nt - 2);
;             const char* a1 = cA + (size_t)(t + 1) * kstep;
;             const char* a2 = last ? nA : cA + (size_t)(t + 2) * kstep; const char* b2 = last ? nB : cB + (size_t)(t + 2) * kstep;
;             const char* a3 = a2 + kstep; const char* b3 = b2 + kstep;
;             PG8_LDB(B0, 0, 0); PG8_LDB(B1, 0, 1); PG8_SCHED; PG8_LDA(At, 0, 0); PG8_STAGE(PG8_SA(1, 1), a1 + hsA, voffA);
;             PG8_WAIT_V(8); PG8_WAIT_L(0); PG8_BAR; PG8_MMA(0, 0, At, B0); PG8_MMA(0, 1, At, B1); PG8_BAR; PG8_SCHED;
;             PG8_LDA(At, 0, 1); PG8_STAGE(PG8_SB(0, 0), b2, voffB); PG8_STAGE(PG8_SB(0, 1), b2 + hsB, voffB); PG8_STAGE(PG8_SA(0, 0), a2, voffA);
;             PG8_WAIT_V(8); PG8_WAIT_L(0); PG8_BAR; PG8_MMA(1, 0, At, B0); PG8_MMA(1, 1, At, B1); PG8_BAR; PG8_SCHED;
.LBB0_342:
	s_ashr_i32 s25, s24, 31
	s_lshl_b64 s[28:29], s[24:25], 18
	s_add_u32 s28, s0, s28
	s_addc_u32 s29, s1, s29
	s_and_b64 s[4:5], s[4:5], exec
	s_cselect_b32 s25, s29, s51
	s_cselect_b32 s31, s28, s50
	s_add_u32 s68, s50, 0x100
	v_mov_b32_e32 v0, 0
	s_addc_u32 s69, s51, 0
	s_mov_b32 s70, -2
	ds_read_b128 v[146:149], v159
	ds_read_b128 v[150:153], v159 offset:1024
	ds_read_b128 v[162:165], v159 offset:2048
	ds_read_b128 v[170:173], v159 offset:3072
	ds_read_b128 v[174:177], v160
	ds_read_b128 v[178:181], v160 offset:1024
	ds_read_b128 v[182:185], v160 offset:2048
	ds_read_b128 v[186:189], v160 offset:3072
	s_add_u32 s4, s34, 0x100
	s_addc_u32 s5, s35, 0
	s_cmp_eq_u32 s70, 4
	s_cselect_b32 s53, s27, s5
	s_cselect_b32 s52, s26, s4
	s_cselect_b32 s51, s25, s69
	s_cselect_b32 s50, s31, s68
	s_add_i32 m0, s13, 0xc000
	ds_read_b128 v[190:193], v161
	ds_read_b128 v[194:197], v161 offset:1024
	ds_read_b128 v[198:201], v161 offset:2048
	ds_read_b128 v[202:205], v161 offset:3072
	ds_read_b128 v[206:209], v161 offset:4096
	ds_read_b128 v[210:213], v161 offset:5120
	ds_read_b128 v[214:217], v161 offset:6144
	ds_read_b128 v[218:221], v161 offset:7168
	global_load_lds_dwordx4 v138, s[34:35]
	s_add_i32 m0, s13, 0xe000
	s_nop 0
	global_load_lds_dwordx4 v140, s[34:35]
	s_waitcnt vmcnt(8)
	s_waitcnt lgkmcnt(0)
	s_barrier
	s_setprio 1
	s_waitcnt lgkmcnt(0)
	v_mfma_f32_16x16x32_bf16 v[124:127], v[146:149], v[190:193], 0
	v_mfma_f32_16x16x32_bf16 v[124:127], v[150:153], v[194:197], v[124:127]
	v_mfma_f32_16x16x32_bf16 v[120:123], v[170:173], v[194:197], 0
	v_mfma_f32_16x16x32_bf16 v[120:123], v[162:165], v[190:193], v[120:123]
	v_mfma_f32_16x16x32_bf16 v[104:107], v[162:165], v[198:201], 0
	v_mfma_f32_16x16x32_bf16 v[104:107], v[170:173], v[202:205], v[104:107]
	v_mfma_f32_16x16x32_bf16 v[108:111], v[150:153], v[202:205], 0
	v_mfma_f32_16x16x32_bf16 v[108:111], v[146:149], v[198:201], v[108:111]
	v_mfma_f32_16x16x32_bf16 v[92:95], v[146:149], v[206:209], 0
	v_mfma_f32_16x16x32_bf16 v[92:95], v[150:153], v[210:213], v[92:95]
	v_mfma_f32_16x16x32_bf16 v[88:91], v[170:173], v[210:213], 0
	v_mfma_f32_16x16x32_bf16 v[88:91], v[162:165], v[206:209], v[88:91]
	v_mfma_f32_16x16x32_bf16 v[72:75], v[162:165], v[214:217], 0
	v_mfma_f32_16x16x32_bf16 v[72:75], v[170:173], v[218:221], v[72:75]
	v_mfma_f32_16x16x32_bf16 v[76:79], v[150:153], v[218:221], 0
	v_mfma_f32_16x16x32_bf16 v[76:79], v[146:149], v[214:217], v[76:79]
	s_setprio 0
	s_setprio 1
	v_mfma_f32_16x16x32_bf16 v[116:119], v[174:177], v[190:193], 0
	v_mfma_f32_16x16x32_bf16 v[116:119], v[178:181], v[194:197], v[116:119]
	v_mfma_f32_16x16x32_bf16 v[112:115], v[186:189], v[194:197], 0
	v_mfma_f32_16x16x32_bf16 v[112:115], v[182:185], v[190:193], v[112:115]
	v_mfma_f32_16x16x32_bf16 v[96:99], v[182:185], v[198:201], 0
	v_mfma_f32_16x16x32_bf16 v[96:99], v[186:189], v[202:205], v[96:99]
	v_mfma_f32_16x16x32_bf16 v[100:103], v[178:181], v[202:205], 0
	v_mfma_f32_16x16x32_bf16 v[100:103], v[174:177], v[198:201], v[100:103]
	v_mfma_f32_16x16x32_bf16 v[84:87], v[174:177], v[206:209], 0
	v_mfma_f32_16x16x32_bf16 v[84:87], v[178:181], v[210:213], v[84:87]
	v_mfma_f32_16x16x32_bf16 v[80:83], v[186:189], v[210:213], 0
	v_mfma_f32_16x16x32_bf16 v[80:83], v[182:185], v[206:209], v[80:83]
	v_mfma_f32_16x16x32_bf16 v[64:67], v[182:185], v[214:217], 0
	v_mfma_f32_16x16x32_bf16 v[64:67], v[186:189], v[218:221], v[64:67]
	v_mfma_f32_16x16x32_bf16 v[68:71], v[178:181], v[218:221], 0
	v_mfma_f32_16x16x32_bf16 v[68:71], v[174:177], v[214:217], v[68:71]
	s_setprio 0
	s_barrier
	s_add_i32 s34, s56, s12
	s_add_u32 s98, s50, 0x80
	s_addc_u32 s99, s51, 0
	s_mov_b32 m0, s34
	ds_read_b128 v[190:193], v161 offset:16384
	ds_read_b128 v[194:197], v161 offset:17408
	ds_read_b128 v[198:201], v161 offset:18432
	ds_read_b128 v[202:205], v161 offset:19456
	ds_read_b128 v[206:209], v161 offset:20480
	ds_read_b128 v[210:213], v161 offset:21504
	ds_read_b128 v[214:217], v161 offset:22528
	ds_read_b128 v[218:221], v161 offset:23552
	global_load_lds_dwordx4 v130, s[50:51]
	s_add_i32 m0, s34, 0x2000
	s_add_u32 s34, s50, 0x20000
	s_addc_u32 s35, s51, 0
	s_add_i32 s46, s57, s12
	global_load_lds_dwordx4 v134, s[50:51]
	s_mov_b32 m0, s46
	s_nop 0
	global_load_lds_dwordx4 v130, s[34:35]
	s_add_i32 m0, s46, 0x2000
	s_nop 0
	global_load_lds_dwordx4 v134, s[34:35]
	s_add_u32 s100, s52, 0x80
	s_addc_u32 s101, s53, 0
	s_mov_b32 m0, s13
	s_nop 0
	global_load_lds_dwordx4 v128, s[52:53]
	s_mov_b32 m0, s33
	s_nop 0
	global_load_lds_dwordx4 v132, s[52:53]
	s_waitcnt vmcnt(8)
	s_waitcnt lgkmcnt(0)
	s_barrier
; #define PG8_STAGE(bufoff, gbase, voff) do { _Pragma("unroll") for (int _i = 0; _i < 2; ++_i) \
;         __builtin_amdgcn_global_load_lds((const unsigned*)((const char*)(gbase) + (voff)[_i]), (LAS unsigned*)(lds + (bufoff) + ldsw + _i * 8192), 16, 0, 0); } while (0)
; #define PG8_LDA(dst, b, h) do { _Pragma("unroll") for (int m = 0; m < 4; ++m) _Pragma("unroll") for (int k = 0; k < 2; ++k) dst[m][k] = *(const LAS bf16x8*)(lds + PG8_SA(b, h) + aoff + m * 2048 + k * 1024); } while (0)
; #define PG8_LDB(dst, b, h) do { _Pragma("unroll") for (int n = 0; n < 2; ++n) _Pragma("unroll") for (int k = 0; k < 2; ++k) dst[n][k] = *(const LAS bf16x8*)(lds + PG8_SB(b, h) + boff + n * 2048 + k * 1024); } while (0)
; #define PG8_MMA(ai, bj, At, Bt) do { __builtin_amdgcn_s_setprio(1); _Pragma("unroll") for (int m = 0; m < 4; ++m) _Pragma("unroll") for (int n = 0; n < 2; ++n) _Pragma("unroll") for (int k = 0; k < 2; ++k) \
;         acc[ai][bj][m][n] = __builtin_amdgcn_mfma_f32_16x16x32_bf16(Bt[n][k], At[m][k], acc[ai][bj][m][n], 0, 0, 0); __builtin_amdgcn_s_setprio(0); } while (0)
; #define PG8_WAIT_V(n) asm volatile("s_waitcnt vmcnt(" #n ")" ::: "memory")
; #define PG8_WAIT_L(n) asm volatile("s_waitcnt lgkmcnt(" #n ")" ::: "memory")
; #define PG8_BAR __builtin_amdgcn_s_barrier()
; #define PG8_SCHED __builtin_amdgcn_sched_barrier(0)
; DI void gemm_phase(LAS unsigned char* lds, const Gemm g, const StaticOrder& S, const Epi& E) {
;     ...
;             PG8_WAIT_V(8); PG8_WAIT_L(0); PG8_BAR; PG8_MMA(1, 0, At, B0); PG8_MMA(1, 1, At, B1); PG8_BAR; PG8_SCHED;
;             PG8_LDB(B0, 1, 0); PG8_LDB(B1, 1, 1); PG8_SCHED; PG8_LDA(At, 1, 0); PG8_STAGE(PG8_SA(0, 1), a2 + hsA, voffA);
;             PG8_WAIT_V(8); PG8_WAIT_L(0); PG8_BAR; PG8_MMA(0, 0, At, B0); PG8_MMA(0, 1, At, B1); PG8_BAR; PG8_SCHED;
	s_setprio 1
	s_waitcnt lgkmcnt(0)
	v_mfma_f32_16x16x32_bf16 v[60:63], v[146:149], v[190:193], 0
	v_mfma_f32_16x16x32_bf16 v[60:63], v[150:153], v[194:197], v[60:63]
	v_mfma_f32_16x16x32_bf16 v[56:59], v[170:173], v[194:197], 0
	v_mfma_f32_16x16x32_bf16 v[56:59], v[162:165], v[190:193], v[56:59]
	v_mfma_f32_16x16x32_bf16 v[40:43], v[162:165], v[198:201], 0
	v_mfma_f32_16x16x32_bf16 v[40:43], v[170:173], v[202:205], v[40:43]
	v_mfma_f32_16x16x32_bf16 v[44:47], v[150:153], v[202:205], 0
	v_mfma_f32_16x16x32_bf16 v[44:47], v[146:149], v[198:201], v[44:47]
	v_mfma_f32_16x16x32_bf16 v[28:31], v[146:149], v[206:209], 0
	v_mfma_f32_16x16x32_bf16 v[28:31], v[150:153], v[210:213], v[28:31]
	v_mfma_f32_16x16x32_bf16 v[24:27], v[170:173], v[210:213], 0
	v_mfma_f32_16x16x32_bf16 v[24:27], v[162:165], v[206:209], v[24:27]
	v_mfma_f32_16x16x32_bf16 v[8:11], v[162:165], v[214:217], 0
	v_mfma_f32_16x16x32_bf16 v[8:11], v[170:173], v[218:221], v[8:11]
	v_mfma_f32_16x16x32_bf16 v[12:15], v[150:153], v[218:221], 0
	v_mfma_f32_16x16x32_bf16 v[12:15], v[146:149], v[214:217], v[12:15]
	s_setprio 0
	s_setprio 1
	v_mfma_f32_16x16x32_bf16 v[52:55], v[174:177], v[190:193], 0
	v_mfma_f32_16x16x32_bf16 v[52:55], v[178:181], v[194:197], v[52:55]
	v_mfma_f32_16x16x32_bf16 v[48:51], v[186:189], v[194:197], 0
	v_mfma_f32_16x16x32_bf16 v[48:51], v[182:185], v[190:193], v[48:51]
	v_mfma_f32_16x16x32_bf16 v[32:35], v[182:185], v[198:201], 0
	v_mfma_f32_16x16x32_bf16 v[32:35], v[186:189], v[202:205], v[32:35]
	v_mfma_f32_16x16x32_bf16 v[36:39], v[178:181], v[202:205], 0
	v_mfma_f32_16x16x32_bf16 v[36:39], v[174:177], v[198:201], v[36:39]
	v_mfma_f32_16x16x32_bf16 v[20:23], v[174:177], v[206:209], 0
	v_mfma_f32_16x16x32_bf16 v[20:23], v[178:181], v[210:213], v[20:23]
	v_mfma_f32_16x16x32_bf16 v[16:19], v[186:189], v[210:213], 0
	v_mfma_f32_16x16x32_bf16 v[16:19], v[182:185], v[206:209], v[16:19]
	v_mfma_f32_16x16x32_bf16 v[0:3], v[182:185], v[214:217], 0
	v_mfma_f32_16x16x32_bf16 v[0:3], v[186:189], v[218:221], v[0:3]
	v_mfma_f32_16x16x32_bf16 v[4:7], v[178:181], v[218:221], 0
	v_mfma_f32_16x16x32_bf16 v[4:7], v[174:177], v[214:217], v[4:7]
	s_setprio 0
	s_barrier
	s_add_i32 s46, 0, 0x18000
	v_add_u32_e32 v136, s46, v157
	s_add_i32 s47, 0, 0x1c000
	ds_read_b128 v[146:149], v136
	ds_read_b128 v[150:153], v136 offset:1024
	ds_read_b128 v[162:165], v136 offset:2048
	ds_read_b128 v[170:173], v136 offset:3072
	v_add_u32_e32 v136, s47, v157
	ds_read_b128 v[174:177], v136
	ds_read_b128 v[178:181], v136 offset:1024
	ds_read_b128 v[182:185], v136 offset:2048
	ds_read_b128 v[186:189], v136 offset:3072
	s_add_u32 s34, s52, 0xb0000
	s_addc_u32 s35, s53, 0
	s_mov_b32 m0, s40
	ds_read_b128 v[190:193], v161 offset:32768
	ds_read_b128 v[194:197], v161 offset:33792
	ds_read_b128 v[198:201], v161 offset:34816
	ds_read_b128 v[202:205], v161 offset:35840
	ds_read_b128 v[206:209], v161 offset:36864
	ds_read_b128 v[210:213], v161 offset:37888
	ds_read_b128 v[214:217], v161 offset:38912
	ds_read_b128 v[218:221], v161 offset:39936
	global_load_lds_dwordx4 v128, s[34:35]
	s_mov_b32 m0, s41
	s_nop 0
	global_load_lds_dwordx4 v132, s[34:35]
	s_waitcnt vmcnt(8)
	s_waitcnt lgkmcnt(0)
	s_barrier
	s_setprio 1
	s_waitcnt lgkmcnt(0)
	v_mfma_f32_16x16x32_bf16 v[124:127], v[146:149], v[190:193], v[124:127]
	v_mfma_f32_16x16x32_bf16 v[124:127], v[150:153], v[194:197], v[124:127]
	v_mfma_f32_16x16x32_bf16 v[120:123], v[170:173], v[194:197], v[120:123]
	v_mfma_f32_16x16x32_bf16 v[120:123], v[162:165], v[190:193], v[120:123]
	v_mfma_f32_16x16x32_bf16 v[104:107], v[162:165], v[198:201], v[104:107]
	v_mfma_f32_16x16x32_bf16 v[104:107], v[170:173], v[202:205], v[104:107]
	v_mfma_f32_16x16x32_bf16 v[108:111], v[150:153], v[202:205], v[108:111]
	v_mfma_f32_16x16x32_bf16 v[108:111], v[146:149], v[198:201], v[108:111]
	v_mfma_f32_16x16x32_bf16 v[92:95], v[146:149], v[206:209], v[92:95]
	v_mfma_f32_16x16x32_bf16 v[92:95], v[150:153], v[210:213], v[92:95]
	v_mfma_f32_16x16x32_bf16 v[88:91], v[170:173], v[210:213], v[88:91]
	v_mfma_f32_16x16x32_bf16 v[88:91], v[162:165], v[206:209], v[88:91]
	v_mfma_f32_16x16x32_bf16 v[72:75], v[162:165], v[214:217], v[72:75]
	v_mfma_f32_16x16x32_bf16 v[72:75], v[170:173], v[218:221], v[72:75]
	v_mfma_f32_16x16x32_bf16 v[76:79], v[150:153], v[218:221], v[76:79]
	v_mfma_f32_16x16x32_bf16 v[76:79], v[146:149], v[214:217], v[76:79]
	s_setprio 0
	s_setprio 1
	v_mfma_f32_16x16x32_bf16 v[116:119], v[174:177], v[190:193], v[116:119]
	v_mfma_f32_16x16x32_bf16 v[116:119], v[178:181], v[194:197], v[116:119]
	v_mfma_f32_16x16x32_bf16 v[112:115], v[186:189], v[194:197], v[112:115]
	v_mfma_f32_16x16x32_bf16 v[112:115], v[182:185], v[190:193], v[112:115]
	v_mfma_f32_16x16x32_bf16 v[96:99], v[182:185], v[198:201], v[96:99]
	v_mfma_f32_16x16x32_bf16 v[96:99], v[186:189], v[202:205], v[96:99]
	v_mfma_f32_16x16x32_bf16 v[100:103], v[178:181], v[202:205], v[100:103]
	v_mfma_f32_16x16x32_bf16 v[100:103], v[174:177], v[198:201], v[100:103]
	v_mfma_f32_16x16x32_bf16 v[84:87], v[174:177], v[206:209], v[84:87]
	v_mfma_f32_16x16x32_bf16 v[84:87], v[178:181], v[210:213], v[84:87]
	v_mfma_f32_16x16x32_bf16 v[80:83], v[186:189], v[210:213], v[80:83]
	v_mfma_f32_16x16x32_bf16 v[80:83], v[182:185], v[206:209], v[80:83]
	v_mfma_f32_16x16x32_bf16 v[64:67], v[182:185], v[214:217], v[64:67]
	v_mfma_f32_16x16x32_bf16 v[64:67], v[186:189], v[218:221], v[64:67]
	v_mfma_f32_16x16x32_bf16 v[68:71], v[178:181], v[218:221], v[68:71]
	v_mfma_f32_16x16x32_bf16 v[68:71], v[174:177], v[214:217], v[68:71]
	s_setprio 0
	s_barrier
; #define PG8_STAGE(bufoff, gbase, voff) do { _Pragma("unroll") for (int _i = 0; _i < 2; ++_i) \
;         __builtin_amdgcn_global_load_lds((const unsigned*)((const char*)(gbase) + (voff)[_i]), (LAS unsigned*)(lds + (bufoff) + ldsw + _i * 8192), 16, 0, 0); } while (0)
; #define PG8_LDA(dst, b, h) do { _Pragma("unroll") for (int m = 0; m < 4; ++m) _Pragma("unroll") for (int k = 0; k < 2; ++k) dst[m][k] = *(const LAS bf16x8*)(lds + PG8_SA(b, h) + aoff + m * 2048 + k * 1024); } while (0)
; #define PG8_MMA(ai, bj, At, Bt) do { __builtin_amdgcn_s_setprio(1); _Pragma("unroll") for (int m = 0; m < 4; ++m) _Pragma("unroll") for (int n = 0; n < 2; ++n) _Pragma("unroll") for (int k = 0; k < 2; ++k) \
;         acc[ai][bj][m][n] = __builtin_amdgcn_mfma_f32_16x16x32_bf16(Bt[n][k], At[m][k], acc[ai][bj][m][n], 0, 0, 0); __builtin_amdgcn_s_setprio(0); } while (0)
; #define PG8_WAIT_V(n) asm volatile("s_waitcnt vmcnt(" #n ")" ::: "memory")
; #define PG8_WAIT_L(n) asm volatile("s_waitcnt lgkmcnt(" #n ")" ::: "memory")
; #define PG8_BAR __builtin_amdgcn_s_barrier()
; #define PG8_SCHED __builtin_amdgcn_sched_barrier(0)
; DI void gemm_phase(LAS unsigned char* lds, const Gemm g, const StaticOrder& S, const Epi& E) {
;     ...
;             PG8_LDA(At, 1, 1); PG8_STAGE(PG8_SB(1, 0), b3, voffB); PG8_STAGE(PG8_SB(1, 1), b3 + hsB, voffB); PG8_STAGE(PG8_SA(1, 0), a3, voffA);
;             PG8_WAIT_V(8); PG8_WAIT_L(0); PG8_BAR; PG8_MMA(1, 0, At, B0); PG8_MMA(1, 1, At, B1); PG8_BAR; PG8_SCHED;
;         }
	s_add_i32 s34, s46, s12
	s_mov_b32 m0, s34
	ds_read_b128 v[190:193], v161 offset:49152
	ds_read_b128 v[194:197], v161 offset:50176
	ds_read_b128 v[198:201], v161 offset:51200
	ds_read_b128 v[202:205], v161 offset:52224
	ds_read_b128 v[206:209], v161 offset:53248
	ds_read_b128 v[210:213], v161 offset:54272
	ds_read_b128 v[214:217], v161 offset:55296
	ds_read_b128 v[218:221], v161 offset:56320
	global_load_lds_dwordx4 v130, s[98:99]
	s_add_i32 m0, s34, 0x2000
	s_add_u32 s34, s50, 0x20080
	s_addc_u32 s35, s51, 0
	s_add_i32 s46, s47, s12
	global_load_lds_dwordx4 v134, s[98:99]
	s_mov_b32 m0, s46
	s_nop 0
	global_load_lds_dwordx4 v130, s[34:35]
	s_add_i32 m0, s46, 0x2000
	s_nop 0
	global_load_lds_dwordx4 v134, s[34:35]
	s_mov_b32 m0, s48
	s_nop 0
	global_load_lds_dwordx4 v128, s[100:101]
	s_mov_b32 m0, s49
	s_nop 0
	global_load_lds_dwordx4 v132, s[100:101]
	s_waitcnt vmcnt(8)
	s_waitcnt lgkmcnt(0)
	s_barrier
	s_setprio 1
	s_waitcnt lgkmcnt(0)
	v_mfma_f32_16x16x32_bf16 v[60:63], v[146:149], v[190:193], v[60:63]
	v_mfma_f32_16x16x32_bf16 v[60:63], v[150:153], v[194:197], v[60:63]
	v_mfma_f32_16x16x32_bf16 v[56:59], v[170:173], v[194:197], v[56:59]
	v_mfma_f32_16x16x32_bf16 v[56:59], v[162:165], v[190:193], v[56:59]
	v_mfma_f32_16x16x32_bf16 v[40:43], v[162:165], v[198:201], v[40:43]
	v_mfma_f32_16x16x32_bf16 v[40:43], v[170:173], v[202:205], v[40:43]
	v_mfma_f32_16x16x32_bf16 v[44:47], v[150:153], v[202:205], v[44:47]
	v_mfma_f32_16x16x32_bf16 v[44:47], v[146:149], v[198:201], v[44:47]
	v_mfma_f32_16x16x32_bf16 v[28:31], v[146:149], v[206:209], v[28:31]
	v_mfma_f32_16x16x32_bf16 v[28:31], v[150:153], v[210:213], v[28:31]
	v_mfma_f32_16x16x32_bf16 v[24:27], v[170:173], v[210:213], v[24:27]
	v_mfma_f32_16x16x32_bf16 v[24:27], v[162:165], v[206:209], v[24:27]
	v_mfma_f32_16x16x32_bf16 v[8:11], v[162:165], v[214:217], v[8:11]
	v_mfma_f32_16x16x32_bf16 v[8:11], v[170:173], v[218:221], v[8:11]
	v_mfma_f32_16x16x32_bf16 v[12:15], v[150:153], v[218:221], v[12:15]
	v_mfma_f32_16x16x32_bf16 v[12:15], v[146:149], v[214:217], v[12:15]
	s_setprio 0
	s_setprio 1
	v_mfma_f32_16x16x32_bf16 v[52:55], v[174:177], v[190:193], v[52:55]
	v_mfma_f32_16x16x32_bf16 v[52:55], v[178:181], v[194:197], v[52:55]
	v_mfma_f32_16x16x32_bf16 v[48:51], v[186:189], v[194:197], v[48:51]
	v_mfma_f32_16x16x32_bf16 v[48:51], v[182:185], v[190:193], v[48:51]
	v_mfma_f32_16x16x32_bf16 v[32:35], v[182:185], v[198:201], v[32:35]
	v_mfma_f32_16x16x32_bf16 v[32:35], v[186:189], v[202:205], v[32:35]
	v_mfma_f32_16x16x32_bf16 v[36:39], v[178:181], v[202:205], v[36:39]
	v_mfma_f32_16x16x32_bf16 v[36:39], v[174:177], v[198:201], v[36:39]
	v_mfma_f32_16x16x32_bf16 v[20:23], v[174:177], v[206:209], v[20:23]
	v_mfma_f32_16x16x32_bf16 v[20:23], v[178:181], v[210:213], v[20:23]
	v_mfma_f32_16x16x32_bf16 v[16:19], v[186:189], v[210:213], v[16:19]
	v_mfma_f32_16x16x32_bf16 v[16:19], v[182:185], v[206:209], v[16:19]
	v_mfma_f32_16x16x32_bf16 v[0:3], v[182:185], v[214:217], v[0:3]
	v_mfma_f32_16x16x32_bf16 v[0:3], v[186:189], v[218:221], v[0:3]
	v_mfma_f32_16x16x32_bf16 v[4:7], v[178:181], v[218:221], v[4:7]
	v_mfma_f32_16x16x32_bf16 v[4:7], v[174:177], v[214:217], v[4:7]
	s_setprio 0
	s_barrier
	s_add_i32 s70, s70, 2
	s_add_u32 s68, s68, 0x100
	s_addc_u32 s69, s69, 0
	s_cmp_gt_u32 s70, 5
	s_mov_b64 s[34:35], s[4:5]

; #define PG8_STAGE(bufoff, gbase, voff) do { _Pragma("unroll") for (int _i = 0; _i < 2; ++_i) \
;         __builtin_amdgcn_global_load_lds((const unsigned*)((const char*)(gbase) + (voff)[_i]), (LAS unsigned*)(lds + (bufoff) + ldsw + _i * 8192), 16, 0, 0); } while (0)
; #define PG8_LDA(dst, b, h) do { _Pragma("unroll") for (int m = 0; m < 4; ++m) _Pragma("unroll") for (int k = 0; k < 2; ++k) dst[m][k] = *(const LAS bf16x8*)(lds + PG8_SA(b, h) + aoff + m * 2048 + k * 1024); } while (0)
; #define PG8_LDB(dst, b, h) do { _Pragma("unroll") for (int n = 0; n < 2; ++n) _Pragma("unroll") for (int k = 0; k < 2; ++k) dst[n][k] = *(const LAS bf16x8*)(lds + PG8_SB(b, h) + boff + n * 2048 + k * 1024); } while (0)
; #define PG8_MMA(ai, bj, At, Bt) do { __builtin_amdgcn_s_setprio(1); _Pragma("unroll") for (int m = 0; m < 4; ++m) _Pragma("unroll") for (int n = 0; n < 2; ++n) _Pragma("unroll") for (int k = 0; k < 2; ++k) \
;         acc[ai][bj][m][n] = __builtin_amdgcn_mfma_f32_16x16x32_bf16(Bt[n][k], At[m][k], acc[ai][bj][m][n], 0, 0, 0); __builtin_amdgcn_s_setprio(0); } while (0)
; #define PG8_WAIT_V(n) asm volatile("s_waitcnt vmcnt(" #n ")" ::: "memory")
; #define PG8_BAR __builtin_amdgcn_s_barrier()
; DI void gemm_phase(LAS unsigned char* lds, const Gemm g, const StaticOrder& S, const Epi& E) {
;     ...
;         const bool has_next = S.next(ui + 1, nxt);
;         const char* nA = has_next ? (const char*)g.A + (size_t)nxt.pm * tsA : cA; const char* nB = has_next ? (const char*)g.Bt + (size_t)nxt.pn * tsB : cB;
;         for (int t = 0; t < nt; t += 2) {
;             const bool last = (t == nt - 2);
;             const char* a1 = cA + (size_t)(t + 1) * kstep;
;             const char* a2 = last ? nA : cA + (size_t)(t + 2) * kstep; const char* b2 = last ? nB : cB + (size_t)(t + 2) * kstep;
;             const char* a3 = a2 + kstep; const char* b3 = b2 + kstep;
;             PG8_LDB(B0, 0, 0); PG8_LDB(B1, 0, 1); PG8_SCHED; PG8_LDA(At, 0, 0); PG8_STAGE(PG8_SA(1, 1), a1 + hsA, voffA);
;             PG8_WAIT_V(8); PG8_WAIT_L(0); PG8_BAR; PG8_MMA(0, 0, At, B0); PG8_MMA(0, 1, At, B1); PG8_BAR; PG8_SCHED;
;             PG8_LDA(At, 0, 1); PG8_STAGE(PG8_SB(0, 0), b2, voffB); PG8_STAGE(PG8_SB(0, 1), b2 + hsB, voffB); PG8_STAGE(PG8_SA(0, 0), a2, voffA);
;             PG8_WAIT_V(8); PG8_WAIT_L(0); PG8_BAR; PG8_MMA(1, 0, At, B0); PG8_MMA(1, 1, At, B1); PG8_BAR; PG8_SCHED;
.LBB0_402:
	s_ashr_i32 s21, s20, 31
	s_lshl_b64 s[24:25], s[20:21], 17
	s_add_u32 s24, s12, s24
	s_addc_u32 s25, s13, s25
	s_and_b64 s[6:7], s[6:7], exec
	v_mov_b32_e32 v0, 0
	s_cselect_b32 s21, s25, s29
	s_cselect_b32 s27, s24, s28
	s_mov_b32 s46, 0
	s_mov_b64 s[6:7], -1
	s_mov_b64 s[34:35], 0
	s_add_u32 s47, s30, s46
	s_addc_u32 s66, s31, 0
	s_add_u32 s54, s47, 0x100
	s_addc_u32 s55, s66, 0
	s_and_b64 s[52:53], s[34:35], exec
	s_cselect_b32 s55, s23, s55
	s_cselect_b32 s54, s22, s54
	s_add_u32 s46, s28, s46
	s_addc_u32 s52, s29, 0
	s_add_u32 s46, s46, 0x100
	s_addc_u32 s52, s52, 0
	s_and_b64 s[34:35], s[34:35], exec
	s_cselect_b32 s57, s21, s52
	s_cselect_b32 s56, s27, s46
	s_add_u32 s68, s47, 0xb0080
	ds_read_b128 v[140:143], v153
	ds_read_b128 v[144:147], v153 offset:1024
	ds_read_b128 v[156:159], v153 offset:2048
	ds_read_b128 v[160:163], v153 offset:3072
	ds_read_b128 v[170:173], v154
	ds_read_b128 v[174:177], v154 offset:1024
	ds_read_b128 v[178:181], v154 offset:2048
	ds_read_b128 v[182:185], v154 offset:3072
	s_addc_u32 s69, s66, 0
	s_add_i32 s79, s70, s33
	s_add_i32 m0, s40, 0xc000
	s_add_i32 s82, s40, 0xe000
	s_add_i32 s76, s79, 0x2000
	s_add_u32 s66, s56, 0x10000
	s_addc_u32 s67, s57, 0
	s_add_i32 s78, s71, s33
	s_add_i32 s77, s78, 0x2000
	s_add_i32 s75, 0, 0x18000
	s_add_i32 s74, 0, 0x1c000
	s_add_u32 s52, s54, 0xb0000
	s_addc_u32 s53, s55, 0
	s_add_i32 s47, s75, s33
	s_add_i32 s46, s47, 0x2000
	s_add_u32 s34, s56, 0x10080
	s_addc_u32 s35, s57, 0
	s_add_i32 s81, s74, s33
	s_add_i32 s80, s81, 0x2000
	ds_read_b128 v[186:189], v155
	ds_read_b128 v[190:193], v155 offset:1024
	ds_read_b128 v[194:197], v155 offset:2048
	ds_read_b128 v[198:201], v155 offset:3072
	ds_read_b128 v[202:205], v155 offset:4096
	ds_read_b128 v[206:209], v155 offset:5120
	ds_read_b128 v[210:213], v155 offset:6144
	ds_read_b128 v[214:217], v155 offset:7168
	global_load_lds_dwordx4 v128, s[68:69]
	s_mov_b32 m0, s82
	s_nop 0
	global_load_lds_dwordx4 v132, s[68:69]
	s_waitcnt vmcnt(8)
	s_waitcnt lgkmcnt(0)
	s_barrier
	s_setprio 1
	s_waitcnt lgkmcnt(0)
	v_mfma_f32_16x16x32_bf16 v[124:127], v[140:143], v[186:189], 0
	v_mfma_f32_16x16x32_bf16 v[124:127], v[144:147], v[190:193], v[124:127]
	v_mfma_f32_16x16x32_bf16 v[120:123], v[160:163], v[190:193], 0
	v_mfma_f32_16x16x32_bf16 v[120:123], v[156:159], v[186:189], v[120:123]
	v_mfma_f32_16x16x32_bf16 v[104:107], v[156:159], v[194:197], 0
	v_mfma_f32_16x16x32_bf16 v[104:107], v[160:163], v[198:201], v[104:107]
	v_mfma_f32_16x16x32_bf16 v[108:111], v[144:147], v[198:201], 0
	v_mfma_f32_16x16x32_bf16 v[108:111], v[140:143], v[194:197], v[108:111]
	v_mfma_f32_16x16x32_bf16 v[92:95], v[140:143], v[202:205], 0
	v_mfma_f32_16x16x32_bf16 v[92:95], v[144:147], v[206:209], v[92:95]
	v_mfma_f32_16x16x32_bf16 v[88:91], v[160:163], v[206:209], 0
	v_mfma_f32_16x16x32_bf16 v[88:91], v[156:159], v[202:205], v[88:91]
	v_mfma_f32_16x16x32_bf16 v[72:75], v[156:159], v[210:213], 0
	v_mfma_f32_16x16x32_bf16 v[72:75], v[160:163], v[214:217], v[72:75]
	v_mfma_f32_16x16x32_bf16 v[76:79], v[144:147], v[214:217], 0
	v_mfma_f32_16x16x32_bf16 v[76:79], v[140:143], v[210:213], v[76:79]
	s_setprio 0
	s_setprio 1
	v_mfma_f32_16x16x32_bf16 v[116:119], v[170:173], v[186:189], 0
	v_mfma_f32_16x16x32_bf16 v[116:119], v[174:177], v[190:193], v[116:119]
	v_mfma_f32_16x16x32_bf16 v[112:115], v[182:185], v[190:193], 0
	v_mfma_f32_16x16x32_bf16 v[112:115], v[178:181], v[186:189], v[112:115]
	v_mfma_f32_16x16x32_bf16 v[96:99], v[178:181], v[194:197], 0
	v_mfma_f32_16x16x32_bf16 v[96:99], v[182:185], v[198:201], v[96:99]
	v_mfma_f32_16x16x32_bf16 v[100:103], v[174:177], v[198:201], 0
	v_mfma_f32_16x16x32_bf16 v[100:103], v[170:173], v[194:197], v[100:103]
	v_mfma_f32_16x16x32_bf16 v[84:87], v[170:173], v[202:205], 0
	v_mfma_f32_16x16x32_bf16 v[84:87], v[174:177], v[206:209], v[84:87]
	v_mfma_f32_16x16x32_bf16 v[80:83], v[182:185], v[206:209], 0
	v_mfma_f32_16x16x32_bf16 v[80:83], v[178:181], v[202:205], v[80:83]
	v_mfma_f32_16x16x32_bf16 v[64:67], v[178:181], v[210:213], 0
	v_mfma_f32_16x16x32_bf16 v[64:67], v[182:185], v[214:217], v[64:67]
	v_mfma_f32_16x16x32_bf16 v[68:71], v[174:177], v[214:217], 0
	v_mfma_f32_16x16x32_bf16 v[68:71], v[170:173], v[210:213], v[68:71]
	s_setprio 0
	s_barrier
	s_mov_b32 m0, s79
	s_add_u32 s98, s56, 0x80
	s_addc_u32 s99, s57, 0
	ds_read_b128 v[186:189], v155 offset:16384
	ds_read_b128 v[190:193], v155 offset:17408
	ds_read_b128 v[194:197], v155 offset:18432
	ds_read_b128 v[198:201], v155 offset:19456
	ds_read_b128 v[202:205], v155 offset:20480
	ds_read_b128 v[206:209], v155 offset:21504
	ds_read_b128 v[210:213], v155 offset:22528
	ds_read_b128 v[214:217], v155 offset:23552
	global_load_lds_dwordx4 v130, s[56:57]
	s_mov_b32 m0, s76
	s_nop 0
	global_load_lds_dwordx4 v134, s[56:57]
	s_mov_b32 m0, s78
	s_nop 0
	global_load_lds_dwordx4 v130, s[66:67]
	s_mov_b32 m0, s77
	s_nop 0
	global_load_lds_dwordx4 v134, s[66:67]
	s_add_u32 s100, s54, 0x80
	s_addc_u32 s101, s55, 0
	s_mov_b32 m0, s40
	s_nop 0
	global_load_lds_dwordx4 v128, s[54:55]
	s_mov_b32 m0, s41
	s_nop 0
	global_load_lds_dwordx4 v132, s[54:55]
	s_waitcnt vmcnt(8)
	s_waitcnt lgkmcnt(0)
	s_barrier
; #define PG8_STAGE(bufoff, gbase, voff) do { _Pragma("unroll") for (int _i = 0; _i < 2; ++_i) \
;         __builtin_amdgcn_global_load_lds((const unsigned*)((const char*)(gbase) + (voff)[_i]), (LAS unsigned*)(lds + (bufoff) + ldsw + _i * 8192), 16, 0, 0); } while (0)
; #define PG8_LDA(dst, b, h) do { _Pragma("unroll") for (int m = 0; m < 4; ++m) _Pragma("unroll") for (int k = 0; k < 2; ++k) dst[m][k] = *(const LAS bf16x8*)(lds + PG8_SA(b, h) + aoff + m * 2048 + k * 1024); } while (0)
; #define PG8_LDB(dst, b, h) do { _Pragma("unroll") for (int n = 0; n < 2; ++n) _Pragma("unroll") for (int k = 0; k < 2; ++k) dst[n][k] = *(const LAS bf16x8*)(lds + PG8_SB(b, h) + boff + n * 2048 + k * 1024); } while (0)
; #define PG8_MMA(ai, bj, At, Bt) do { __builtin_amdgcn_s_setprio(1); _Pragma("unroll") for (int m = 0; m < 4; ++m) _Pragma("unroll") for (int n = 0; n < 2; ++n) _Pragma("unroll") for (int k = 0; k < 2; ++k) \
;         acc[ai][bj][m][n] = __builtin_amdgcn_mfma_f32_16x16x32_bf16(Bt[n][k], At[m][k], acc[ai][bj][m][n], 0, 0, 0); __builtin_amdgcn_s_setprio(0); } while (0)
; #define PG8_WAIT_V(n) asm volatile("s_waitcnt vmcnt(" #n ")" ::: "memory")
; #define PG8_WAIT_L(n) asm volatile("s_waitcnt lgkmcnt(" #n ")" ::: "memory")
; #define PG8_BAR __builtin_amdgcn_s_barrier()
; #define PG8_SCHED __builtin_amdgcn_sched_barrier(0)
; DI void gemm_phase(LAS unsigned char* lds, const Gemm g, const StaticOrder& S, const Epi& E) {
;     ...
;             PG8_WAIT_V(8); PG8_WAIT_L(0); PG8_BAR; PG8_MMA(1, 0, At, B0); PG8_MMA(1, 1, At, B1); PG8_BAR; PG8_SCHED;
;             PG8_LDB(B0, 1, 0); PG8_LDB(B1, 1, 1); PG8_SCHED; PG8_LDA(At, 1, 0); PG8_STAGE(PG8_SA(0, 1), a2 + hsA, voffA);
;             PG8_WAIT_V(8); PG8_WAIT_L(0); PG8_BAR; PG8_MMA(0, 0, At, B0); PG8_MMA(0, 1, At, B1); PG8_BAR; PG8_SCHED;
	s_setprio 1
	s_waitcnt lgkmcnt(0)
	v_mfma_f32_16x16x32_bf16 v[60:63], v[140:143], v[186:189], 0
	v_mfma_f32_16x16x32_bf16 v[60:63], v[144:147], v[190:193], v[60:63]
	v_mfma_f32_16x16x32_bf16 v[56:59], v[160:163], v[190:193], 0
	v_mfma_f32_16x16x32_bf16 v[56:59], v[156:159], v[186:189], v[56:59]
	v_mfma_f32_16x16x32_bf16 v[40:43], v[156:159], v[194:197], 0
	v_mfma_f32_16x16x32_bf16 v[40:43], v[160:163], v[198:201], v[40:43]
	v_mfma_f32_16x16x32_bf16 v[44:47], v[144:147], v[198:201], 0
	v_mfma_f32_16x16x32_bf16 v[44:47], v[140:143], v[194:197], v[44:47]
	v_mfma_f32_16x16x32_bf16 v[28:31], v[140:143], v[202:205], 0
	v_mfma_f32_16x16x32_bf16 v[28:31], v[144:147], v[206:209], v[28:31]
	v_mfma_f32_16x16x32_bf16 v[24:27], v[160:163], v[206:209], 0
	v_mfma_f32_16x16x32_bf16 v[24:27], v[156:159], v[202:205], v[24:27]
	v_mfma_f32_16x16x32_bf16 v[8:11], v[156:159], v[210:213], 0
	v_mfma_f32_16x16x32_bf16 v[8:11], v[160:163], v[214:217], v[8:11]
	v_mfma_f32_16x16x32_bf16 v[12:15], v[144:147], v[214:217], 0
	v_mfma_f32_16x16x32_bf16 v[12:15], v[140:143], v[210:213], v[12:15]
	s_setprio 0
	s_setprio 1
	v_mfma_f32_16x16x32_bf16 v[52:55], v[170:173], v[186:189], 0
	v_mfma_f32_16x16x32_bf16 v[52:55], v[174:177], v[190:193], v[52:55]
	v_mfma_f32_16x16x32_bf16 v[48:51], v[182:185], v[190:193], 0
	v_mfma_f32_16x16x32_bf16 v[48:51], v[178:181], v[186:189], v[48:51]
	v_mfma_f32_16x16x32_bf16 v[32:35], v[178:181], v[194:197], 0
	v_mfma_f32_16x16x32_bf16 v[32:35], v[182:185], v[198:201], v[32:35]
	v_mfma_f32_16x16x32_bf16 v[36:39], v[174:177], v[198:201], 0
	v_mfma_f32_16x16x32_bf16 v[36:39], v[170:173], v[194:197], v[36:39]
	v_mfma_f32_16x16x32_bf16 v[20:23], v[170:173], v[202:205], 0
	v_mfma_f32_16x16x32_bf16 v[20:23], v[174:177], v[206:209], v[20:23]
	v_mfma_f32_16x16x32_bf16 v[16:19], v[182:185], v[206:209], 0
	v_mfma_f32_16x16x32_bf16 v[16:19], v[178:181], v[202:205], v[16:19]
	v_mfma_f32_16x16x32_bf16 v[0:3], v[178:181], v[210:213], 0
	v_mfma_f32_16x16x32_bf16 v[0:3], v[182:185], v[214:217], v[0:3]
	v_mfma_f32_16x16x32_bf16 v[4:7], v[174:177], v[214:217], 0
	v_mfma_f32_16x16x32_bf16 v[4:7], v[170:173], v[210:213], v[4:7]
	s_setprio 0
	s_barrier
	v_add_u32_e32 v160, s75, v151
	v_add_u32_e32 v166, s74, v151
	ds_read_b128 v[140:143], v160
	ds_read_b128 v[144:147], v160 offset:1024
	ds_read_b128 v[156:159], v160 offset:2048
	ds_read_b128 v[160:163], v160 offset:3072
	ds_read_b128 v[170:173], v166
	ds_read_b128 v[174:177], v166 offset:1024
	ds_read_b128 v[178:181], v166 offset:2048
	ds_read_b128 v[182:185], v166 offset:3072
	s_mov_b32 m0, s42
	ds_read_b128 v[186:189], v155 offset:32768
	ds_read_b128 v[190:193], v155 offset:33792
	ds_read_b128 v[194:197], v155 offset:34816
	ds_read_b128 v[198:201], v155 offset:35840
	ds_read_b128 v[202:205], v155 offset:36864
	ds_read_b128 v[206:209], v155 offset:37888
	ds_read_b128 v[210:213], v155 offset:38912
	ds_read_b128 v[214:217], v155 offset:39936
	global_load_lds_dwordx4 v128, s[52:53]
	s_mov_b32 m0, s43
	s_nop 0
	global_load_lds_dwordx4 v132, s[52:53]
	s_waitcnt vmcnt(8)
	s_waitcnt lgkmcnt(0)
	s_barrier
	s_setprio 1
	s_waitcnt lgkmcnt(0)
	v_mfma_f32_16x16x32_bf16 v[124:127], v[140:143], v[186:189], v[124:127]
	v_mfma_f32_16x16x32_bf16 v[124:127], v[144:147], v[190:193], v[124:127]
	v_mfma_f32_16x16x32_bf16 v[120:123], v[160:163], v[190:193], v[120:123]
	v_mfma_f32_16x16x32_bf16 v[120:123], v[156:159], v[186:189], v[120:123]
	v_mfma_f32_16x16x32_bf16 v[104:107], v[156:159], v[194:197], v[104:107]
	v_mfma_f32_16x16x32_bf16 v[104:107], v[160:163], v[198:201], v[104:107]
	v_mfma_f32_16x16x32_bf16 v[108:111], v[144:147], v[198:201], v[108:111]
	v_mfma_f32_16x16x32_bf16 v[108:111], v[140:143], v[194:197], v[108:111]
	v_mfma_f32_16x16x32_bf16 v[92:95], v[140:143], v[202:205], v[92:95]
	v_mfma_f32_16x16x32_bf16 v[92:95], v[144:147], v[206:209], v[92:95]
	v_mfma_f32_16x16x32_bf16 v[88:91], v[160:163], v[206:209], v[88:91]
	v_mfma_f32_16x16x32_bf16 v[88:91], v[156:159], v[202:205], v[88:91]
	v_mfma_f32_16x16x32_bf16 v[72:75], v[156:159], v[210:213], v[72:75]
	v_mfma_f32_16x16x32_bf16 v[72:75], v[160:163], v[214:217], v[72:75]
	v_mfma_f32_16x16x32_bf16 v[76:79], v[144:147], v[214:217], v[76:79]
	v_mfma_f32_16x16x32_bf16 v[76:79], v[140:143], v[210:213], v[76:79]
	s_setprio 0
	s_setprio 1
	v_mfma_f32_16x16x32_bf16 v[116:119], v[170:173], v[186:189], v[116:119]
	v_mfma_f32_16x16x32_bf16 v[116:119], v[174:177], v[190:193], v[116:119]
	v_mfma_f32_16x16x32_bf16 v[112:115], v[182:185], v[190:193], v[112:115]
	v_mfma_f32_16x16x32_bf16 v[112:115], v[178:181], v[186:189], v[112:115]
	v_mfma_f32_16x16x32_bf16 v[96:99], v[178:181], v[194:197], v[96:99]
	v_mfma_f32_16x16x32_bf16 v[96:99], v[182:185], v[198:201], v[96:99]
	v_mfma_f32_16x16x32_bf16 v[100:103], v[174:177], v[198:201], v[100:103]
	v_mfma_f32_16x16x32_bf16 v[100:103], v[170:173], v[194:197], v[100:103]
	v_mfma_f32_16x16x32_bf16 v[84:87], v[170:173], v[202:205], v[84:87]
	v_mfma_f32_16x16x32_bf16 v[84:87], v[174:177], v[206:209], v[84:87]
	v_mfma_f32_16x16x32_bf16 v[80:83], v[182:185], v[206:209], v[80:83]
	v_mfma_f32_16x16x32_bf16 v[80:83], v[178:181], v[202:205], v[80:83]
	v_mfma_f32_16x16x32_bf16 v[64:67], v[178:181], v[210:213], v[64:67]
	v_mfma_f32_16x16x32_bf16 v[64:67], v[182:185], v[214:217], v[64:67]
	v_mfma_f32_16x16x32_bf16 v[68:71], v[174:177], v[214:217], v[68:71]
	v_mfma_f32_16x16x32_bf16 v[68:71], v[170:173], v[210:213], v[68:71]
	s_setprio 0
	s_barrier
; #define PG8_STAGE(bufoff, gbase, voff) do { _Pragma("unroll") for (int _i = 0; _i < 2; ++_i) \
;         __builtin_amdgcn_global_load_lds((const unsigned*)((const char*)(gbase) + (voff)[_i]), (LAS unsigned*)(lds + (bufoff) + ldsw + _i * 8192), 16, 0, 0); } while (0)
; #define PG8_LDA(dst, b, h) do { _Pragma("unroll") for (int m = 0; m < 4; ++m) _Pragma("unroll") for (int k = 0; k < 2; ++k) dst[m][k] = *(const LAS bf16x8*)(lds + PG8_SA(b, h) + aoff + m * 2048 + k * 1024); } while (0)
; #define PG8_MMA(ai, bj, At, Bt) do { __builtin_amdgcn_s_setprio(1); _Pragma("unroll") for (int m = 0; m < 4; ++m) _Pragma("unroll") for (int n = 0; n < 2; ++n) _Pragma("unroll") for (int k = 0; k < 2; ++k) \
;         acc[ai][bj][m][n] = __builtin_amdgcn_mfma_f32_16x16x32_bf16(Bt[n][k], At[m][k], acc[ai][bj][m][n], 0, 0, 0); __builtin_amdgcn_s_setprio(0); } while (0)
; #define PG8_WAIT_V(n) asm volatile("s_waitcnt vmcnt(" #n ")" ::: "memory")
; #define PG8_WAIT_L(n) asm volatile("s_waitcnt lgkmcnt(" #n ")" ::: "memory")
; #define PG8_BAR __builtin_amdgcn_s_barrier()
; #define PG8_SCHED __builtin_amdgcn_sched_barrier(0)
; DI void gemm_phase(LAS unsigned char* lds, const Gemm g, const StaticOrder& S, const Epi& E) {
;     ...
;             PG8_LDA(At, 1, 1); PG8_STAGE(PG8_SB(1, 0), b3, voffB); PG8_STAGE(PG8_SB(1, 1), b3 + hsB, voffB); PG8_STAGE(PG8_SA(1, 0), a3, voffA);
;             PG8_WAIT_V(8); PG8_WAIT_L(0); PG8_BAR; PG8_MMA(1, 0, At, B0); PG8_MMA(1, 1, At, B1); PG8_BAR; PG8_SCHED;
;         }
	s_mov_b32 m0, s47
	ds_read_b128 v[186:189], v155 offset:49152
	ds_read_b128 v[190:193], v155 offset:50176
	ds_read_b128 v[194:197], v155 offset:51200
	ds_read_b128 v[198:201], v155 offset:52224
	ds_read_b128 v[202:205], v155 offset:53248
	ds_read_b128 v[206:209], v155 offset:54272
	ds_read_b128 v[210:213], v155 offset:55296
	ds_read_b128 v[214:217], v155 offset:56320
	global_load_lds_dwordx4 v130, s[98:99]
	s_mov_b32 m0, s46
	s_nop 0
	global_load_lds_dwordx4 v134, s[98:99]
	s_mov_b32 m0, s81
	s_nop 0
	global_load_lds_dwordx4 v130, s[34:35]
	s_mov_b32 m0, s80
	s_nop 0
	global_load_lds_dwordx4 v134, s[34:35]
	s_mov_b32 m0, s58
	s_nop 0
	global_load_lds_dwordx4 v128, s[100:101]
	s_mov_b32 m0, s59
	s_nop 0
	global_load_lds_dwordx4 v132, s[100:101]
	s_waitcnt vmcnt(8)
	s_waitcnt lgkmcnt(0)
	s_barrier
	s_setprio 1
	s_waitcnt lgkmcnt(0)
	v_mfma_f32_16x16x32_bf16 v[60:63], v[140:143], v[186:189], v[60:63]
	v_mfma_f32_16x16x32_bf16 v[60:63], v[144:147], v[190:193], v[60:63]
	v_mfma_f32_16x16x32_bf16 v[56:59], v[160:163], v[190:193], v[56:59]
	v_mfma_f32_16x16x32_bf16 v[56:59], v[156:159], v[186:189], v[56:59]
	v_mfma_f32_16x16x32_bf16 v[40:43], v[156:159], v[194:197], v[40:43]
	v_mfma_f32_16x16x32_bf16 v[40:43], v[160:163], v[198:201], v[40:43]
	v_mfma_f32_16x16x32_bf16 v[44:47], v[144:147], v[198:201], v[44:47]
	v_mfma_f32_16x16x32_bf16 v[44:47], v[140:143], v[194:197], v[44:47]
	v_mfma_f32_16x16x32_bf16 v[28:31], v[140:143], v[202:205], v[28:31]
	v_mfma_f32_16x16x32_bf16 v[28:31], v[144:147], v[206:209], v[28:31]
	v_mfma_f32_16x16x32_bf16 v[24:27], v[160:163], v[206:209], v[24:27]
	v_mfma_f32_16x16x32_bf16 v[24:27], v[156:159], v[202:205], v[24:27]
	v_mfma_f32_16x16x32_bf16 v[8:11], v[156:159], v[210:213], v[8:11]
	v_mfma_f32_16x16x32_bf16 v[8:11], v[160:163], v[214:217], v[8:11]
	v_mfma_f32_16x16x32_bf16 v[12:15], v[144:147], v[214:217], v[12:15]
	v_mfma_f32_16x16x32_bf16 v[12:15], v[140:143], v[210:213], v[12:15]
	s_setprio 0
	s_setprio 1
	v_mfma_f32_16x16x32_bf16 v[52:55], v[170:173], v[186:189], v[52:55]
	v_mfma_f32_16x16x32_bf16 v[52:55], v[174:177], v[190:193], v[52:55]
	v_mfma_f32_16x16x32_bf16 v[48:51], v[182:185], v[190:193], v[48:51]
	v_mfma_f32_16x16x32_bf16 v[48:51], v[178:181], v[186:189], v[48:51]
	v_mfma_f32_16x16x32_bf16 v[32:35], v[178:181], v[194:197], v[32:35]
	v_mfma_f32_16x16x32_bf16 v[32:35], v[182:185], v[198:201], v[32:35]
	v_mfma_f32_16x16x32_bf16 v[36:39], v[174:177], v[198:201], v[36:39]
	v_mfma_f32_16x16x32_bf16 v[36:39], v[170:173], v[194:197], v[36:39]
	v_mfma_f32_16x16x32_bf16 v[20:23], v[170:173], v[202:205], v[20:23]
	v_mfma_f32_16x16x32_bf16 v[20:23], v[174:177], v[206:209], v[20:23]
	v_mfma_f32_16x16x32_bf16 v[16:19], v[182:185], v[206:209], v[16:19]
	v_mfma_f32_16x16x32_bf16 v[16:19], v[178:181], v[202:205], v[16:19]
	v_mfma_f32_16x16x32_bf16 v[0:3], v[178:181], v[210:213], v[0:3]
	v_mfma_f32_16x16x32_bf16 v[0:3], v[182:185], v[214:217], v[0:3]
	v_mfma_f32_16x16x32_bf16 v[4:7], v[174:177], v[214:217], v[4:7]
	v_mfma_f32_16x16x32_bf16 v[4:7], v[170:173], v[210:213], v[4:7]
	s_setprio 0
	s_barrier
	s_movk_i32 s46, 0x100
	s_andn2_b64 vcc, exec, s[6:7]
	s_mov_b64 s[34:35], -1
	s_mov_b64 s[6:7], 0

; #define PG8_STAGE(bufoff, gbase, voff) do { _Pragma("unroll") for (int _i = 0; _i < 2; ++_i) \
;         __builtin_amdgcn_global_load_lds((const unsigned*)((const char*)(gbase) + (voff)[_i]), (LAS unsigned*)(lds + (bufoff) + ldsw + _i * 8192), 16, 0, 0); } while (0)
; #define PG8_LDA(dst, b, h) do { _Pragma("unroll") for (int m = 0; m < 4; ++m) _Pragma("unroll") for (int k = 0; k < 2; ++k) dst[m][k] = *(const LAS bf16x8*)(lds + PG8_SA(b, h) + aoff + m * 2048 + k * 1024); } while (0)
; #define PG8_LDB(dst, b, h) do { _Pragma("unroll") for (int n = 0; n < 2; ++n) _Pragma("unroll") for (int k = 0; k < 2; ++k) dst[n][k] = *(const LAS bf16x8*)(lds + PG8_SB(b, h) + boff + n * 2048 + k * 1024); } while (0)
; #define PG8_MMA(ai, bj, At, Bt) do { __builtin_amdgcn_s_setprio(1); _Pragma("unroll") for (int m = 0; m < 4; ++m) _Pragma("unroll") for (int n = 0; n < 2; ++n) _Pragma("unroll") for (int k = 0; k < 2; ++k) \
;         acc[ai][bj][m][n] = __builtin_amdgcn_mfma_f32_16x16x32_bf16(Bt[n][k], At[m][k], acc[ai][bj][m][n], 0, 0, 0); __builtin_amdgcn_s_setprio(0); } while (0)
; #define PG8_WAIT_V(n) asm volatile("s_waitcnt vmcnt(" #n ")" ::: "memory")
; #define PG8_BAR __builtin_amdgcn_s_barrier()
; DI void gemm_phase(LAS unsigned char* lds, const Gemm g, const StaticOrder& S, const Epi& E) {
;     ...
;         const bool has_next = S.next(ui + 1, nxt);
;         const char* nA = has_next ? (const char*)g.A + (size_t)nxt.pm * tsA : cA; const char* nB = has_next ? (const char*)g.Bt + (size_t)nxt.pn * tsB : cB;
;         for (int t = 0; t < nt; t += 2) {
;             const bool last = (t == nt - 2);
;             const char* a1 = cA + (size_t)(t + 1) * kstep;
;             const char* a2 = last ? nA : cA + (size_t)(t + 2) * kstep; const char* b2 = last ? nB : cB + (size_t)(t + 2) * kstep;
;             const char* a3 = a2 + kstep; const char* b3 = b2 + kstep;
;             PG8_LDB(B0, 0, 0); PG8_LDB(B1, 0, 1); PG8_SCHED; PG8_LDA(At, 0, 0); PG8_STAGE(PG8_SA(1, 1), a1 + hsA, voffA);
;             PG8_WAIT_V(8); PG8_WAIT_L(0); PG8_BAR; PG8_MMA(0, 0, At, B0); PG8_MMA(0, 1, At, B1); PG8_BAR; PG8_SCHED;
;             PG8_LDA(At, 0, 1); PG8_STAGE(PG8_SB(0, 0), b2, voffB); PG8_STAGE(PG8_SB(0, 1), b2 + hsB, voffB); PG8_STAGE(PG8_SA(0, 0), a2, voffA);
;             PG8_WAIT_V(8); PG8_WAIT_L(0); PG8_BAR; PG8_MMA(1, 0, At, B0); PG8_MMA(1, 1, At, B1); PG8_BAR; PG8_SCHED;
.LBB0_460:
	s_ashr_i32 s21, s20, 31
	s_lshl_b64 s[24:25], s[20:21], 17
	s_add_u32 s24, s12, s24
	s_addc_u32 s25, s13, s25
	s_and_b64 s[4:5], s[4:5], exec
	v_mov_b32_e32 v0, 0
	s_cselect_b32 s21, s25, s31
	s_cselect_b32 s76, s24, s30
	s_mov_b32 s46, 0
	s_mov_b64 s[4:5], -1
	s_mov_b64 s[34:35], 0
	s_add_u32 s47, s30, s46
	s_addc_u32 s68, s31, 0
	s_add_u32 s56, s47, 0x100
	s_addc_u32 s57, s68, 0
	s_and_b64 s[54:55], s[34:35], exec
	s_cselect_b32 s57, s21, s57
	s_cselect_b32 s56, s76, s56
	s_add_u32 s46, s28, s46
	s_addc_u32 s54, s29, 0
	s_add_u32 s46, s46, 0x100
	s_addc_u32 s54, s54, 0
	s_and_b64 s[34:35], s[34:35], exec
	s_cselect_b32 s67, s23, s54
	s_cselect_b32 s66, s22, s46
	s_add_u32 s70, s47, 0x10080
	s_addc_u32 s71, s68, 0
	s_add_i32 s84, s58, s33
	ds_read_b128 v[140:143], v149
	ds_read_b128 v[152:155], v149 offset:1024
	ds_read_b128 v[156:159], v149 offset:2048
	ds_read_b128 v[160:163], v149 offset:3072
	ds_read_b128 v[170:173], v150
	ds_read_b128 v[174:177], v150 offset:1024
	ds_read_b128 v[178:181], v150 offset:2048
	ds_read_b128 v[182:185], v150 offset:3072
	s_add_i32 m0, s27, 0xc000
	s_add_i32 s85, s27, 0xe000
	s_add_i32 s81, s84, 0x2000
	s_add_u32 s68, s66, 0xb0000
	s_addc_u32 s69, s67, 0
	s_add_i32 s83, s59, s33
	s_add_i32 s82, s83, 0x2000
	s_add_i32 s80, 0, 0x18000
	s_add_i32 s79, 0, 0x1c000
	s_add_u32 s54, s56, 0x10000
	s_addc_u32 s55, s57, 0
	s_add_i32 s78, s80, s33
	s_add_i32 s47, s78, 0x2000
	s_add_u32 s34, s66, 0xb0080
	s_addc_u32 s35, s67, 0
	s_add_i32 s77, s79, s33
	s_add_i32 s46, s77, 0x2000
	ds_read_b128 v[186:189], v151
	ds_read_b128 v[190:193], v151 offset:1024
	ds_read_b128 v[194:197], v151 offset:2048
	ds_read_b128 v[198:201], v151 offset:3072
	ds_read_b128 v[202:205], v151 offset:4096
	ds_read_b128 v[206:209], v151 offset:5120
	ds_read_b128 v[210:213], v151 offset:6144
	ds_read_b128 v[214:217], v151 offset:7168
	global_load_lds_dwordx4 v128, s[70:71]
	s_mov_b32 m0, s85
	s_nop 0
	global_load_lds_dwordx4 v132, s[70:71]
	s_waitcnt vmcnt(8)
	s_waitcnt lgkmcnt(0)
	s_barrier
	s_setprio 1
	s_waitcnt lgkmcnt(0)
	v_mfma_f32_16x16x32_bf16 v[124:127], v[140:143], v[186:189], 0
	v_mfma_f32_16x16x32_bf16 v[124:127], v[152:155], v[190:193], v[124:127]
	v_mfma_f32_16x16x32_bf16 v[120:123], v[160:163], v[190:193], 0
	v_mfma_f32_16x16x32_bf16 v[120:123], v[156:159], v[186:189], v[120:123]
	v_mfma_f32_16x16x32_bf16 v[104:107], v[156:159], v[194:197], 0
	v_mfma_f32_16x16x32_bf16 v[104:107], v[160:163], v[198:201], v[104:107]
	v_mfma_f32_16x16x32_bf16 v[108:111], v[152:155], v[198:201], 0
	v_mfma_f32_16x16x32_bf16 v[108:111], v[140:143], v[194:197], v[108:111]
	v_mfma_f32_16x16x32_bf16 v[92:95], v[140:143], v[202:205], 0
	v_mfma_f32_16x16x32_bf16 v[92:95], v[152:155], v[206:209], v[92:95]
	v_mfma_f32_16x16x32_bf16 v[88:91], v[160:163], v[206:209], 0
	v_mfma_f32_16x16x32_bf16 v[88:91], v[156:159], v[202:205], v[88:91]
	v_mfma_f32_16x16x32_bf16 v[72:75], v[156:159], v[210:213], 0
	v_mfma_f32_16x16x32_bf16 v[72:75], v[160:163], v[214:217], v[72:75]
	v_mfma_f32_16x16x32_bf16 v[76:79], v[152:155], v[214:217], 0
	v_mfma_f32_16x16x32_bf16 v[76:79], v[140:143], v[210:213], v[76:79]
	s_setprio 0
	s_setprio 1
	v_mfma_f32_16x16x32_bf16 v[116:119], v[170:173], v[186:189], 0
	v_mfma_f32_16x16x32_bf16 v[116:119], v[174:177], v[190:193], v[116:119]
	v_mfma_f32_16x16x32_bf16 v[112:115], v[182:185], v[190:193], 0
	v_mfma_f32_16x16x32_bf16 v[112:115], v[178:181], v[186:189], v[112:115]
	v_mfma_f32_16x16x32_bf16 v[96:99], v[178:181], v[194:197], 0
	v_mfma_f32_16x16x32_bf16 v[96:99], v[182:185], v[198:201], v[96:99]
	v_mfma_f32_16x16x32_bf16 v[100:103], v[174:177], v[198:201], 0
	v_mfma_f32_16x16x32_bf16 v[100:103], v[170:173], v[194:197], v[100:103]
	v_mfma_f32_16x16x32_bf16 v[84:87], v[170:173], v[202:205], 0
	v_mfma_f32_16x16x32_bf16 v[84:87], v[174:177], v[206:209], v[84:87]
	v_mfma_f32_16x16x32_bf16 v[80:83], v[182:185], v[206:209], 0
	v_mfma_f32_16x16x32_bf16 v[80:83], v[178:181], v[202:205], v[80:83]
	v_mfma_f32_16x16x32_bf16 v[64:67], v[178:181], v[210:213], 0
	v_mfma_f32_16x16x32_bf16 v[64:67], v[182:185], v[214:217], v[64:67]
	v_mfma_f32_16x16x32_bf16 v[68:71], v[174:177], v[214:217], 0
	v_mfma_f32_16x16x32_bf16 v[68:71], v[170:173], v[210:213], v[68:71]
	s_setprio 0
	s_barrier
	s_mov_b32 m0, s84
	s_add_u32 s98, s66, 0x80
	s_addc_u32 s99, s67, 0
	ds_read_b128 v[186:189], v151 offset:16384
	ds_read_b128 v[190:193], v151 offset:17408
	ds_read_b128 v[194:197], v151 offset:18432
	ds_read_b128 v[198:201], v151 offset:19456
	ds_read_b128 v[202:205], v151 offset:20480
	ds_read_b128 v[206:209], v151 offset:21504
	ds_read_b128 v[210:213], v151 offset:22528
	ds_read_b128 v[214:217], v151 offset:23552
	global_load_lds_dwordx4 v130, s[66:67]
	s_mov_b32 m0, s81
	s_nop 0
	global_load_lds_dwordx4 v134, s[66:67]
	s_mov_b32 m0, s83
	s_nop 0
	global_load_lds_dwordx4 v130, s[68:69]
	s_mov_b32 m0, s82
	s_nop 0
	global_load_lds_dwordx4 v134, s[68:69]
	s_add_u32 s100, s56, 0x80
	s_addc_u32 s101, s57, 0
	s_mov_b32 m0, s27
	s_nop 0
	global_load_lds_dwordx4 v128, s[56:57]
	s_mov_b32 m0, s40
	s_nop 0
	global_load_lds_dwordx4 v132, s[56:57]
	s_waitcnt vmcnt(8)
	s_waitcnt lgkmcnt(0)
	s_barrier
; #define PG8_STAGE(bufoff, gbase, voff) do { _Pragma("unroll") for (int _i = 0; _i < 2; ++_i) \
;         __builtin_amdgcn_global_load_lds((const unsigned*)((const char*)(gbase) + (voff)[_i]), (LAS unsigned*)(lds + (bufoff) + ldsw + _i * 8192), 16, 0, 0); } while (0)
; #define PG8_LDA(dst, b, h) do { _Pragma("unroll") for (int m = 0; m < 4; ++m) _Pragma("unroll") for (int k = 0; k < 2; ++k) dst[m][k] = *(const LAS bf16x8*)(lds + PG8_SA(b, h) + aoff + m * 2048 + k * 1024); } while (0)
; #define PG8_LDB(dst, b, h) do { _Pragma("unroll") for (int n = 0; n < 2; ++n) _Pragma("unroll") for (int k = 0; k < 2; ++k) dst[n][k] = *(const LAS bf16x8*)(lds + PG8_SB(b, h) + boff + n * 2048 + k * 1024); } while (0)
; #define PG8_MMA(ai, bj, At, Bt) do { __builtin_amdgcn_s_setprio(1); _Pragma("unroll") for (int m = 0; m < 4; ++m) _Pragma("unroll") for (int n = 0; n < 2; ++n) _Pragma("unroll") for (int k = 0; k < 2; ++k) \
;         acc[ai][bj][m][n] = __builtin_amdgcn_mfma_f32_16x16x32_bf16(Bt[n][k], At[m][k], acc[ai][bj][m][n], 0, 0, 0); __builtin_amdgcn_s_setprio(0); } while (0)
; #define PG8_WAIT_V(n) asm volatile("s_waitcnt vmcnt(" #n ")" ::: "memory")
; #define PG8_WAIT_L(n) asm volatile("s_waitcnt lgkmcnt(" #n ")" ::: "memory")
; #define PG8_BAR __builtin_amdgcn_s_barrier()
; #define PG8_SCHED __builtin_amdgcn_sched_barrier(0)
; DI void gemm_phase(LAS unsigned char* lds, const Gemm g, const StaticOrder& S, const Epi& E) {
;     ...
;             PG8_WAIT_V(8); PG8_WAIT_L(0); PG8_BAR; PG8_MMA(1, 0, At, B0); PG8_MMA(1, 1, At, B1); PG8_BAR; PG8_SCHED;
;             PG8_LDB(B0, 1, 0); PG8_LDB(B1, 1, 1); PG8_SCHED; PG8_LDA(At, 1, 0); PG8_STAGE(PG8_SA(0, 1), a2 + hsA, voffA);
;             PG8_WAIT_V(8); PG8_WAIT_L(0); PG8_BAR; PG8_MMA(0, 0, At, B0); PG8_MMA(0, 1, At, B1); PG8_BAR; PG8_SCHED;
	s_setprio 1
	s_waitcnt lgkmcnt(0)
	v_mfma_f32_16x16x32_bf16 v[60:63], v[140:143], v[186:189], 0
	v_mfma_f32_16x16x32_bf16 v[60:63], v[152:155], v[190:193], v[60:63]
	v_mfma_f32_16x16x32_bf16 v[56:59], v[160:163], v[190:193], 0
	v_mfma_f32_16x16x32_bf16 v[56:59], v[156:159], v[186:189], v[56:59]
	v_mfma_f32_16x16x32_bf16 v[40:43], v[156:159], v[194:197], 0
	v_mfma_f32_16x16x32_bf16 v[40:43], v[160:163], v[198:201], v[40:43]
	v_mfma_f32_16x16x32_bf16 v[44:47], v[152:155], v[198:201], 0
	v_mfma_f32_16x16x32_bf16 v[44:47], v[140:143], v[194:197], v[44:47]
	v_mfma_f32_16x16x32_bf16 v[28:31], v[140:143], v[202:205], 0
	v_mfma_f32_16x16x32_bf16 v[28:31], v[152:155], v[206:209], v[28:31]
	v_mfma_f32_16x16x32_bf16 v[24:27], v[160:163], v[206:209], 0
	v_mfma_f32_16x16x32_bf16 v[24:27], v[156:159], v[202:205], v[24:27]
	v_mfma_f32_16x16x32_bf16 v[8:11], v[156:159], v[210:213], 0
	v_mfma_f32_16x16x32_bf16 v[8:11], v[160:163], v[214:217], v[8:11]
	v_mfma_f32_16x16x32_bf16 v[12:15], v[152:155], v[214:217], 0
	v_mfma_f32_16x16x32_bf16 v[12:15], v[140:143], v[210:213], v[12:15]
	s_setprio 0
	s_setprio 1
	v_mfma_f32_16x16x32_bf16 v[52:55], v[170:173], v[186:189], 0
	v_mfma_f32_16x16x32_bf16 v[52:55], v[174:177], v[190:193], v[52:55]
	v_mfma_f32_16x16x32_bf16 v[48:51], v[182:185], v[190:193], 0
	v_mfma_f32_16x16x32_bf16 v[48:51], v[178:181], v[186:189], v[48:51]
	v_mfma_f32_16x16x32_bf16 v[32:35], v[178:181], v[194:197], 0
	v_mfma_f32_16x16x32_bf16 v[32:35], v[182:185], v[198:201], v[32:35]
	v_mfma_f32_16x16x32_bf16 v[36:39], v[174:177], v[198:201], 0
	v_mfma_f32_16x16x32_bf16 v[36:39], v[170:173], v[194:197], v[36:39]
	v_mfma_f32_16x16x32_bf16 v[20:23], v[170:173], v[202:205], 0
	v_mfma_f32_16x16x32_bf16 v[20:23], v[174:177], v[206:209], v[20:23]
	v_mfma_f32_16x16x32_bf16 v[16:19], v[182:185], v[206:209], 0
	v_mfma_f32_16x16x32_bf16 v[16:19], v[178:181], v[202:205], v[16:19]
	v_mfma_f32_16x16x32_bf16 v[0:3], v[178:181], v[210:213], 0
	v_mfma_f32_16x16x32_bf16 v[0:3], v[182:185], v[214:217], v[0:3]
	v_mfma_f32_16x16x32_bf16 v[4:7], v[174:177], v[214:217], 0
	v_mfma_f32_16x16x32_bf16 v[4:7], v[170:173], v[210:213], v[4:7]
	s_setprio 0
	s_barrier
	v_add_u32_e32 v160, s80, v147
	v_add_u32_e32 v166, s79, v147
	ds_read_b128 v[140:143], v160
	ds_read_b128 v[152:155], v160 offset:1024
	ds_read_b128 v[156:159], v160 offset:2048
	ds_read_b128 v[160:163], v160 offset:3072
	ds_read_b128 v[170:173], v166
	ds_read_b128 v[174:177], v166 offset:1024
	ds_read_b128 v[178:181], v166 offset:2048
	ds_read_b128 v[182:185], v166 offset:3072
	s_mov_b32 m0, s41
	ds_read_b128 v[186:189], v151 offset:32768
	ds_read_b128 v[190:193], v151 offset:33792
	ds_read_b128 v[194:197], v151 offset:34816
	ds_read_b128 v[198:201], v151 offset:35840
	ds_read_b128 v[202:205], v151 offset:36864
	ds_read_b128 v[206:209], v151 offset:37888
	ds_read_b128 v[210:213], v151 offset:38912
	ds_read_b128 v[214:217], v151 offset:39936
	global_load_lds_dwordx4 v128, s[54:55]
	s_mov_b32 m0, s42
	s_nop 0
	global_load_lds_dwordx4 v132, s[54:55]
	s_waitcnt vmcnt(8)
	s_waitcnt lgkmcnt(0)
	s_barrier
	s_setprio 1
	s_waitcnt lgkmcnt(0)
	v_mfma_f32_16x16x32_bf16 v[124:127], v[140:143], v[186:189], v[124:127]
	v_mfma_f32_16x16x32_bf16 v[124:127], v[152:155], v[190:193], v[124:127]
	v_mfma_f32_16x16x32_bf16 v[120:123], v[160:163], v[190:193], v[120:123]
	v_mfma_f32_16x16x32_bf16 v[120:123], v[156:159], v[186:189], v[120:123]
	v_mfma_f32_16x16x32_bf16 v[104:107], v[156:159], v[194:197], v[104:107]
	v_mfma_f32_16x16x32_bf16 v[104:107], v[160:163], v[198:201], v[104:107]
	v_mfma_f32_16x16x32_bf16 v[108:111], v[152:155], v[198:201], v[108:111]
	v_mfma_f32_16x16x32_bf16 v[108:111], v[140:143], v[194:197], v[108:111]
	v_mfma_f32_16x16x32_bf16 v[92:95], v[140:143], v[202:205], v[92:95]
	v_mfma_f32_16x16x32_bf16 v[92:95], v[152:155], v[206:209], v[92:95]
	v_mfma_f32_16x16x32_bf16 v[88:91], v[160:163], v[206:209], v[88:91]
	v_mfma_f32_16x16x32_bf16 v[88:91], v[156:159], v[202:205], v[88:91]
	v_mfma_f32_16x16x32_bf16 v[72:75], v[156:159], v[210:213], v[72:75]
	v_mfma_f32_16x16x32_bf16 v[72:75], v[160:163], v[214:217], v[72:75]
	v_mfma_f32_16x16x32_bf16 v[76:79], v[152:155], v[214:217], v[76:79]
	v_mfma_f32_16x16x32_bf16 v[76:79], v[140:143], v[210:213], v[76:79]
	s_setprio 0
	s_setprio 1
	v_mfma_f32_16x16x32_bf16 v[116:119], v[170:173], v[186:189], v[116:119]
	v_mfma_f32_16x16x32_bf16 v[116:119], v[174:177], v[190:193], v[116:119]
	v_mfma_f32_16x16x32_bf16 v[112:115], v[182:185], v[190:193], v[112:115]
	v_mfma_f32_16x16x32_bf16 v[112:115], v[178:181], v[186:189], v[112:115]
	v_mfma_f32_16x16x32_bf16 v[96:99], v[178:181], v[194:197], v[96:99]
	v_mfma_f32_16x16x32_bf16 v[96:99], v[182:185], v[198:201], v[96:99]
	v_mfma_f32_16x16x32_bf16 v[100:103], v[174:177], v[198:201], v[100:103]
	v_mfma_f32_16x16x32_bf16 v[100:103], v[170:173], v[194:197], v[100:103]
	v_mfma_f32_16x16x32_bf16 v[84:87], v[170:173], v[202:205], v[84:87]
	v_mfma_f32_16x16x32_bf16 v[84:87], v[174:177], v[206:209], v[84:87]
	v_mfma_f32_16x16x32_bf16 v[80:83], v[182:185], v[206:209], v[80:83]
	v_mfma_f32_16x16x32_bf16 v[80:83], v[178:181], v[202:205], v[80:83]
	v_mfma_f32_16x16x32_bf16 v[64:67], v[178:181], v[210:213], v[64:67]
	v_mfma_f32_16x16x32_bf16 v[64:67], v[182:185], v[214:217], v[64:67]
	v_mfma_f32_16x16x32_bf16 v[68:71], v[174:177], v[214:217], v[68:71]
	v_mfma_f32_16x16x32_bf16 v[68:71], v[170:173], v[210:213], v[68:71]
	s_setprio 0
	s_barrier
; #define PG8_STAGE(bufoff, gbase, voff) do { _Pragma("unroll") for (int _i = 0; _i < 2; ++_i) \
;         __builtin_amdgcn_global_load_lds((const unsigned*)((const char*)(gbase) + (voff)[_i]), (LAS unsigned*)(lds + (bufoff) + ldsw + _i * 8192), 16, 0, 0); } while (0)
; #define PG8_LDA(dst, b, h) do { _Pragma("unroll") for (int m = 0; m < 4; ++m) _Pragma("unroll") for (int k = 0; k < 2; ++k) dst[m][k] = *(const LAS bf16x8*)(lds + PG8_SA(b, h) + aoff + m * 2048 + k * 1024); } while (0)
; #define PG8_MMA(ai, bj, At, Bt) do { __builtin_amdgcn_s_setprio(1); _Pragma("unroll") for (int m = 0; m < 4; ++m) _Pragma("unroll") for (int n = 0; n < 2; ++n) _Pragma("unroll") for (int k = 0; k < 2; ++k) \
;         acc[ai][bj][m][n] = __builtin_amdgcn_mfma_f32_16x16x32_bf16(Bt[n][k], At[m][k], acc[ai][bj][m][n], 0, 0, 0); __builtin_amdgcn_s_setprio(0); } while (0)
; #define PG8_WAIT_V(n) asm volatile("s_waitcnt vmcnt(" #n ")" ::: "memory")
; #define PG8_WAIT_L(n) asm volatile("s_waitcnt lgkmcnt(" #n ")" ::: "memory")
; #define PG8_BAR __builtin_amdgcn_s_barrier()
; #define PG8_SCHED __builtin_amdgcn_sched_barrier(0)
; DI void gemm_phase(LAS unsigned char* lds, const Gemm g, const StaticOrder& S, const Epi& E) {
;     ...
;             PG8_LDA(At, 1, 1); PG8_STAGE(PG8_SB(1, 0), b3, voffB); PG8_STAGE(PG8_SB(1, 1), b3 + hsB, voffB); PG8_STAGE(PG8_SA(1, 0), a3, voffA);
;             PG8_WAIT_V(8); PG8_WAIT_L(0); PG8_BAR; PG8_MMA(1, 0, At, B0); PG8_MMA(1, 1, At, B1); PG8_BAR; PG8_SCHED;
	s_mov_b32 m0, s78
	ds_read_b128 v[186:189], v151 offset:49152
	ds_read_b128 v[190:193], v151 offset:50176
	ds_read_b128 v[194:197], v151 offset:51200
	ds_read_b128 v[198:201], v151 offset:52224
	ds_read_b128 v[202:205], v151 offset:53248
	ds_read_b128 v[206:209], v151 offset:54272
	ds_read_b128 v[210:213], v151 offset:55296
	ds_read_b128 v[214:217], v151 offset:56320
	global_load_lds_dwordx4 v130, s[98:99]
	s_mov_b32 m0, s47
	s_nop 0
	global_load_lds_dwordx4 v134, s[98:99]
	s_mov_b32 m0, s77
	s_nop 0
	global_load_lds_dwordx4 v130, s[34:35]
	s_mov_b32 m0, s46
	s_nop 0
	global_load_lds_dwordx4 v134, s[34:35]
	s_mov_b32 m0, s48
	s_nop 0
	global_load_lds_dwordx4 v128, s[100:101]
	s_mov_b32 m0, s49
	s_nop 0
	global_load_lds_dwordx4 v132, s[100:101]
	s_waitcnt vmcnt(8)
	s_waitcnt lgkmcnt(0)
	s_barrier
	s_setprio 1
	s_waitcnt lgkmcnt(0)
	v_mfma_f32_16x16x32_bf16 v[60:63], v[140:143], v[186:189], v[60:63]
	v_mfma_f32_16x16x32_bf16 v[60:63], v[152:155], v[190:193], v[60:63]
	v_mfma_f32_16x16x32_bf16 v[56:59], v[160:163], v[190:193], v[56:59]
	v_mfma_f32_16x16x32_bf16 v[56:59], v[156:159], v[186:189], v[56:59]
	v_mfma_f32_16x16x32_bf16 v[40:43], v[156:159], v[194:197], v[40:43]
	v_mfma_f32_16x16x32_bf16 v[40:43], v[160:163], v[198:201], v[40:43]
	v_mfma_f32_16x16x32_bf16 v[44:47], v[152:155], v[198:201], v[44:47]
	v_mfma_f32_16x16x32_bf16 v[44:47], v[140:143], v[194:197], v[44:47]
	v_mfma_f32_16x16x32_bf16 v[28:31], v[140:143], v[202:205], v[28:31]
	v_mfma_f32_16x16x32_bf16 v[28:31], v[152:155], v[206:209], v[28:31]
	v_mfma_f32_16x16x32_bf16 v[24:27], v[160:163], v[206:209], v[24:27]
	v_mfma_f32_16x16x32_bf16 v[24:27], v[156:159], v[202:205], v[24:27]
	v_mfma_f32_16x16x32_bf16 v[8:11], v[156:159], v[210:213], v[8:11]
	v_mfma_f32_16x16x32_bf16 v[8:11], v[160:163], v[214:217], v[8:11]
	v_mfma_f32_16x16x32_bf16 v[12:15], v[152:155], v[214:217], v[12:15]
	v_mfma_f32_16x16x32_bf16 v[12:15], v[140:143], v[210:213], v[12:15]
	s_setprio 0
	s_setprio 1
	v_mfma_f32_16x16x32_bf16 v[52:55], v[170:173], v[186:189], v[52:55]
	v_mfma_f32_16x16x32_bf16 v[52:55], v[174:177], v[190:193], v[52:55]
	v_mfma_f32_16x16x32_bf16 v[48:51], v[182:185], v[190:193], v[48:51]
	v_mfma_f32_16x16x32_bf16 v[48:51], v[178:181], v[186:189], v[48:51]
	v_mfma_f32_16x16x32_bf16 v[32:35], v[178:181], v[194:197], v[32:35]
	v_mfma_f32_16x16x32_bf16 v[32:35], v[182:185], v[198:201], v[32:35]
	v_mfma_f32_16x16x32_bf16 v[36:39], v[174:177], v[198:201], v[36:39]
	v_mfma_f32_16x16x32_bf16 v[36:39], v[170:173], v[194:197], v[36:39]
	v_mfma_f32_16x16x32_bf16 v[20:23], v[170:173], v[202:205], v[20:23]
	v_mfma_f32_16x16x32_bf16 v[20:23], v[174:177], v[206:209], v[20:23]
	v_mfma_f32_16x16x32_bf16 v[16:19], v[182:185], v[206:209], v[16:19]
	v_mfma_f32_16x16x32_bf16 v[16:19], v[178:181], v[202:205], v[16:19]
	v_mfma_f32_16x16x32_bf16 v[0:3], v[178:181], v[210:213], v[0:3]
	v_mfma_f32_16x16x32_bf16 v[0:3], v[182:185], v[214:217], v[0:3]
	v_mfma_f32_16x16x32_bf16 v[4:7], v[174:177], v[214:217], v[4:7]
	v_mfma_f32_16x16x32_bf16 v[4:7], v[170:173], v[210:213], v[4:7]
	s_setprio 0
	s_barrier
	s_movk_i32 s46, 0x100
	s_andn2_b64 vcc, exec, s[4:5]
	s_mov_b64 s[34:35], -1
	s_mov_b64 s[4:5], 0

; #define PG8_STAGE(bufoff, gbase, voff) do { _Pragma("unroll") for (int _i = 0; _i < 2; ++_i) \
;         __builtin_amdgcn_global_load_lds((const unsigned*)((const char*)(gbase) + (voff)[_i]), (LAS unsigned*)(lds + (bufoff) + ldsw + _i * 8192), 16, 0, 0); } while (0)
; #define PG8_LDA(dst, b, h) do { _Pragma("unroll") for (int m = 0; m < 4; ++m) _Pragma("unroll") for (int k = 0; k < 2; ++k) dst[m][k] = *(const LAS bf16x8*)(lds + PG8_SA(b, h) + aoff + m * 2048 + k * 1024); } while (0)
; #define PG8_LDB(dst, b, h) do { _Pragma("unroll") for (int n = 0; n < 2; ++n) _Pragma("unroll") for (int k = 0; k < 2; ++k) dst[n][k] = *(const LAS bf16x8*)(lds + PG8_SB(b, h) + boff + n * 2048 + k * 1024); } while (0)
; #define PG8_MMA(ai, bj, At, Bt) do { __builtin_amdgcn_s_setprio(1); _Pragma("unroll") for (int m = 0; m < 4; ++m) _Pragma("unroll") for (int n = 0; n < 2; ++n) _Pragma("unroll") for (int k = 0; k < 2; ++k) \
;         acc[ai][bj][m][n] = __builtin_amdgcn_mfma_f32_16x16x32_bf16(Bt[n][k], At[m][k], acc[ai][bj][m][n], 0, 0, 0); __builtin_amdgcn_s_setprio(0); } while (0)
; #define PG8_WAIT_V(n) asm volatile("s_waitcnt vmcnt(" #n ")" ::: "memory")
; #define PG8_WAIT_L(n) asm volatile("s_waitcnt lgkmcnt(" #n ")" ::: "memory")
; DI void gemm_phase(LAS unsigned char* lds, const Gemm g, const StaticOrder& S, const Epi& E) {
;     ...
;         const char* nA = has_next ? (const char*)g.A + (size_t)nxt.pm * tsA : cA; const char* nB = has_next ? (const char*)g.Bt + (size_t)nxt.pn * tsB : cB;
;         for (int t = 0; t < nt; t += 2) {
;             const bool last = (t == nt - 2);
;             const char* a1 = cA + (size_t)(t + 1) * kstep;
;             const char* a2 = last ? nA : cA + (size_t)(t + 2) * kstep; const char* b2 = last ? nB : cB + (size_t)(t + 2) * kstep;
;             const char* a3 = a2 + kstep; const char* b3 = b2 + kstep;
;             PG8_LDB(B0, 0, 0); PG8_LDB(B1, 0, 1); PG8_SCHED; PG8_LDA(At, 0, 0); PG8_STAGE(PG8_SA(1, 1), a1 + hsA, voffA);
;             PG8_WAIT_V(8); PG8_WAIT_L(0); PG8_BAR; PG8_MMA(0, 0, At, B0); PG8_MMA(0, 1, At, B1); PG8_BAR; PG8_SCHED;
;             PG8_LDA(At, 0, 1); PG8_STAGE(PG8_SB(0, 0), b2, voffB); PG8_STAGE(PG8_SB(0, 1), b2 + hsB, voffB); PG8_STAGE(PG8_SA(0, 0), a2, voffA);
;             PG8_WAIT_V(8); PG8_WAIT_L(0); PG8_BAR; PG8_MMA(1, 0, At, B0); PG8_MMA(1, 1, At, B1); PG8_BAR; PG8_SCHED;
.LBB0_570:
	s_ashr_i32 s27, s26, 31
	s_lshl_b64 s[28:29], s[26:27], 19
	s_add_u32 s28, s33, s28
	s_addc_u32 s29, s40, s29
	s_and_b64 s[46:47], s[30:31], exec
	s_cselect_b32 s76, s29, s55
	s_cselect_b32 s77, s28, s54
	s_add_u32 s78, s54, 0x100
	v_mov_b32_e32 v0, 0
	s_addc_u32 s79, s55, 0
	v_lshl_add_u64 v[146:147], s[54:55], 0, v[142:143]
	v_lshl_add_u64 v[148:149], s[54:55], 0, v[144:145]
	s_mov_b32 s80, -2
	s_mov_b64 s[54:55], 0
	ds_read_b128 v[156:159], v152
	ds_read_b128 v[160:163], v152 offset:1024
	ds_read_b128 v[170:173], v152 offset:2048
	ds_read_b128 v[174:177], v152 offset:3072
	ds_read_b128 v[178:181], v153
	ds_read_b128 v[182:185], v153 offset:1024
	ds_read_b128 v[186:189], v153 offset:2048
	ds_read_b128 v[190:193], v153 offset:3072
	s_add_u32 s56, s54, 0x100
	s_addc_u32 s57, s55, 0
	s_add_u32 s27, s78, s54
	s_addc_u32 s46, s79, s55
	s_cmp_eq_u32 s80, 28
	s_cselect_b32 s69, s76, s46
	s_cselect_b32 s46, 0, s56
	s_cselect_b32 s68, s77, s27
	s_cselect_b32 s27, 0, s57
	s_add_u32 s66, s6, s46
	s_addc_u32 s67, s7, s27
	s_mov_b32 m0, s74
	v_lshl_add_u64 v[164:165], v[146:147], 0, s[54:55]
	ds_read_b128 v[194:197], v154
	ds_read_b128 v[198:201], v154 offset:1024
	ds_read_b128 v[202:205], v154 offset:2048
	ds_read_b128 v[206:209], v154 offset:3072
	ds_read_b128 v[210:213], v154 offset:4096
	ds_read_b128 v[214:217], v154 offset:5120
	ds_read_b128 v[218:221], v154 offset:6144
	ds_read_b128 v[222:225], v154 offset:7168
	global_load_lds_dwordx4 v[164:165], off
	v_lshl_add_u64 v[164:165], v[148:149], 0, s[54:55]
	s_mov_b32 m0, s75
	s_nop 0
	global_load_lds_dwordx4 v[164:165], off
	s_waitcnt vmcnt(8)
	s_waitcnt lgkmcnt(0)
	s_barrier
	s_setprio 1
	s_waitcnt lgkmcnt(0)
	v_mfma_f32_16x16x32_bf16 v[124:127], v[156:159], v[194:197], 0
	v_mfma_f32_16x16x32_bf16 v[124:127], v[160:163], v[198:201], v[124:127]
	v_mfma_f32_16x16x32_bf16 v[120:123], v[174:177], v[198:201], 0
	v_mfma_f32_16x16x32_bf16 v[120:123], v[170:173], v[194:197], v[120:123]
	v_mfma_f32_16x16x32_bf16 v[104:107], v[170:173], v[202:205], 0
	v_mfma_f32_16x16x32_bf16 v[104:107], v[174:177], v[206:209], v[104:107]
	v_mfma_f32_16x16x32_bf16 v[108:111], v[160:163], v[206:209], 0
	v_mfma_f32_16x16x32_bf16 v[108:111], v[156:159], v[202:205], v[108:111]
	v_mfma_f32_16x16x32_bf16 v[92:95], v[156:159], v[210:213], 0
	v_mfma_f32_16x16x32_bf16 v[92:95], v[160:163], v[214:217], v[92:95]
	v_mfma_f32_16x16x32_bf16 v[88:91], v[174:177], v[214:217], 0
	v_mfma_f32_16x16x32_bf16 v[88:91], v[170:173], v[210:213], v[88:91]
	v_mfma_f32_16x16x32_bf16 v[72:75], v[170:173], v[218:221], 0
	v_mfma_f32_16x16x32_bf16 v[72:75], v[174:177], v[222:225], v[72:75]
	v_mfma_f32_16x16x32_bf16 v[76:79], v[160:163], v[222:225], 0
	v_mfma_f32_16x16x32_bf16 v[76:79], v[156:159], v[218:221], v[76:79]
	s_setprio 0
	s_setprio 1
	v_mfma_f32_16x16x32_bf16 v[116:119], v[178:181], v[194:197], 0
	v_mfma_f32_16x16x32_bf16 v[116:119], v[182:185], v[198:201], v[116:119]
	v_mfma_f32_16x16x32_bf16 v[112:115], v[190:193], v[198:201], 0
	v_mfma_f32_16x16x32_bf16 v[112:115], v[186:189], v[194:197], v[112:115]
	v_mfma_f32_16x16x32_bf16 v[96:99], v[186:189], v[202:205], 0
	v_mfma_f32_16x16x32_bf16 v[96:99], v[190:193], v[206:209], v[96:99]
	v_mfma_f32_16x16x32_bf16 v[100:103], v[182:185], v[206:209], 0
	v_mfma_f32_16x16x32_bf16 v[100:103], v[178:181], v[202:205], v[100:103]
	v_mfma_f32_16x16x32_bf16 v[84:87], v[178:181], v[210:213], 0
	v_mfma_f32_16x16x32_bf16 v[84:87], v[182:185], v[214:217], v[84:87]
	v_mfma_f32_16x16x32_bf16 v[80:83], v[190:193], v[214:217], 0
	v_mfma_f32_16x16x32_bf16 v[80:83], v[186:189], v[210:213], v[80:83]
	v_mfma_f32_16x16x32_bf16 v[64:67], v[186:189], v[218:221], 0
	v_mfma_f32_16x16x32_bf16 v[64:67], v[190:193], v[222:225], v[64:67]
	v_mfma_f32_16x16x32_bf16 v[68:71], v[182:185], v[222:225], 0
	v_mfma_f32_16x16x32_bf16 v[68:71], v[178:181], v[218:221], v[68:71]
	s_setprio 0
	s_barrier
	s_add_i32 s27, s13, s41
	v_lshl_add_u64 v[164:165], s[66:67], 0, v[130:131]
	s_mov_b32 m0, s27
	ds_read_b128 v[194:197], v154 offset:16384
	ds_read_b128 v[198:201], v154 offset:17408
	ds_read_b128 v[202:205], v154 offset:18432
	ds_read_b128 v[206:209], v154 offset:19456
	ds_read_b128 v[210:213], v154 offset:20480
	ds_read_b128 v[214:217], v154 offset:21504
	ds_read_b128 v[218:221], v154 offset:22528
	ds_read_b128 v[222:225], v154 offset:23552
	global_load_lds_dwordx4 v[164:165], off
	s_add_i32 m0, s27, 0x2000
	s_add_u32 s46, s66, 0x80000
	v_lshl_add_u64 v[226:227], s[66:67], 0, v[134:135]
	s_addc_u32 s47, s67, 0
	s_add_i32 s27, s73, s41
	global_load_lds_dwordx4 v[226:227], off
	v_lshl_add_u64 v[228:229], s[46:47], 0, v[130:131]
	s_mov_b32 m0, s27
	v_lshl_add_u64 v[230:231], s[68:69], 0, v[132:133]
	global_load_lds_dwordx4 v[228:229], off
	v_lshl_add_u64 v[228:229], s[46:47], 0, v[134:135]
	s_add_i32 m0, s27, 0x2000
	s_nop 0
	global_load_lds_dwordx4 v[228:229], off
	v_lshl_add_u64 v[228:229], s[68:69], 0, v[128:129]
	s_mov_b32 m0, s35
	s_nop 0
	global_load_lds_dwordx4 v[228:229], off
	s_mov_b32 m0, s42
	s_nop 0
	global_load_lds_dwordx4 v[230:231], off
	s_waitcnt vmcnt(8)
	s_waitcnt lgkmcnt(0)
	s_barrier
; #define PG8_STAGE(bufoff, gbase, voff) do { _Pragma("unroll") for (int _i = 0; _i < 2; ++_i) \
;         __builtin_amdgcn_global_load_lds((const unsigned*)((const char*)(gbase) + (voff)[_i]), (LAS unsigned*)(lds + (bufoff) + ldsw + _i * 8192), 16, 0, 0); } while (0)
; #define PG8_LDA(dst, b, h) do { _Pragma("unroll") for (int m = 0; m < 4; ++m) _Pragma("unroll") for (int k = 0; k < 2; ++k) dst[m][k] = *(const LAS bf16x8*)(lds + PG8_SA(b, h) + aoff + m * 2048 + k * 1024); } while (0)
; #define PG8_LDB(dst, b, h) do { _Pragma("unroll") for (int n = 0; n < 2; ++n) _Pragma("unroll") for (int k = 0; k < 2; ++k) dst[n][k] = *(const LAS bf16x8*)(lds + PG8_SB(b, h) + boff + n * 2048 + k * 1024); } while (0)
; #define PG8_MMA(ai, bj, At, Bt) do { __builtin_amdgcn_s_setprio(1); _Pragma("unroll") for (int m = 0; m < 4; ++m) _Pragma("unroll") for (int n = 0; n < 2; ++n) _Pragma("unroll") for (int k = 0; k < 2; ++k) \
;         acc[ai][bj][m][n] = __builtin_amdgcn_mfma_f32_16x16x32_bf16(Bt[n][k], At[m][k], acc[ai][bj][m][n], 0, 0, 0); __builtin_amdgcn_s_setprio(0); } while (0)
; #define PG8_WAIT_V(n) asm volatile("s_waitcnt vmcnt(" #n ")" ::: "memory")
; #define PG8_WAIT_L(n) asm volatile("s_waitcnt lgkmcnt(" #n ")" ::: "memory")
; #define PG8_BAR __builtin_amdgcn_s_barrier()
; #define PG8_SCHED __builtin_amdgcn_sched_barrier(0)
; DI void gemm_phase(LAS unsigned char* lds, const Gemm g, const StaticOrder& S, const Epi& E) {
;     ...
;             PG8_WAIT_V(8); PG8_WAIT_L(0); PG8_BAR; PG8_MMA(1, 0, At, B0); PG8_MMA(1, 1, At, B1); PG8_BAR; PG8_SCHED;
;             PG8_LDB(B0, 1, 0); PG8_LDB(B1, 1, 1); PG8_SCHED; PG8_LDA(At, 1, 0); PG8_STAGE(PG8_SA(0, 1), a2 + hsA, voffA);
;             PG8_WAIT_V(8); PG8_WAIT_L(0); PG8_BAR; PG8_MMA(0, 0, At, B0); PG8_MMA(0, 1, At, B1); PG8_BAR; PG8_SCHED;
	s_setprio 1
	s_waitcnt lgkmcnt(0)
	v_mfma_f32_16x16x32_bf16 v[60:63], v[156:159], v[194:197], 0
	v_mfma_f32_16x16x32_bf16 v[60:63], v[160:163], v[198:201], v[60:63]
	v_mfma_f32_16x16x32_bf16 v[56:59], v[174:177], v[198:201], 0
	v_mfma_f32_16x16x32_bf16 v[56:59], v[170:173], v[194:197], v[56:59]
	v_mfma_f32_16x16x32_bf16 v[40:43], v[170:173], v[202:205], 0
	v_mfma_f32_16x16x32_bf16 v[40:43], v[174:177], v[206:209], v[40:43]
	v_mfma_f32_16x16x32_bf16 v[44:47], v[160:163], v[206:209], 0
	v_mfma_f32_16x16x32_bf16 v[44:47], v[156:159], v[202:205], v[44:47]
	v_mfma_f32_16x16x32_bf16 v[28:31], v[156:159], v[210:213], 0
	v_mfma_f32_16x16x32_bf16 v[28:31], v[160:163], v[214:217], v[28:31]
	v_mfma_f32_16x16x32_bf16 v[24:27], v[174:177], v[214:217], 0
	v_mfma_f32_16x16x32_bf16 v[24:27], v[170:173], v[210:213], v[24:27]
	v_mfma_f32_16x16x32_bf16 v[8:11], v[170:173], v[218:221], 0
	v_mfma_f32_16x16x32_bf16 v[8:11], v[174:177], v[222:225], v[8:11]
	v_mfma_f32_16x16x32_bf16 v[12:15], v[160:163], v[222:225], 0
	v_mfma_f32_16x16x32_bf16 v[12:15], v[156:159], v[218:221], v[12:15]
	s_setprio 0
	s_setprio 1
	v_mfma_f32_16x16x32_bf16 v[52:55], v[178:181], v[194:197], 0
	v_mfma_f32_16x16x32_bf16 v[52:55], v[182:185], v[198:201], v[52:55]
	v_mfma_f32_16x16x32_bf16 v[48:51], v[190:193], v[198:201], 0
	v_mfma_f32_16x16x32_bf16 v[48:51], v[186:189], v[194:197], v[48:51]
	v_mfma_f32_16x16x32_bf16 v[32:35], v[186:189], v[202:205], 0
	v_mfma_f32_16x16x32_bf16 v[32:35], v[190:193], v[206:209], v[32:35]
	v_mfma_f32_16x16x32_bf16 v[36:39], v[182:185], v[206:209], 0
	v_mfma_f32_16x16x32_bf16 v[36:39], v[178:181], v[202:205], v[36:39]
	v_mfma_f32_16x16x32_bf16 v[20:23], v[178:181], v[210:213], 0
	v_mfma_f32_16x16x32_bf16 v[20:23], v[182:185], v[214:217], v[20:23]
	v_mfma_f32_16x16x32_bf16 v[16:19], v[190:193], v[214:217], 0
	v_mfma_f32_16x16x32_bf16 v[16:19], v[186:189], v[210:213], v[16:19]
	v_mfma_f32_16x16x32_bf16 v[0:3], v[186:189], v[218:221], 0
	v_mfma_f32_16x16x32_bf16 v[0:3], v[190:193], v[222:225], v[0:3]
	v_mfma_f32_16x16x32_bf16 v[4:7], v[182:185], v[222:225], 0
	v_mfma_f32_16x16x32_bf16 v[4:7], v[178:181], v[218:221], v[4:7]
	s_setprio 0
	s_barrier
	s_add_i32 s27, 0, 0x18000
	v_add_u32_e32 v155, s27, v151
	s_add_i32 s54, 0, 0x1c000
	ds_read_b128 v[156:159], v155
	ds_read_b128 v[160:163], v155 offset:1024
	ds_read_b128 v[170:173], v155 offset:2048
	ds_read_b128 v[174:177], v155 offset:3072
	v_add_u32_e32 v155, s54, v151
	ds_read_b128 v[178:181], v155
	ds_read_b128 v[182:185], v155 offset:1024
	ds_read_b128 v[186:189], v155 offset:2048
	ds_read_b128 v[190:193], v155 offset:3072
	s_add_u32 s46, s68, 0x40000
	s_addc_u32 s47, s69, 0
	s_mov_b32 m0, s43
	v_lshl_add_u64 v[232:233], s[46:47], 0, v[128:129]
	ds_read_b128 v[194:197], v154 offset:32768
	ds_read_b128 v[198:201], v154 offset:33792
	ds_read_b128 v[202:205], v154 offset:34816
	ds_read_b128 v[206:209], v154 offset:35840
	ds_read_b128 v[210:213], v154 offset:36864
	ds_read_b128 v[214:217], v154 offset:37888
	ds_read_b128 v[218:221], v154 offset:38912
	ds_read_b128 v[222:225], v154 offset:39936
	global_load_lds_dwordx4 v[232:233], off
	v_lshl_add_u64 v[232:233], s[46:47], 0, v[132:133]
	s_mov_b32 m0, s48
	s_nop 0
	global_load_lds_dwordx4 v[232:233], off
	s_waitcnt vmcnt(8)
	s_waitcnt lgkmcnt(0)
	s_barrier
	s_setprio 1
	s_waitcnt lgkmcnt(0)
	v_mfma_f32_16x16x32_bf16 v[124:127], v[156:159], v[194:197], v[124:127]
	v_mfma_f32_16x16x32_bf16 v[124:127], v[160:163], v[198:201], v[124:127]
	v_mfma_f32_16x16x32_bf16 v[120:123], v[174:177], v[198:201], v[120:123]
	v_mfma_f32_16x16x32_bf16 v[120:123], v[170:173], v[194:197], v[120:123]
	v_mfma_f32_16x16x32_bf16 v[104:107], v[170:173], v[202:205], v[104:107]
	v_mfma_f32_16x16x32_bf16 v[104:107], v[174:177], v[206:209], v[104:107]
	v_mfma_f32_16x16x32_bf16 v[108:111], v[160:163], v[206:209], v[108:111]
	v_mfma_f32_16x16x32_bf16 v[108:111], v[156:159], v[202:205], v[108:111]
	v_mfma_f32_16x16x32_bf16 v[92:95], v[156:159], v[210:213], v[92:95]
	v_mfma_f32_16x16x32_bf16 v[92:95], v[160:163], v[214:217], v[92:95]
	v_mfma_f32_16x16x32_bf16 v[88:91], v[174:177], v[214:217], v[88:91]
	v_mfma_f32_16x16x32_bf16 v[88:91], v[170:173], v[210:213], v[88:91]
	v_mfma_f32_16x16x32_bf16 v[72:75], v[170:173], v[218:221], v[72:75]
	v_mfma_f32_16x16x32_bf16 v[72:75], v[174:177], v[222:225], v[72:75]
	v_mfma_f32_16x16x32_bf16 v[76:79], v[160:163], v[222:225], v[76:79]
	v_mfma_f32_16x16x32_bf16 v[76:79], v[156:159], v[218:221], v[76:79]
	s_setprio 0
	s_setprio 1
	v_mfma_f32_16x16x32_bf16 v[116:119], v[178:181], v[194:197], v[116:119]
	v_mfma_f32_16x16x32_bf16 v[116:119], v[182:185], v[198:201], v[116:119]
	v_mfma_f32_16x16x32_bf16 v[112:115], v[190:193], v[198:201], v[112:115]
	v_mfma_f32_16x16x32_bf16 v[112:115], v[186:189], v[194:197], v[112:115]
	v_mfma_f32_16x16x32_bf16 v[96:99], v[186:189], v[202:205], v[96:99]
	v_mfma_f32_16x16x32_bf16 v[96:99], v[190:193], v[206:209], v[96:99]
	v_mfma_f32_16x16x32_bf16 v[100:103], v[182:185], v[206:209], v[100:103]
	v_mfma_f32_16x16x32_bf16 v[100:103], v[178:181], v[202:205], v[100:103]
	v_mfma_f32_16x16x32_bf16 v[84:87], v[178:181], v[210:213], v[84:87]
	v_mfma_f32_16x16x32_bf16 v[84:87], v[182:185], v[214:217], v[84:87]
	v_mfma_f32_16x16x32_bf16 v[80:83], v[190:193], v[214:217], v[80:83]
	v_mfma_f32_16x16x32_bf16 v[80:83], v[186:189], v[210:213], v[80:83]
	v_mfma_f32_16x16x32_bf16 v[64:67], v[186:189], v[218:221], v[64:67]
	v_mfma_f32_16x16x32_bf16 v[64:67], v[190:193], v[222:225], v[64:67]
	v_mfma_f32_16x16x32_bf16 v[68:71], v[182:185], v[222:225], v[68:71]
	v_mfma_f32_16x16x32_bf16 v[68:71], v[178:181], v[218:221], v[68:71]
	s_setprio 0
	s_barrier
; #define PG8_STAGE(bufoff, gbase, voff) do { _Pragma("unroll") for (int _i = 0; _i < 2; ++_i) \
;         __builtin_amdgcn_global_load_lds((const unsigned*)((const char*)(gbase) + (voff)[_i]), (LAS unsigned*)(lds + (bufoff) + ldsw + _i * 8192), 16, 0, 0); } while (0)
; #define PG8_LDA(dst, b, h) do { _Pragma("unroll") for (int m = 0; m < 4; ++m) _Pragma("unroll") for (int k = 0; k < 2; ++k) dst[m][k] = *(const LAS bf16x8*)(lds + PG8_SA(b, h) + aoff + m * 2048 + k * 1024); } while (0)
; #define PG8_MMA(ai, bj, At, Bt) do { __builtin_amdgcn_s_setprio(1); _Pragma("unroll") for (int m = 0; m < 4; ++m) _Pragma("unroll") for (int n = 0; n < 2; ++n) _Pragma("unroll") for (int k = 0; k < 2; ++k) \
;         acc[ai][bj][m][n] = __builtin_amdgcn_mfma_f32_16x16x32_bf16(Bt[n][k], At[m][k], acc[ai][bj][m][n], 0, 0, 0); __builtin_amdgcn_s_setprio(0); } while (0)
; #define PG8_WAIT_V(n) asm volatile("s_waitcnt vmcnt(" #n ")" ::: "memory")
; #define PG8_WAIT_L(n) asm volatile("s_waitcnt lgkmcnt(" #n ")" ::: "memory")
; #define PG8_BAR __builtin_amdgcn_s_barrier()
; #define PG8_SCHED __builtin_amdgcn_sched_barrier(0)
; DI void gemm_phase(LAS unsigned char* lds, const Gemm g, const StaticOrder& S, const Epi& E) {
;     ...
;             PG8_LDA(At, 1, 1); PG8_STAGE(PG8_SB(1, 0), b3, voffB); PG8_STAGE(PG8_SB(1, 1), b3 + hsB, voffB); PG8_STAGE(PG8_SA(1, 0), a3, voffA);
;             PG8_WAIT_V(8); PG8_WAIT_L(0); PG8_BAR; PG8_MMA(1, 0, At, B0); PG8_MMA(1, 1, At, B1); PG8_BAR; PG8_SCHED;
;         }
	s_add_i32 s46, s27, s41
	v_lshl_add_u64 v[164:165], v[164:165], 0, s[16:17]
	s_mov_b32 m0, s46
	ds_read_b128 v[194:197], v154 offset:49152
	ds_read_b128 v[198:201], v154 offset:50176
	ds_read_b128 v[202:205], v154 offset:51200
	ds_read_b128 v[206:209], v154 offset:52224
	ds_read_b128 v[210:213], v154 offset:53248
	ds_read_b128 v[214:217], v154 offset:54272
	ds_read_b128 v[218:221], v154 offset:55296
	ds_read_b128 v[222:225], v154 offset:56320
	global_load_lds_dwordx4 v[164:165], off
	s_add_i32 m0, s46, 0x2000
	s_add_u32 s46, s66, 0x80080
	v_lshl_add_u64 v[164:165], v[226:227], 0, s[16:17]
	s_addc_u32 s47, s67, 0
	s_add_i32 s54, s54, s41
	global_load_lds_dwordx4 v[164:165], off
	v_lshl_add_u64 v[164:165], s[46:47], 0, v[130:131]
	s_mov_b32 m0, s54
	s_nop 0
	global_load_lds_dwordx4 v[164:165], off
	v_lshl_add_u64 v[164:165], s[46:47], 0, v[134:135]
	s_add_i32 m0, s54, 0x2000
	s_nop 0
	global_load_lds_dwordx4 v[164:165], off
	v_lshl_add_u64 v[164:165], v[228:229], 0, s[16:17]
	s_mov_b32 m0, s71
	s_nop 0
	global_load_lds_dwordx4 v[164:165], off
	v_lshl_add_u64 v[164:165], v[230:231], 0, s[16:17]
	s_mov_b32 m0, s72
	s_nop 0
	global_load_lds_dwordx4 v[164:165], off
	s_waitcnt vmcnt(8)
	s_waitcnt lgkmcnt(0)
	s_barrier
	s_setprio 1
	s_waitcnt lgkmcnt(0)
	v_mfma_f32_16x16x32_bf16 v[60:63], v[156:159], v[194:197], v[60:63]
	v_mfma_f32_16x16x32_bf16 v[60:63], v[160:163], v[198:201], v[60:63]
	v_mfma_f32_16x16x32_bf16 v[56:59], v[174:177], v[198:201], v[56:59]
	v_mfma_f32_16x16x32_bf16 v[56:59], v[170:173], v[194:197], v[56:59]
	v_mfma_f32_16x16x32_bf16 v[40:43], v[170:173], v[202:205], v[40:43]
	v_mfma_f32_16x16x32_bf16 v[40:43], v[174:177], v[206:209], v[40:43]
	v_mfma_f32_16x16x32_bf16 v[44:47], v[160:163], v[206:209], v[44:47]
	v_mfma_f32_16x16x32_bf16 v[44:47], v[156:159], v[202:205], v[44:47]
	v_mfma_f32_16x16x32_bf16 v[28:31], v[156:159], v[210:213], v[28:31]
	v_mfma_f32_16x16x32_bf16 v[28:31], v[160:163], v[214:217], v[28:31]
	v_mfma_f32_16x16x32_bf16 v[24:27], v[174:177], v[214:217], v[24:27]
	v_mfma_f32_16x16x32_bf16 v[24:27], v[170:173], v[210:213], v[24:27]
	v_mfma_f32_16x16x32_bf16 v[8:11], v[170:173], v[218:221], v[8:11]
	v_mfma_f32_16x16x32_bf16 v[8:11], v[174:177], v[222:225], v[8:11]
	v_mfma_f32_16x16x32_bf16 v[12:15], v[160:163], v[222:225], v[12:15]
	v_mfma_f32_16x16x32_bf16 v[12:15], v[156:159], v[218:221], v[12:15]
	s_setprio 0
	s_setprio 1
	v_mfma_f32_16x16x32_bf16 v[52:55], v[178:181], v[194:197], v[52:55]
	v_mfma_f32_16x16x32_bf16 v[52:55], v[182:185], v[198:201], v[52:55]
	v_mfma_f32_16x16x32_bf16 v[48:51], v[190:193], v[198:201], v[48:51]
	v_mfma_f32_16x16x32_bf16 v[48:51], v[186:189], v[194:197], v[48:51]
	v_mfma_f32_16x16x32_bf16 v[32:35], v[186:189], v[202:205], v[32:35]
	v_mfma_f32_16x16x32_bf16 v[32:35], v[190:193], v[206:209], v[32:35]
	v_mfma_f32_16x16x32_bf16 v[36:39], v[182:185], v[206:209], v[36:39]
	v_mfma_f32_16x16x32_bf16 v[36:39], v[178:181], v[202:205], v[36:39]
	v_mfma_f32_16x16x32_bf16 v[20:23], v[178:181], v[210:213], v[20:23]
	v_mfma_f32_16x16x32_bf16 v[20:23], v[182:185], v[214:217], v[20:23]
	v_mfma_f32_16x16x32_bf16 v[16:19], v[190:193], v[214:217], v[16:19]
	v_mfma_f32_16x16x32_bf16 v[16:19], v[186:189], v[210:213], v[16:19]
	v_mfma_f32_16x16x32_bf16 v[0:3], v[186:189], v[218:221], v[0:3]
	v_mfma_f32_16x16x32_bf16 v[0:3], v[190:193], v[222:225], v[0:3]
	v_mfma_f32_16x16x32_bf16 v[4:7], v[182:185], v[222:225], v[4:7]
	v_mfma_f32_16x16x32_bf16 v[4:7], v[178:181], v[218:221], v[4:7]
	s_setprio 0
	s_barrier
	s_add_i32 s80, s80, 2
	s_cmp_gt_u32 s80, 29
	s_mov_b64 s[54:55], s[56:57]

; #define PG8_STAGE(bufoff, gbase, voff) do { _Pragma("unroll") for (int _i = 0; _i < 2; ++_i) \
;         __builtin_amdgcn_global_load_lds((const unsigned*)((const char*)(gbase) + (voff)[_i]), (LAS unsigned*)(lds + (bufoff) + ldsw + _i * 8192), 16, 0, 0); } while (0)
; #define PG8_LDA(dst, b, h) do { _Pragma("unroll") for (int m = 0; m < 4; ++m) _Pragma("unroll") for (int k = 0; k < 2; ++k) dst[m][k] = *(const LAS bf16x8*)(lds + PG8_SA(b, h) + aoff + m * 2048 + k * 1024); } while (0)
; #define PG8_LDB(dst, b, h) do { _Pragma("unroll") for (int n = 0; n < 2; ++n) _Pragma("unroll") for (int k = 0; k < 2; ++k) dst[n][k] = *(const LAS bf16x8*)(lds + PG8_SB(b, h) + boff + n * 2048 + k * 1024); } while (0)
; #define PG8_MMA(ai, bj, At, Bt) do { __builtin_amdgcn_s_setprio(1); _Pragma("unroll") for (int m = 0; m < 4; ++m) _Pragma("unroll") for (int n = 0; n < 2; ++n) _Pragma("unroll") for (int k = 0; k < 2; ++k) \
;         acc[ai][bj][m][n] = __builtin_amdgcn_mfma_f32_16x16x32_bf16(Bt[n][k], At[m][k], acc[ai][bj][m][n], 0, 0, 0); __builtin_amdgcn_s_setprio(0); } while (0)
; #define PG8_WAIT_V(n) asm volatile("s_waitcnt vmcnt(" #n ")" ::: "memory")
; #define PG8_WAIT_L(n) asm volatile("s_waitcnt lgkmcnt(" #n ")" ::: "memory")
; DI void gemm_phase(LAS unsigned char* lds, const Gemm g, const StaticOrder& S, const Epi& E) {
;     ...
;         const char* nA = has_next ? (const char*)g.A + (size_t)nxt.pm * tsA : cA; const char* nB = has_next ? (const char*)g.Bt + (size_t)nxt.pn * tsB : cB;
;         for (int t = 0; t < nt; t += 2) {
;             const bool last = (t == nt - 2);
;             const char* a1 = cA + (size_t)(t + 1) * kstep;
;             const char* a2 = last ? nA : cA + (size_t)(t + 2) * kstep; const char* b2 = last ? nB : cB + (size_t)(t + 2) * kstep;
;             const char* a3 = a2 + kstep; const char* b3 = b2 + kstep;
;             PG8_LDB(B0, 0, 0); PG8_LDB(B1, 0, 1); PG8_SCHED; PG8_LDA(At, 0, 0); PG8_STAGE(PG8_SA(1, 1), a1 + hsA, voffA);
;             PG8_WAIT_V(8); PG8_WAIT_L(0); PG8_BAR; PG8_MMA(0, 0, At, B0); PG8_MMA(0, 1, At, B1); PG8_BAR; PG8_SCHED;
;             PG8_LDA(At, 0, 1); PG8_STAGE(PG8_SB(0, 0), b2, voffB); PG8_STAGE(PG8_SB(0, 1), b2 + hsB, voffB); PG8_STAGE(PG8_SA(0, 0), a2, voffA);
;             PG8_WAIT_V(8); PG8_WAIT_L(0); PG8_BAR; PG8_MMA(1, 0, At, B0); PG8_MMA(1, 1, At, B1); PG8_BAR; PG8_SCHED;
.LBB0_935:
	s_ashr_i32 s21, s20, 31
	s_lshl_b64 s[22:23], s[20:21], 20
	s_add_u32 s22, s53, s22
	s_addc_u32 s23, s54, s23
	s_and_b64 s[24:25], s[6:7], exec
	s_cselect_b32 s21, s23, s31
	s_cselect_b32 s27, s22, s30
	s_ashr_i32 s19, s18, 31
	s_lshl_b64 s[24:25], s[18:19], 20
	s_add_u32 s24, s0, s24
	s_addc_u32 s25, s1, s25
	s_and_b64 s[36:37], s[6:7], exec
	s_cselect_b32 s19, s25, s35
	s_cselect_b32 s48, s24, s34
	s_add_u32 s30, s30, 0x80080
	s_addc_u32 s31, s31, 0
	s_add_u32 s49, s34, 0x100
	v_mov_b32_e32 v0, 0
	s_addc_u32 s50, s35, 0
	s_mov_b32 s51, -2
	s_waitcnt lgkmcnt(0)
	ds_read_b128 v[144:147], v155
	ds_read_b128 v[148:151], v155 offset:1024
	ds_read_b128 v[160:163], v155 offset:2048
	ds_read_b128 v[170:173], v155 offset:3072
	ds_read_b128 v[174:177], v156
	ds_read_b128 v[178:181], v156 offset:1024
	ds_read_b128 v[182:185], v156 offset:2048
	ds_read_b128 v[186:189], v156 offset:3072
	s_add_u32 s34, s30, 0xfff80080
	s_addc_u32 s35, s31, -1
	s_cmp_eq_u32 s51, 28
	s_cselect_b32 s37, s21, s35
	s_cselect_b32 s36, s27, s34
	s_cselect_b32 s35, s19, s50
	s_cselect_b32 s34, s48, s49
	s_add_i32 m0, s13, 0xc000
	ds_read_b128 v[190:193], v157
	ds_read_b128 v[194:197], v157 offset:1024
	ds_read_b128 v[198:201], v157 offset:2048
	ds_read_b128 v[202:205], v157 offset:3072
	ds_read_b128 v[206:209], v157 offset:4096
	ds_read_b128 v[210:213], v157 offset:5120
	ds_read_b128 v[214:217], v157 offset:6144
	ds_read_b128 v[218:221], v157 offset:7168
	global_load_lds_dwordx4 v136, s[30:31]
	s_add_i32 m0, s13, 0xe000
	s_nop 0
	global_load_lds_dwordx4 v138, s[30:31]
	s_waitcnt vmcnt(8)
	s_waitcnt lgkmcnt(0)
	s_barrier
	s_setprio 1
	s_waitcnt lgkmcnt(0)
	v_mfma_f32_16x16x32_bf16 v[124:127], v[144:147], v[190:193], 0
	v_mfma_f32_16x16x32_bf16 v[124:127], v[148:151], v[194:197], v[124:127]
	v_mfma_f32_16x16x32_bf16 v[120:123], v[170:173], v[194:197], 0
	v_mfma_f32_16x16x32_bf16 v[120:123], v[160:163], v[190:193], v[120:123]
	v_mfma_f32_16x16x32_bf16 v[104:107], v[160:163], v[198:201], 0
	v_mfma_f32_16x16x32_bf16 v[104:107], v[170:173], v[202:205], v[104:107]
	v_mfma_f32_16x16x32_bf16 v[108:111], v[148:151], v[202:205], 0
	v_mfma_f32_16x16x32_bf16 v[108:111], v[144:147], v[198:201], v[108:111]
	v_mfma_f32_16x16x32_bf16 v[92:95], v[144:147], v[206:209], 0
	v_mfma_f32_16x16x32_bf16 v[92:95], v[148:151], v[210:213], v[92:95]
	v_mfma_f32_16x16x32_bf16 v[88:91], v[170:173], v[210:213], 0
	v_mfma_f32_16x16x32_bf16 v[88:91], v[160:163], v[206:209], v[88:91]
	v_mfma_f32_16x16x32_bf16 v[72:75], v[160:163], v[214:217], 0
	v_mfma_f32_16x16x32_bf16 v[72:75], v[170:173], v[218:221], v[72:75]
	v_mfma_f32_16x16x32_bf16 v[76:79], v[148:151], v[218:221], 0
	v_mfma_f32_16x16x32_bf16 v[76:79], v[144:147], v[214:217], v[76:79]
	s_setprio 0
	s_setprio 1
	v_mfma_f32_16x16x32_bf16 v[116:119], v[174:177], v[190:193], 0
	v_mfma_f32_16x16x32_bf16 v[116:119], v[178:181], v[194:197], v[116:119]
	v_mfma_f32_16x16x32_bf16 v[112:115], v[186:189], v[194:197], 0
	v_mfma_f32_16x16x32_bf16 v[112:115], v[182:185], v[190:193], v[112:115]
	v_mfma_f32_16x16x32_bf16 v[96:99], v[182:185], v[198:201], 0
	v_mfma_f32_16x16x32_bf16 v[96:99], v[186:189], v[202:205], v[96:99]
	v_mfma_f32_16x16x32_bf16 v[100:103], v[178:181], v[202:205], 0
	v_mfma_f32_16x16x32_bf16 v[100:103], v[174:177], v[198:201], v[100:103]
	v_mfma_f32_16x16x32_bf16 v[84:87], v[174:177], v[206:209], 0
	v_mfma_f32_16x16x32_bf16 v[84:87], v[178:181], v[210:213], v[84:87]
	v_mfma_f32_16x16x32_bf16 v[80:83], v[186:189], v[210:213], 0
	v_mfma_f32_16x16x32_bf16 v[80:83], v[182:185], v[206:209], v[80:83]
	v_mfma_f32_16x16x32_bf16 v[64:67], v[182:185], v[214:217], 0
	v_mfma_f32_16x16x32_bf16 v[64:67], v[186:189], v[218:221], v[64:67]
	v_mfma_f32_16x16x32_bf16 v[68:71], v[178:181], v[218:221], 0
	v_mfma_f32_16x16x32_bf16 v[68:71], v[174:177], v[214:217], v[68:71]
	s_setprio 0
	s_barrier
	s_add_i32 s46, s42, s12
	s_add_u32 s98, s34, 0x80
	s_addc_u32 s99, s35, 0
	s_mov_b32 m0, s46
	ds_read_b128 v[190:193], v157 offset:16384
	ds_read_b128 v[194:197], v157 offset:17408
	ds_read_b128 v[198:201], v157 offset:18432
	ds_read_b128 v[202:205], v157 offset:19456
	ds_read_b128 v[206:209], v157 offset:20480
	ds_read_b128 v[210:213], v157 offset:21504
	ds_read_b128 v[214:217], v157 offset:22528
	ds_read_b128 v[218:221], v157 offset:23552
	global_load_lds_dwordx4 v130, s[34:35]
	s_add_i32 m0, s46, 0x2000
	s_add_u32 s46, s34, 0x80000
	s_addc_u32 s47, s35, 0
	s_add_i32 s52, s43, s12
	global_load_lds_dwordx4 v134, s[34:35]
	s_mov_b32 m0, s52
	s_nop 0
	global_load_lds_dwordx4 v130, s[46:47]
	s_add_i32 m0, s52, 0x2000
	s_nop 0
	global_load_lds_dwordx4 v134, s[46:47]
	s_add_u32 s100, s36, 0x80
	s_addc_u32 s101, s37, 0
	s_mov_b32 m0, s13
	s_nop 0
	global_load_lds_dwordx4 v128, s[36:37]
	s_mov_b32 m0, s29
	s_nop 0
	global_load_lds_dwordx4 v132, s[36:37]
	s_waitcnt vmcnt(8)
	s_waitcnt lgkmcnt(0)
	s_barrier
; #define PG8_STAGE(bufoff, gbase, voff) do { _Pragma("unroll") for (int _i = 0; _i < 2; ++_i) \
;         __builtin_amdgcn_global_load_lds((const unsigned*)((const char*)(gbase) + (voff)[_i]), (LAS unsigned*)(lds + (bufoff) + ldsw + _i * 8192), 16, 0, 0); } while (0)
; #define PG8_LDA(dst, b, h) do { _Pragma("unroll") for (int m = 0; m < 4; ++m) _Pragma("unroll") for (int k = 0; k < 2; ++k) dst[m][k] = *(const LAS bf16x8*)(lds + PG8_SA(b, h) + aoff + m * 2048 + k * 1024); } while (0)
; #define PG8_LDB(dst, b, h) do { _Pragma("unroll") for (int n = 0; n < 2; ++n) _Pragma("unroll") for (int k = 0; k < 2; ++k) dst[n][k] = *(const LAS bf16x8*)(lds + PG8_SB(b, h) + boff + n * 2048 + k * 1024); } while (0)
; #define PG8_MMA(ai, bj, At, Bt) do { __builtin_amdgcn_s_setprio(1); _Pragma("unroll") for (int m = 0; m < 4; ++m) _Pragma("unroll") for (int n = 0; n < 2; ++n) _Pragma("unroll") for (int k = 0; k < 2; ++k) \
;         acc[ai][bj][m][n] = __builtin_amdgcn_mfma_f32_16x16x32_bf16(Bt[n][k], At[m][k], acc[ai][bj][m][n], 0, 0, 0); __builtin_amdgcn_s_setprio(0); } while (0)
; #define PG8_WAIT_V(n) asm volatile("s_waitcnt vmcnt(" #n ")" ::: "memory")
; #define PG8_WAIT_L(n) asm volatile("s_waitcnt lgkmcnt(" #n ")" ::: "memory")
; #define PG8_BAR __builtin_amdgcn_s_barrier()
; #define PG8_SCHED __builtin_amdgcn_sched_barrier(0)
; DI void gemm_phase(LAS unsigned char* lds, const Gemm g, const StaticOrder& S, const Epi& E) {
;     ...
;             PG8_WAIT_V(8); PG8_WAIT_L(0); PG8_BAR; PG8_MMA(1, 0, At, B0); PG8_MMA(1, 1, At, B1); PG8_BAR; PG8_SCHED;
;             PG8_LDB(B0, 1, 0); PG8_LDB(B1, 1, 1); PG8_SCHED; PG8_LDA(At, 1, 0); PG8_STAGE(PG8_SA(0, 1), a2 + hsA, voffA);
;             PG8_WAIT_V(8); PG8_WAIT_L(0); PG8_BAR; PG8_MMA(0, 0, At, B0); PG8_MMA(0, 1, At, B1); PG8_BAR; PG8_SCHED;
	s_setprio 1
	s_waitcnt lgkmcnt(0)
	v_mfma_f32_16x16x32_bf16 v[60:63], v[144:147], v[190:193], 0
	v_mfma_f32_16x16x32_bf16 v[60:63], v[148:151], v[194:197], v[60:63]
	v_mfma_f32_16x16x32_bf16 v[56:59], v[170:173], v[194:197], 0
	v_mfma_f32_16x16x32_bf16 v[56:59], v[160:163], v[190:193], v[56:59]
	v_mfma_f32_16x16x32_bf16 v[40:43], v[160:163], v[198:201], 0
	v_mfma_f32_16x16x32_bf16 v[40:43], v[170:173], v[202:205], v[40:43]
	v_mfma_f32_16x16x32_bf16 v[44:47], v[148:151], v[202:205], 0
	v_mfma_f32_16x16x32_bf16 v[44:47], v[144:147], v[198:201], v[44:47]
	v_mfma_f32_16x16x32_bf16 v[28:31], v[144:147], v[206:209], 0
	v_mfma_f32_16x16x32_bf16 v[28:31], v[148:151], v[210:213], v[28:31]
	v_mfma_f32_16x16x32_bf16 v[24:27], v[170:173], v[210:213], 0
	v_mfma_f32_16x16x32_bf16 v[24:27], v[160:163], v[206:209], v[24:27]
	v_mfma_f32_16x16x32_bf16 v[8:11], v[160:163], v[214:217], 0
	v_mfma_f32_16x16x32_bf16 v[8:11], v[170:173], v[218:221], v[8:11]
	v_mfma_f32_16x16x32_bf16 v[12:15], v[148:151], v[218:221], 0
	v_mfma_f32_16x16x32_bf16 v[12:15], v[144:147], v[214:217], v[12:15]
	s_setprio 0
	s_setprio 1
	v_mfma_f32_16x16x32_bf16 v[52:55], v[174:177], v[190:193], 0
	v_mfma_f32_16x16x32_bf16 v[52:55], v[178:181], v[194:197], v[52:55]
	v_mfma_f32_16x16x32_bf16 v[48:51], v[186:189], v[194:197], 0
	v_mfma_f32_16x16x32_bf16 v[48:51], v[182:185], v[190:193], v[48:51]
	v_mfma_f32_16x16x32_bf16 v[32:35], v[182:185], v[198:201], 0
	v_mfma_f32_16x16x32_bf16 v[32:35], v[186:189], v[202:205], v[32:35]
	v_mfma_f32_16x16x32_bf16 v[36:39], v[178:181], v[202:205], 0
	v_mfma_f32_16x16x32_bf16 v[36:39], v[174:177], v[198:201], v[36:39]
	v_mfma_f32_16x16x32_bf16 v[20:23], v[174:177], v[206:209], 0
	v_mfma_f32_16x16x32_bf16 v[20:23], v[178:181], v[210:213], v[20:23]
	v_mfma_f32_16x16x32_bf16 v[16:19], v[186:189], v[210:213], 0
	v_mfma_f32_16x16x32_bf16 v[16:19], v[182:185], v[206:209], v[16:19]
	v_mfma_f32_16x16x32_bf16 v[0:3], v[182:185], v[214:217], 0
	v_mfma_f32_16x16x32_bf16 v[0:3], v[186:189], v[218:221], v[0:3]
	v_mfma_f32_16x16x32_bf16 v[4:7], v[178:181], v[218:221], 0
	v_mfma_f32_16x16x32_bf16 v[4:7], v[174:177], v[214:217], v[4:7]
	s_setprio 0
	s_barrier
	s_add_i32 s46, 0, 0x18000
	v_add_u32_e32 v159, s46, v153
	s_add_i32 s47, 0, 0x1c000
	ds_read_b128 v[144:147], v159
	ds_read_b128 v[148:151], v159 offset:1024
	ds_read_b128 v[160:163], v159 offset:2048
	ds_read_b128 v[170:173], v159 offset:3072
	v_add_u32_e32 v159, s47, v153
	ds_read_b128 v[174:177], v159
	ds_read_b128 v[178:181], v159 offset:1024
	ds_read_b128 v[182:185], v159 offset:2048
	ds_read_b128 v[186:189], v159 offset:3072
	s_add_u32 s36, s36, 0x80000
	s_addc_u32 s37, s37, 0
	s_mov_b32 m0, s33
	ds_read_b128 v[190:193], v157 offset:32768
	ds_read_b128 v[194:197], v157 offset:33792
	ds_read_b128 v[198:201], v157 offset:34816
	ds_read_b128 v[202:205], v157 offset:35840
	ds_read_b128 v[206:209], v157 offset:36864
	ds_read_b128 v[210:213], v157 offset:37888
	ds_read_b128 v[214:217], v157 offset:38912
	ds_read_b128 v[218:221], v157 offset:39936
	global_load_lds_dwordx4 v128, s[36:37]
	s_mov_b32 m0, s38
	s_nop 0
	global_load_lds_dwordx4 v132, s[36:37]
	s_waitcnt vmcnt(8)
	s_waitcnt lgkmcnt(0)
	s_barrier
	s_setprio 1
	s_waitcnt lgkmcnt(0)
	v_mfma_f32_16x16x32_bf16 v[124:127], v[144:147], v[190:193], v[124:127]
	v_mfma_f32_16x16x32_bf16 v[124:127], v[148:151], v[194:197], v[124:127]
	v_mfma_f32_16x16x32_bf16 v[120:123], v[170:173], v[194:197], v[120:123]
	v_mfma_f32_16x16x32_bf16 v[120:123], v[160:163], v[190:193], v[120:123]
	v_mfma_f32_16x16x32_bf16 v[104:107], v[160:163], v[198:201], v[104:107]
	v_mfma_f32_16x16x32_bf16 v[104:107], v[170:173], v[202:205], v[104:107]
	v_mfma_f32_16x16x32_bf16 v[108:111], v[148:151], v[202:205], v[108:111]
	v_mfma_f32_16x16x32_bf16 v[108:111], v[144:147], v[198:201], v[108:111]
	v_mfma_f32_16x16x32_bf16 v[92:95], v[144:147], v[206:209], v[92:95]
	v_mfma_f32_16x16x32_bf16 v[92:95], v[148:151], v[210:213], v[92:95]
	v_mfma_f32_16x16x32_bf16 v[88:91], v[170:173], v[210:213], v[88:91]
	v_mfma_f32_16x16x32_bf16 v[88:91], v[160:163], v[206:209], v[88:91]
	v_mfma_f32_16x16x32_bf16 v[72:75], v[160:163], v[214:217], v[72:75]
	v_mfma_f32_16x16x32_bf16 v[72:75], v[170:173], v[218:221], v[72:75]
	v_mfma_f32_16x16x32_bf16 v[76:79], v[148:151], v[218:221], v[76:79]
	v_mfma_f32_16x16x32_bf16 v[76:79], v[144:147], v[214:217], v[76:79]
	s_setprio 0
	s_setprio 1
	v_mfma_f32_16x16x32_bf16 v[116:119], v[174:177], v[190:193], v[116:119]
	v_mfma_f32_16x16x32_bf16 v[116:119], v[178:181], v[194:197], v[116:119]
	v_mfma_f32_16x16x32_bf16 v[112:115], v[186:189], v[194:197], v[112:115]
	v_mfma_f32_16x16x32_bf16 v[112:115], v[182:185], v[190:193], v[112:115]
	v_mfma_f32_16x16x32_bf16 v[96:99], v[182:185], v[198:201], v[96:99]
	v_mfma_f32_16x16x32_bf16 v[96:99], v[186:189], v[202:205], v[96:99]
	v_mfma_f32_16x16x32_bf16 v[100:103], v[178:181], v[202:205], v[100:103]
	v_mfma_f32_16x16x32_bf16 v[100:103], v[174:177], v[198:201], v[100:103]
	v_mfma_f32_16x16x32_bf16 v[84:87], v[174:177], v[206:209], v[84:87]
	v_mfma_f32_16x16x32_bf16 v[84:87], v[178:181], v[210:213], v[84:87]
	v_mfma_f32_16x16x32_bf16 v[80:83], v[186:189], v[210:213], v[80:83]
	v_mfma_f32_16x16x32_bf16 v[80:83], v[182:185], v[206:209], v[80:83]
	v_mfma_f32_16x16x32_bf16 v[64:67], v[182:185], v[214:217], v[64:67]
	v_mfma_f32_16x16x32_bf16 v[64:67], v[186:189], v[218:221], v[64:67]
	v_mfma_f32_16x16x32_bf16 v[68:71], v[178:181], v[218:221], v[68:71]
	v_mfma_f32_16x16x32_bf16 v[68:71], v[174:177], v[214:217], v[68:71]
	s_setprio 0
	s_barrier
; #define PG8_STAGE(bufoff, gbase, voff) do { _Pragma("unroll") for (int _i = 0; _i < 2; ++_i) \
;         __builtin_amdgcn_global_load_lds((const unsigned*)((const char*)(gbase) + (voff)[_i]), (LAS unsigned*)(lds + (bufoff) + ldsw + _i * 8192), 16, 0, 0); } while (0)
; #define PG8_LDA(dst, b, h) do { _Pragma("unroll") for (int m = 0; m < 4; ++m) _Pragma("unroll") for (int k = 0; k < 2; ++k) dst[m][k] = *(const LAS bf16x8*)(lds + PG8_SA(b, h) + aoff + m * 2048 + k * 1024); } while (0)
; #define PG8_MMA(ai, bj, At, Bt) do { __builtin_amdgcn_s_setprio(1); _Pragma("unroll") for (int m = 0; m < 4; ++m) _Pragma("unroll") for (int n = 0; n < 2; ++n) _Pragma("unroll") for (int k = 0; k < 2; ++k) \
;         acc[ai][bj][m][n] = __builtin_amdgcn_mfma_f32_16x16x32_bf16(Bt[n][k], At[m][k], acc[ai][bj][m][n], 0, 0, 0); __builtin_amdgcn_s_setprio(0); } while (0)
; #define PG8_WAIT_V(n) asm volatile("s_waitcnt vmcnt(" #n ")" ::: "memory")
; #define PG8_WAIT_L(n) asm volatile("s_waitcnt lgkmcnt(" #n ")" ::: "memory")
; #define PG8_BAR __builtin_amdgcn_s_barrier()
; #define PG8_SCHED __builtin_amdgcn_sched_barrier(0)
; DI void gemm_phase(LAS unsigned char* lds, const Gemm g, const StaticOrder& S, const Epi& E) {
;     ...
;             PG8_LDA(At, 1, 1); PG8_STAGE(PG8_SB(1, 0), b3, voffB); PG8_STAGE(PG8_SB(1, 1), b3 + hsB, voffB); PG8_STAGE(PG8_SA(1, 0), a3, voffA);
;             PG8_WAIT_V(8); PG8_WAIT_L(0); PG8_BAR; PG8_MMA(1, 0, At, B0); PG8_MMA(1, 1, At, B1); PG8_BAR; PG8_SCHED;
;         }
	s_add_i32 s36, s46, s12
	s_mov_b32 m0, s36
	ds_read_b128 v[190:193], v157 offset:49152
	ds_read_b128 v[194:197], v157 offset:50176
	ds_read_b128 v[198:201], v157 offset:51200
	ds_read_b128 v[202:205], v157 offset:52224
	ds_read_b128 v[206:209], v157 offset:53248
	ds_read_b128 v[210:213], v157 offset:54272
	ds_read_b128 v[214:217], v157 offset:55296
	ds_read_b128 v[218:221], v157 offset:56320
	global_load_lds_dwordx4 v130, s[98:99]
	s_add_i32 m0, s36, 0x2000
	s_add_u32 s34, s34, 0x80080
	s_addc_u32 s35, s35, 0
	s_add_i32 s36, s47, s12
	global_load_lds_dwordx4 v134, s[98:99]
	s_mov_b32 m0, s36
	s_nop 0
	global_load_lds_dwordx4 v130, s[34:35]
	s_add_i32 m0, s36, 0x2000
	s_nop 0
	global_load_lds_dwordx4 v134, s[34:35]
	s_mov_b32 m0, s40
	s_nop 0
	global_load_lds_dwordx4 v128, s[100:101]
	s_mov_b32 m0, s41
	s_nop 0
	global_load_lds_dwordx4 v132, s[100:101]
	s_waitcnt vmcnt(8)
	s_waitcnt lgkmcnt(0)
	s_barrier
	s_setprio 1
	s_waitcnt lgkmcnt(0)
	v_mfma_f32_16x16x32_bf16 v[60:63], v[144:147], v[190:193], v[60:63]
	v_mfma_f32_16x16x32_bf16 v[60:63], v[148:151], v[194:197], v[60:63]
	v_mfma_f32_16x16x32_bf16 v[56:59], v[170:173], v[194:197], v[56:59]
	v_mfma_f32_16x16x32_bf16 v[56:59], v[160:163], v[190:193], v[56:59]
	v_mfma_f32_16x16x32_bf16 v[40:43], v[160:163], v[198:201], v[40:43]
	v_mfma_f32_16x16x32_bf16 v[40:43], v[170:173], v[202:205], v[40:43]
	v_mfma_f32_16x16x32_bf16 v[44:47], v[148:151], v[202:205], v[44:47]
	v_mfma_f32_16x16x32_bf16 v[44:47], v[144:147], v[198:201], v[44:47]
	v_mfma_f32_16x16x32_bf16 v[28:31], v[144:147], v[206:209], v[28:31]
	v_mfma_f32_16x16x32_bf16 v[28:31], v[148:151], v[210:213], v[28:31]
	v_mfma_f32_16x16x32_bf16 v[24:27], v[170:173], v[210:213], v[24:27]
	v_mfma_f32_16x16x32_bf16 v[24:27], v[160:163], v[206:209], v[24:27]
	v_mfma_f32_16x16x32_bf16 v[8:11], v[160:163], v[214:217], v[8:11]
	v_mfma_f32_16x16x32_bf16 v[8:11], v[170:173], v[218:221], v[8:11]
	v_mfma_f32_16x16x32_bf16 v[12:15], v[148:151], v[218:221], v[12:15]
	v_mfma_f32_16x16x32_bf16 v[12:15], v[144:147], v[214:217], v[12:15]
	s_setprio 0
	s_setprio 1
	v_mfma_f32_16x16x32_bf16 v[52:55], v[174:177], v[190:193], v[52:55]
	v_mfma_f32_16x16x32_bf16 v[52:55], v[178:181], v[194:197], v[52:55]
	v_mfma_f32_16x16x32_bf16 v[48:51], v[186:189], v[194:197], v[48:51]
	v_mfma_f32_16x16x32_bf16 v[48:51], v[182:185], v[190:193], v[48:51]
	v_mfma_f32_16x16x32_bf16 v[32:35], v[182:185], v[198:201], v[32:35]
	v_mfma_f32_16x16x32_bf16 v[32:35], v[186:189], v[202:205], v[32:35]
	v_mfma_f32_16x16x32_bf16 v[36:39], v[178:181], v[202:205], v[36:39]
	v_mfma_f32_16x16x32_bf16 v[36:39], v[174:177], v[198:201], v[36:39]
	v_mfma_f32_16x16x32_bf16 v[20:23], v[174:177], v[206:209], v[20:23]
	v_mfma_f32_16x16x32_bf16 v[20:23], v[178:181], v[210:213], v[20:23]
	v_mfma_f32_16x16x32_bf16 v[16:19], v[186:189], v[210:213], v[16:19]
	v_mfma_f32_16x16x32_bf16 v[16:19], v[182:185], v[206:209], v[16:19]
	v_mfma_f32_16x16x32_bf16 v[0:3], v[182:185], v[214:217], v[0:3]
	v_mfma_f32_16x16x32_bf16 v[0:3], v[186:189], v[218:221], v[0:3]
	v_mfma_f32_16x16x32_bf16 v[4:7], v[178:181], v[218:221], v[4:7]
	v_mfma_f32_16x16x32_bf16 v[4:7], v[174:177], v[214:217], v[4:7]
	s_setprio 0
	s_barrier
	s_add_i32 s51, s51, 2
	s_add_u32 s30, s30, 0x100
	s_addc_u32 s31, s31, 0
	s_add_u32 s49, s49, 0x100
	s_addc_u32 s50, s50, 0
	s_cmp_gt_u32 s51, 29

; #define PG8_STAGE(bufoff, gbase, voff) do { _Pragma("unroll") for (int _i = 0; _i < 2; ++_i) \
;         __builtin_amdgcn_global_load_lds((const unsigned*)((const char*)(gbase) + (voff)[_i]), (LAS unsigned*)(lds + (bufoff) + ldsw + _i * 8192), 16, 0, 0); } while (0)
; #define PG8_LDA(dst, b, h) do { _Pragma("unroll") for (int m = 0; m < 4; ++m) _Pragma("unroll") for (int k = 0; k < 2; ++k) dst[m][k] = *(const LAS bf16x8*)(lds + PG8_SA(b, h) + aoff + m * 2048 + k * 1024); } while (0)
; #define PG8_LDB(dst, b, h) do { _Pragma("unroll") for (int n = 0; n < 2; ++n) _Pragma("unroll") for (int k = 0; k < 2; ++k) dst[n][k] = *(const LAS bf16x8*)(lds + PG8_SB(b, h) + boff + n * 2048 + k * 1024); } while (0)
; #define PG8_MMA(ai, bj, At, Bt) do { __builtin_amdgcn_s_setprio(1); _Pragma("unroll") for (int m = 0; m < 4; ++m) _Pragma("unroll") for (int n = 0; n < 2; ++n) _Pragma("unroll") for (int k = 0; k < 2; ++k) \
;         acc[ai][bj][m][n] = __builtin_amdgcn_mfma_f32_16x16x32_bf16(Bt[n][k], At[m][k], acc[ai][bj][m][n], 0, 0, 0); __builtin_amdgcn_s_setprio(0); } while (0)
; #define PG8_WAIT_V(n) asm volatile("s_waitcnt vmcnt(" #n ")" ::: "memory")
; #define PG8_WAIT_L(n) asm volatile("s_waitcnt lgkmcnt(" #n ")" ::: "memory")
; DI void gemm_phase(LAS unsigned char* lds, const Gemm g, const StaticOrder& S, const Epi& E) {
;     ...
;         const char* nA = has_next ? (const char*)g.A + (size_t)nxt.pm * tsA : cA; const char* nB = has_next ? (const char*)g.Bt + (size_t)nxt.pn * tsB : cB;
;         for (int t = 0; t < nt; t += 2) {
;             const bool last = (t == nt - 2);
;             const char* a1 = cA + (size_t)(t + 1) * kstep;
;             const char* a2 = last ? nA : cA + (size_t)(t + 2) * kstep; const char* b2 = last ? nB : cB + (size_t)(t + 2) * kstep;
;             const char* a3 = a2 + kstep; const char* b3 = b2 + kstep;
;             PG8_LDB(B0, 0, 0); PG8_LDB(B1, 0, 1); PG8_SCHED; PG8_LDA(At, 0, 0); PG8_STAGE(PG8_SA(1, 1), a1 + hsA, voffA);
;             PG8_WAIT_V(8); PG8_WAIT_L(0); PG8_BAR; PG8_MMA(0, 0, At, B0); PG8_MMA(0, 1, At, B1); PG8_BAR; PG8_SCHED;
;             PG8_LDA(At, 0, 1); PG8_STAGE(PG8_SB(0, 0), b2, voffB); PG8_STAGE(PG8_SB(0, 1), b2 + hsB, voffB); PG8_STAGE(PG8_SA(0, 0), a2, voffA);
;             PG8_WAIT_V(8); PG8_WAIT_L(0); PG8_BAR; PG8_MMA(1, 0, At, B0); PG8_MMA(1, 1, At, B1); PG8_BAR; PG8_SCHED;
.LBB0_1019:
	s_ashr_i32 s17, s16, 31
	s_lshl_b64 s[18:19], s[16:17], 20
	s_add_u32 s18, s62, s18
	s_addc_u32 s19, s63, s19
	s_and_b64 s[20:21], s[4:5], exec
	s_cselect_b32 s17, s19, s25
	s_cselect_b32 s41, s18, s24
	s_ashr_i32 s15, s14, 31
	s_lshl_b64 s[20:21], s[14:15], 20
	s_add_u32 s20, s0, s20
	s_addc_u32 s21, s1, s21
	s_and_b64 s[28:29], s[4:5], exec
	s_cselect_b32 s15, s21, s27
	s_cselect_b32 s42, s20, s26
	s_add_u32 s24, s24, 0x80080
	s_addc_u32 s25, s25, 0
	s_add_u32 s43, s26, 0x100
	v_mov_b32_e32 v0, 0
	s_addc_u32 s48, s27, 0
	s_mov_b32 s49, -2
	ds_read_b128 v[144:147], v155
	ds_read_b128 v[148:151], v155 offset:1024
	ds_read_b128 v[160:163], v155 offset:2048
	ds_read_b128 v[170:173], v155 offset:3072
	ds_read_b128 v[174:177], v156
	ds_read_b128 v[178:181], v156 offset:1024
	ds_read_b128 v[182:185], v156 offset:2048
	ds_read_b128 v[186:189], v156 offset:3072
	s_add_u32 s26, s24, 0xfff80080
	s_addc_u32 s27, s25, -1
	s_cmp_eq_u32 s49, 28
	s_cselect_b32 s29, s17, s27
	s_cselect_b32 s28, s41, s26
	s_cselect_b32 s27, s15, s48
	s_cselect_b32 s26, s42, s43
	s_add_i32 m0, s23, 0xc000
	ds_read_b128 v[190:193], v157
	ds_read_b128 v[194:197], v157 offset:1024
	ds_read_b128 v[198:201], v157 offset:2048
	ds_read_b128 v[202:205], v157 offset:3072
	ds_read_b128 v[206:209], v157 offset:4096
	ds_read_b128 v[210:213], v157 offset:5120
	ds_read_b128 v[214:217], v157 offset:6144
	ds_read_b128 v[218:221], v157 offset:7168
	global_load_lds_dwordx4 v136, s[24:25]
	s_add_i32 m0, s23, 0xe000
	s_nop 0
	global_load_lds_dwordx4 v138, s[24:25]
	s_waitcnt vmcnt(8)
	s_waitcnt lgkmcnt(0)
	s_barrier
	s_setprio 1
	s_waitcnt lgkmcnt(0)
	v_mfma_f32_16x16x32_bf16 v[124:127], v[144:147], v[190:193], 0
	v_mfma_f32_16x16x32_bf16 v[124:127], v[148:151], v[194:197], v[124:127]
	v_mfma_f32_16x16x32_bf16 v[120:123], v[170:173], v[194:197], 0
	v_mfma_f32_16x16x32_bf16 v[120:123], v[160:163], v[190:193], v[120:123]
	v_mfma_f32_16x16x32_bf16 v[104:107], v[160:163], v[198:201], 0
	v_mfma_f32_16x16x32_bf16 v[104:107], v[170:173], v[202:205], v[104:107]
	v_mfma_f32_16x16x32_bf16 v[108:111], v[148:151], v[202:205], 0
	v_mfma_f32_16x16x32_bf16 v[108:111], v[144:147], v[198:201], v[108:111]
	v_mfma_f32_16x16x32_bf16 v[92:95], v[144:147], v[206:209], 0
	v_mfma_f32_16x16x32_bf16 v[92:95], v[148:151], v[210:213], v[92:95]
	v_mfma_f32_16x16x32_bf16 v[88:91], v[170:173], v[210:213], 0
	v_mfma_f32_16x16x32_bf16 v[88:91], v[160:163], v[206:209], v[88:91]
	v_mfma_f32_16x16x32_bf16 v[72:75], v[160:163], v[214:217], 0
	v_mfma_f32_16x16x32_bf16 v[72:75], v[170:173], v[218:221], v[72:75]
	v_mfma_f32_16x16x32_bf16 v[76:79], v[148:151], v[218:221], 0
	v_mfma_f32_16x16x32_bf16 v[76:79], v[144:147], v[214:217], v[76:79]
	s_setprio 0
	s_setprio 1
	v_mfma_f32_16x16x32_bf16 v[116:119], v[174:177], v[190:193], 0
	v_mfma_f32_16x16x32_bf16 v[116:119], v[178:181], v[194:197], v[116:119]
	v_mfma_f32_16x16x32_bf16 v[112:115], v[186:189], v[194:197], 0
	v_mfma_f32_16x16x32_bf16 v[112:115], v[182:185], v[190:193], v[112:115]
	v_mfma_f32_16x16x32_bf16 v[96:99], v[182:185], v[198:201], 0
	v_mfma_f32_16x16x32_bf16 v[96:99], v[186:189], v[202:205], v[96:99]
	v_mfma_f32_16x16x32_bf16 v[100:103], v[178:181], v[202:205], 0
	v_mfma_f32_16x16x32_bf16 v[100:103], v[174:177], v[198:201], v[100:103]
	v_mfma_f32_16x16x32_bf16 v[84:87], v[174:177], v[206:209], 0
	v_mfma_f32_16x16x32_bf16 v[84:87], v[178:181], v[210:213], v[84:87]
	v_mfma_f32_16x16x32_bf16 v[80:83], v[186:189], v[210:213], 0
	v_mfma_f32_16x16x32_bf16 v[80:83], v[182:185], v[206:209], v[80:83]
	v_mfma_f32_16x16x32_bf16 v[64:67], v[182:185], v[214:217], 0
	v_mfma_f32_16x16x32_bf16 v[64:67], v[186:189], v[218:221], v[64:67]
	v_mfma_f32_16x16x32_bf16 v[68:71], v[178:181], v[218:221], 0
	v_mfma_f32_16x16x32_bf16 v[68:71], v[174:177], v[214:217], v[68:71]
	s_setprio 0
	s_barrier
	s_add_i32 s46, s37, s12
	s_add_u32 s98, s26, 0x80
	s_addc_u32 s99, s27, 0
	s_mov_b32 m0, s46
	ds_read_b128 v[190:193], v157 offset:16384
	ds_read_b128 v[194:197], v157 offset:17408
	ds_read_b128 v[198:201], v157 offset:18432
	ds_read_b128 v[202:205], v157 offset:19456
	ds_read_b128 v[206:209], v157 offset:20480
	ds_read_b128 v[210:213], v157 offset:21504
	ds_read_b128 v[214:217], v157 offset:22528
	ds_read_b128 v[218:221], v157 offset:23552
	global_load_lds_dwordx4 v132, s[26:27]
	s_add_i32 m0, s46, 0x2000
	s_add_u32 s46, s26, 0x80000
	s_addc_u32 s47, s27, 0
	s_add_i32 s50, s38, s12
	global_load_lds_dwordx4 v128, s[26:27]
	s_mov_b32 m0, s50
	s_nop 0
	global_load_lds_dwordx4 v132, s[46:47]
	s_add_i32 m0, s50, 0x2000
	s_nop 0
	global_load_lds_dwordx4 v128, s[46:47]
	s_add_u32 s100, s28, 0x80
	s_addc_u32 s101, s29, 0
	s_mov_b32 m0, s23
	s_nop 0
	global_load_lds_dwordx4 v134, s[28:29]
	s_mov_b32 m0, s30
	s_nop 0
	global_load_lds_dwordx4 v130, s[28:29]
	s_waitcnt vmcnt(8)
	s_waitcnt lgkmcnt(0)
	s_barrier
; #define PG8_STAGE(bufoff, gbase, voff) do { _Pragma("unroll") for (int _i = 0; _i < 2; ++_i) \
;         __builtin_amdgcn_global_load_lds((const unsigned*)((const char*)(gbase) + (voff)[_i]), (LAS unsigned*)(lds + (bufoff) + ldsw + _i * 8192), 16, 0, 0); } while (0)
; #define PG8_LDA(dst, b, h) do { _Pragma("unroll") for (int m = 0; m < 4; ++m) _Pragma("unroll") for (int k = 0; k < 2; ++k) dst[m][k] = *(const LAS bf16x8*)(lds + PG8_SA(b, h) + aoff + m * 2048 + k * 1024); } while (0)
; #define PG8_LDB(dst, b, h) do { _Pragma("unroll") for (int n = 0; n < 2; ++n) _Pragma("unroll") for (int k = 0; k < 2; ++k) dst[n][k] = *(const LAS bf16x8*)(lds + PG8_SB(b, h) + boff + n * 2048 + k * 1024); } while (0)
; #define PG8_MMA(ai, bj, At, Bt) do { __builtin_amdgcn_s_setprio(1); _Pragma("unroll") for (int m = 0; m < 4; ++m) _Pragma("unroll") for (int n = 0; n < 2; ++n) _Pragma("unroll") for (int k = 0; k < 2; ++k) \
;         acc[ai][bj][m][n] = __builtin_amdgcn_mfma_f32_16x16x32_bf16(Bt[n][k], At[m][k], acc[ai][bj][m][n], 0, 0, 0); __builtin_amdgcn_s_setprio(0); } while (0)
; #define PG8_WAIT_V(n) asm volatile("s_waitcnt vmcnt(" #n ")" ::: "memory")
; #define PG8_WAIT_L(n) asm volatile("s_waitcnt lgkmcnt(" #n ")" ::: "memory")
; #define PG8_BAR __builtin_amdgcn_s_barrier()
; #define PG8_SCHED __builtin_amdgcn_sched_barrier(0)
; DI void gemm_phase(LAS unsigned char* lds, const Gemm g, const StaticOrder& S, const Epi& E) {
;     ...
;             PG8_WAIT_V(8); PG8_WAIT_L(0); PG8_BAR; PG8_MMA(1, 0, At, B0); PG8_MMA(1, 1, At, B1); PG8_BAR; PG8_SCHED;
;             PG8_LDB(B0, 1, 0); PG8_LDB(B1, 1, 1); PG8_SCHED; PG8_LDA(At, 1, 0); PG8_STAGE(PG8_SA(0, 1), a2 + hsA, voffA);
;             PG8_WAIT_V(8); PG8_WAIT_L(0); PG8_BAR; PG8_MMA(0, 0, At, B0); PG8_MMA(0, 1, At, B1); PG8_BAR; PG8_SCHED;
	s_setprio 1
	s_waitcnt lgkmcnt(0)
	v_mfma_f32_16x16x32_bf16 v[60:63], v[144:147], v[190:193], 0
	v_mfma_f32_16x16x32_bf16 v[60:63], v[148:151], v[194:197], v[60:63]
	v_mfma_f32_16x16x32_bf16 v[56:59], v[170:173], v[194:197], 0
	v_mfma_f32_16x16x32_bf16 v[56:59], v[160:163], v[190:193], v[56:59]
	v_mfma_f32_16x16x32_bf16 v[40:43], v[160:163], v[198:201], 0
	v_mfma_f32_16x16x32_bf16 v[40:43], v[170:173], v[202:205], v[40:43]
	v_mfma_f32_16x16x32_bf16 v[44:47], v[148:151], v[202:205], 0
	v_mfma_f32_16x16x32_bf16 v[44:47], v[144:147], v[198:201], v[44:47]
	v_mfma_f32_16x16x32_bf16 v[28:31], v[144:147], v[206:209], 0
	v_mfma_f32_16x16x32_bf16 v[28:31], v[148:151], v[210:213], v[28:31]
	v_mfma_f32_16x16x32_bf16 v[24:27], v[170:173], v[210:213], 0
	v_mfma_f32_16x16x32_bf16 v[24:27], v[160:163], v[206:209], v[24:27]
	v_mfma_f32_16x16x32_bf16 v[8:11], v[160:163], v[214:217], 0
	v_mfma_f32_16x16x32_bf16 v[8:11], v[170:173], v[218:221], v[8:11]
	v_mfma_f32_16x16x32_bf16 v[12:15], v[148:151], v[218:221], 0
	v_mfma_f32_16x16x32_bf16 v[12:15], v[144:147], v[214:217], v[12:15]
	s_setprio 0
	s_setprio 1
	v_mfma_f32_16x16x32_bf16 v[52:55], v[174:177], v[190:193], 0
	v_mfma_f32_16x16x32_bf16 v[52:55], v[178:181], v[194:197], v[52:55]
	v_mfma_f32_16x16x32_bf16 v[48:51], v[186:189], v[194:197], 0
	v_mfma_f32_16x16x32_bf16 v[48:51], v[182:185], v[190:193], v[48:51]
	v_mfma_f32_16x16x32_bf16 v[32:35], v[182:185], v[198:201], 0
	v_mfma_f32_16x16x32_bf16 v[32:35], v[186:189], v[202:205], v[32:35]
	v_mfma_f32_16x16x32_bf16 v[36:39], v[178:181], v[202:205], 0
	v_mfma_f32_16x16x32_bf16 v[36:39], v[174:177], v[198:201], v[36:39]
	v_mfma_f32_16x16x32_bf16 v[20:23], v[174:177], v[206:209], 0
	v_mfma_f32_16x16x32_bf16 v[20:23], v[178:181], v[210:213], v[20:23]
	v_mfma_f32_16x16x32_bf16 v[16:19], v[186:189], v[210:213], 0
	v_mfma_f32_16x16x32_bf16 v[16:19], v[182:185], v[206:209], v[16:19]
	v_mfma_f32_16x16x32_bf16 v[0:3], v[182:185], v[214:217], 0
	v_mfma_f32_16x16x32_bf16 v[0:3], v[186:189], v[218:221], v[0:3]
	v_mfma_f32_16x16x32_bf16 v[4:7], v[178:181], v[218:221], 0
	v_mfma_f32_16x16x32_bf16 v[4:7], v[174:177], v[214:217], v[4:7]
	s_setprio 0
	s_barrier
	s_add_i32 s46, 0, 0x18000
	v_add_u32_e32 v159, s46, v153
	s_add_i32 s47, 0, 0x1c000
	ds_read_b128 v[144:147], v159
	ds_read_b128 v[148:151], v159 offset:1024
	ds_read_b128 v[160:163], v159 offset:2048
	ds_read_b128 v[170:173], v159 offset:3072
	v_add_u32_e32 v159, s47, v153
	ds_read_b128 v[174:177], v159
	ds_read_b128 v[178:181], v159 offset:1024
	ds_read_b128 v[182:185], v159 offset:2048
	ds_read_b128 v[186:189], v159 offset:3072
	s_add_u32 s28, s28, 0x80000
	s_addc_u32 s29, s29, 0
	s_mov_b32 m0, s31
	ds_read_b128 v[190:193], v157 offset:32768
	ds_read_b128 v[194:197], v157 offset:33792
	ds_read_b128 v[198:201], v157 offset:34816
	ds_read_b128 v[202:205], v157 offset:35840
	ds_read_b128 v[206:209], v157 offset:36864
	ds_read_b128 v[210:213], v157 offset:37888
	ds_read_b128 v[214:217], v157 offset:38912
	ds_read_b128 v[218:221], v157 offset:39936
	global_load_lds_dwordx4 v134, s[28:29]
	s_mov_b32 m0, s33
	s_nop 0
	global_load_lds_dwordx4 v130, s[28:29]
	s_waitcnt vmcnt(8)
	s_waitcnt lgkmcnt(0)
	s_barrier
	s_setprio 1
	s_waitcnt lgkmcnt(0)
	v_mfma_f32_16x16x32_bf16 v[124:127], v[144:147], v[190:193], v[124:127]
	v_mfma_f32_16x16x32_bf16 v[124:127], v[148:151], v[194:197], v[124:127]
	v_mfma_f32_16x16x32_bf16 v[120:123], v[170:173], v[194:197], v[120:123]
	v_mfma_f32_16x16x32_bf16 v[120:123], v[160:163], v[190:193], v[120:123]
	v_mfma_f32_16x16x32_bf16 v[104:107], v[160:163], v[198:201], v[104:107]
	v_mfma_f32_16x16x32_bf16 v[104:107], v[170:173], v[202:205], v[104:107]
	v_mfma_f32_16x16x32_bf16 v[108:111], v[148:151], v[202:205], v[108:111]
	v_mfma_f32_16x16x32_bf16 v[108:111], v[144:147], v[198:201], v[108:111]
	v_mfma_f32_16x16x32_bf16 v[92:95], v[144:147], v[206:209], v[92:95]
	v_mfma_f32_16x16x32_bf16 v[92:95], v[148:151], v[210:213], v[92:95]
	v_mfma_f32_16x16x32_bf16 v[88:91], v[170:173], v[210:213], v[88:91]
	v_mfma_f32_16x16x32_bf16 v[88:91], v[160:163], v[206:209], v[88:91]
	v_mfma_f32_16x16x32_bf16 v[72:75], v[160:163], v[214:217], v[72:75]
	v_mfma_f32_16x16x32_bf16 v[72:75], v[170:173], v[218:221], v[72:75]
	v_mfma_f32_16x16x32_bf16 v[76:79], v[148:151], v[218:221], v[76:79]
	v_mfma_f32_16x16x32_bf16 v[76:79], v[144:147], v[214:217], v[76:79]
	s_setprio 0
	s_setprio 1
	v_mfma_f32_16x16x32_bf16 v[116:119], v[174:177], v[190:193], v[116:119]
	v_mfma_f32_16x16x32_bf16 v[116:119], v[178:181], v[194:197], v[116:119]
	v_mfma_f32_16x16x32_bf16 v[112:115], v[186:189], v[194:197], v[112:115]
	v_mfma_f32_16x16x32_bf16 v[112:115], v[182:185], v[190:193], v[112:115]
	v_mfma_f32_16x16x32_bf16 v[96:99], v[182:185], v[198:201], v[96:99]
	v_mfma_f32_16x16x32_bf16 v[96:99], v[186:189], v[202:205], v[96:99]
	v_mfma_f32_16x16x32_bf16 v[100:103], v[178:181], v[202:205], v[100:103]
	v_mfma_f32_16x16x32_bf16 v[100:103], v[174:177], v[198:201], v[100:103]
	v_mfma_f32_16x16x32_bf16 v[84:87], v[174:177], v[206:209], v[84:87]
	v_mfma_f32_16x16x32_bf16 v[84:87], v[178:181], v[210:213], v[84:87]
	v_mfma_f32_16x16x32_bf16 v[80:83], v[186:189], v[210:213], v[80:83]
	v_mfma_f32_16x16x32_bf16 v[80:83], v[182:185], v[206:209], v[80:83]
	v_mfma_f32_16x16x32_bf16 v[64:67], v[182:185], v[214:217], v[64:67]
	v_mfma_f32_16x16x32_bf16 v[64:67], v[186:189], v[218:221], v[64:67]
	v_mfma_f32_16x16x32_bf16 v[68:71], v[178:181], v[218:221], v[68:71]
	v_mfma_f32_16x16x32_bf16 v[68:71], v[174:177], v[214:217], v[68:71]
	s_setprio 0
	s_barrier
; #define PG8_STAGE(bufoff, gbase, voff) do { _Pragma("unroll") for (int _i = 0; _i < 2; ++_i) \
;         __builtin_amdgcn_global_load_lds((const unsigned*)((const char*)(gbase) + (voff)[_i]), (LAS unsigned*)(lds + (bufoff) + ldsw + _i * 8192), 16, 0, 0); } while (0)
; #define PG8_LDA(dst, b, h) do { _Pragma("unroll") for (int m = 0; m < 4; ++m) _Pragma("unroll") for (int k = 0; k < 2; ++k) dst[m][k] = *(const LAS bf16x8*)(lds + PG8_SA(b, h) + aoff + m * 2048 + k * 1024); } while (0)
; #define PG8_MMA(ai, bj, At, Bt) do { __builtin_amdgcn_s_setprio(1); _Pragma("unroll") for (int m = 0; m < 4; ++m) _Pragma("unroll") for (int n = 0; n < 2; ++n) _Pragma("unroll") for (int k = 0; k < 2; ++k) \
;         acc[ai][bj][m][n] = __builtin_amdgcn_mfma_f32_16x16x32_bf16(Bt[n][k], At[m][k], acc[ai][bj][m][n], 0, 0, 0); __builtin_amdgcn_s_setprio(0); } while (0)
; #define PG8_WAIT_V(n) asm volatile("s_waitcnt vmcnt(" #n ")" ::: "memory")
; #define PG8_WAIT_L(n) asm volatile("s_waitcnt lgkmcnt(" #n ")" ::: "memory")
; #define PG8_BAR __builtin_amdgcn_s_barrier()
; #define PG8_SCHED __builtin_amdgcn_sched_barrier(0)
; DI void gemm_phase(LAS unsigned char* lds, const Gemm g, const StaticOrder& S, const Epi& E) {
;     ...
;             PG8_LDA(At, 1, 1); PG8_STAGE(PG8_SB(1, 0), b3, voffB); PG8_STAGE(PG8_SB(1, 1), b3 + hsB, voffB); PG8_STAGE(PG8_SA(1, 0), a3, voffA);
;             PG8_WAIT_V(8); PG8_WAIT_L(0); PG8_BAR; PG8_MMA(1, 0, At, B0); PG8_MMA(1, 1, At, B1); PG8_BAR; PG8_SCHED;
;         }
	s_add_i32 s28, s46, s12
	s_mov_b32 m0, s28
	ds_read_b128 v[190:193], v157 offset:49152
	ds_read_b128 v[194:197], v157 offset:50176
	ds_read_b128 v[198:201], v157 offset:51200
	ds_read_b128 v[202:205], v157 offset:52224
	ds_read_b128 v[206:209], v157 offset:53248
	ds_read_b128 v[210:213], v157 offset:54272
	ds_read_b128 v[214:217], v157 offset:55296
	ds_read_b128 v[218:221], v157 offset:56320
	global_load_lds_dwordx4 v132, s[98:99]
	s_add_i32 m0, s28, 0x2000
	s_add_u32 s26, s26, 0x80080
	s_addc_u32 s27, s27, 0
	s_add_i32 s28, s47, s12
	global_load_lds_dwordx4 v128, s[98:99]
	s_mov_b32 m0, s28
	s_nop 0
	global_load_lds_dwordx4 v132, s[26:27]
	s_add_i32 m0, s28, 0x2000
	s_nop 0
	global_load_lds_dwordx4 v128, s[26:27]
	s_mov_b32 m0, s35
	s_nop 0
	global_load_lds_dwordx4 v134, s[100:101]
	s_mov_b32 m0, s36
	s_nop 0
	global_load_lds_dwordx4 v130, s[100:101]
	s_waitcnt vmcnt(8)
	s_waitcnt lgkmcnt(0)
	s_barrier
	s_setprio 1
	s_waitcnt lgkmcnt(0)
	v_mfma_f32_16x16x32_bf16 v[60:63], v[144:147], v[190:193], v[60:63]
	v_mfma_f32_16x16x32_bf16 v[60:63], v[148:151], v[194:197], v[60:63]
	v_mfma_f32_16x16x32_bf16 v[56:59], v[170:173], v[194:197], v[56:59]
	v_mfma_f32_16x16x32_bf16 v[56:59], v[160:163], v[190:193], v[56:59]
	v_mfma_f32_16x16x32_bf16 v[40:43], v[160:163], v[198:201], v[40:43]
	v_mfma_f32_16x16x32_bf16 v[40:43], v[170:173], v[202:205], v[40:43]
	v_mfma_f32_16x16x32_bf16 v[44:47], v[148:151], v[202:205], v[44:47]
	v_mfma_f32_16x16x32_bf16 v[44:47], v[144:147], v[198:201], v[44:47]
	v_mfma_f32_16x16x32_bf16 v[28:31], v[144:147], v[206:209], v[28:31]
	v_mfma_f32_16x16x32_bf16 v[28:31], v[148:151], v[210:213], v[28:31]
	v_mfma_f32_16x16x32_bf16 v[24:27], v[170:173], v[210:213], v[24:27]
	v_mfma_f32_16x16x32_bf16 v[24:27], v[160:163], v[206:209], v[24:27]
	v_mfma_f32_16x16x32_bf16 v[8:11], v[160:163], v[214:217], v[8:11]
	v_mfma_f32_16x16x32_bf16 v[8:11], v[170:173], v[218:221], v[8:11]
	v_mfma_f32_16x16x32_bf16 v[12:15], v[148:151], v[218:221], v[12:15]
	v_mfma_f32_16x16x32_bf16 v[12:15], v[144:147], v[214:217], v[12:15]
	s_setprio 0
	s_setprio 1
	v_mfma_f32_16x16x32_bf16 v[52:55], v[174:177], v[190:193], v[52:55]
	v_mfma_f32_16x16x32_bf16 v[52:55], v[178:181], v[194:197], v[52:55]
	v_mfma_f32_16x16x32_bf16 v[48:51], v[186:189], v[194:197], v[48:51]
	v_mfma_f32_16x16x32_bf16 v[48:51], v[182:185], v[190:193], v[48:51]
	v_mfma_f32_16x16x32_bf16 v[32:35], v[182:185], v[198:201], v[32:35]
	v_mfma_f32_16x16x32_bf16 v[32:35], v[186:189], v[202:205], v[32:35]
	v_mfma_f32_16x16x32_bf16 v[36:39], v[178:181], v[202:205], v[36:39]
	v_mfma_f32_16x16x32_bf16 v[36:39], v[174:177], v[198:201], v[36:39]
	v_mfma_f32_16x16x32_bf16 v[20:23], v[174:177], v[206:209], v[20:23]
	v_mfma_f32_16x16x32_bf16 v[20:23], v[178:181], v[210:213], v[20:23]
	v_mfma_f32_16x16x32_bf16 v[16:19], v[186:189], v[210:213], v[16:19]
	v_mfma_f32_16x16x32_bf16 v[16:19], v[182:185], v[206:209], v[16:19]
	v_mfma_f32_16x16x32_bf16 v[0:3], v[182:185], v[214:217], v[0:3]
	v_mfma_f32_16x16x32_bf16 v[0:3], v[186:189], v[218:221], v[0:3]
	v_mfma_f32_16x16x32_bf16 v[4:7], v[178:181], v[218:221], v[4:7]
	v_mfma_f32_16x16x32_bf16 v[4:7], v[174:177], v[214:217], v[4:7]
	s_setprio 0
	s_barrier
	s_add_i32 s49, s49, 2
	s_add_u32 s24, s24, 0x100
	s_addc_u32 s25, s25, 0
	s_add_u32 s43, s43, 0x100
	s_addc_u32 s48, s48, 0
	s_cmp_gt_u32 s49, 29

; #define PG8_STAGE(bufoff, gbase, voff) do { _Pragma("unroll") for (int _i = 0; _i < 2; ++_i) \
;         __builtin_amdgcn_global_load_lds((const unsigned*)((const char*)(gbase) + (voff)[_i]), (LAS unsigned*)(lds + (bufoff) + ldsw + _i * 8192), 16, 0, 0); } while (0)
; #define PG8_LDA(dst, b, h) do { _Pragma("unroll") for (int m = 0; m < 4; ++m) _Pragma("unroll") for (int k = 0; k < 2; ++k) dst[m][k] = *(const LAS bf16x8*)(lds + PG8_SA(b, h) + aoff + m * 2048 + k * 1024); } while (0)
; #define PG8_LDB(dst, b, h) do { _Pragma("unroll") for (int n = 0; n < 2; ++n) _Pragma("unroll") for (int k = 0; k < 2; ++k) dst[n][k] = *(const LAS bf16x8*)(lds + PG8_SB(b, h) + boff + n * 2048 + k * 1024); } while (0)
; #define PG8_MMA(ai, bj, At, Bt) do { __builtin_amdgcn_s_setprio(1); _Pragma("unroll") for (int m = 0; m < 4; ++m) _Pragma("unroll") for (int n = 0; n < 2; ++n) _Pragma("unroll") for (int k = 0; k < 2; ++k) \
;         acc[ai][bj][m][n] = __builtin_amdgcn_mfma_f32_16x16x32_bf16(Bt[n][k], At[m][k], acc[ai][bj][m][n], 0, 0, 0); __builtin_amdgcn_s_setprio(0); } while (0)
; #define PG8_WAIT_V(n) asm volatile("s_waitcnt vmcnt(" #n ")" ::: "memory")
; #define PG8_WAIT_L(n) asm volatile("s_waitcnt lgkmcnt(" #n ")" ::: "memory")
; DI void gemm_phase(LAS unsigned char* lds, const Gemm g, const StaticOrder& S, const Epi& E) {
;     ...
;         const char* nA = has_next ? (const char*)g.A + (size_t)nxt.pm * tsA : cA; const char* nB = has_next ? (const char*)g.Bt + (size_t)nxt.pn * tsB : cB;
;         for (int t = 0; t < nt; t += 2) {
;             const bool last = (t == nt - 2);
;             const char* a1 = cA + (size_t)(t + 1) * kstep;
;             const char* a2 = last ? nA : cA + (size_t)(t + 2) * kstep; const char* b2 = last ? nB : cB + (size_t)(t + 2) * kstep;
;             const char* a3 = a2 + kstep; const char* b3 = b2 + kstep;
;             PG8_LDB(B0, 0, 0); PG8_LDB(B1, 0, 1); PG8_SCHED; PG8_LDA(At, 0, 0); PG8_STAGE(PG8_SA(1, 1), a1 + hsA, voffA);
;             PG8_WAIT_V(8); PG8_WAIT_L(0); PG8_BAR; PG8_MMA(0, 0, At, B0); PG8_MMA(0, 1, At, B1); PG8_BAR; PG8_SCHED;
;             PG8_LDA(At, 0, 1); PG8_STAGE(PG8_SB(0, 0), b2, voffB); PG8_STAGE(PG8_SB(0, 1), b2 + hsB, voffB); PG8_STAGE(PG8_SA(0, 0), a2, voffA);
;             PG8_WAIT_V(8); PG8_WAIT_L(0); PG8_BAR; PG8_MMA(1, 0, At, B0); PG8_MMA(1, 1, At, B1); PG8_BAR; PG8_SCHED;
.LBB0_1100:
	s_add_u32 s51, s26, 0x100
	v_mov_b32_e32 v0, 0
	s_addc_u32 s52, s27, 0
	s_mov_b32 s53, -2
	ds_read_b128 v[128:131], v165
	ds_read_b128 v[132:135], v165 offset:1024
	ds_read_b128 v[136:139], v165 offset:2048
	ds_read_b128 v[156:159], v165 offset:3072
	ds_read_b128 v[170:173], v166
	ds_read_b128 v[174:177], v166 offset:1024
	ds_read_b128 v[178:181], v166 offset:2048
	ds_read_b128 v[182:185], v166 offset:3072
	s_add_u32 s26, s24, 0x100
	s_addc_u32 s27, s25, 0
	s_cmpk_eq_i32 s53, 0x54
	s_cselect_b32 s31, s5, s27
	s_cselect_b32 s30, s4, s26
	s_cselect_b32 s29, s23, s52
	s_cselect_b32 s28, s22, s51
	s_add_i32 m0, s13, 0xc000
	ds_read_b128 v[186:189], v168
	ds_read_b128 v[190:193], v168 offset:1024
	ds_read_b128 v[194:197], v168 offset:2048
	ds_read_b128 v[198:201], v168 offset:3072
	ds_read_b128 v[202:205], v168 offset:4096
	ds_read_b128 v[206:209], v168 offset:5120
	ds_read_b128 v[210:213], v168 offset:6144
	ds_read_b128 v[214:217], v168 offset:7168
	global_load_lds_dwordx4 v148, s[24:25]
	s_add_i32 m0, s13, 0xe000
	s_nop 0
	global_load_lds_dwordx4 v150, s[24:25]
	s_waitcnt vmcnt(8)
	s_waitcnt lgkmcnt(0)
	s_barrier
	s_setprio 1
	s_waitcnt lgkmcnt(0)
	v_mfma_f32_16x16x32_bf16 v[124:127], v[128:131], v[186:189], 0
	v_mfma_f32_16x16x32_bf16 v[124:127], v[132:135], v[190:193], v[124:127]
	v_mfma_f32_16x16x32_bf16 v[120:123], v[156:159], v[190:193], 0
	v_mfma_f32_16x16x32_bf16 v[120:123], v[136:139], v[186:189], v[120:123]
	v_mfma_f32_16x16x32_bf16 v[104:107], v[136:139], v[194:197], 0
	v_mfma_f32_16x16x32_bf16 v[104:107], v[156:159], v[198:201], v[104:107]
	v_mfma_f32_16x16x32_bf16 v[112:115], v[132:135], v[198:201], 0
	v_mfma_f32_16x16x32_bf16 v[112:115], v[128:131], v[194:197], v[112:115]
	v_mfma_f32_16x16x32_bf16 v[92:95], v[128:131], v[202:205], 0
	v_mfma_f32_16x16x32_bf16 v[92:95], v[132:135], v[206:209], v[92:95]
	v_mfma_f32_16x16x32_bf16 v[88:91], v[156:159], v[206:209], 0
	v_mfma_f32_16x16x32_bf16 v[88:91], v[136:139], v[202:205], v[88:91]
	v_mfma_f32_16x16x32_bf16 v[72:75], v[136:139], v[210:213], 0
	v_mfma_f32_16x16x32_bf16 v[72:75], v[156:159], v[214:217], v[72:75]
	v_mfma_f32_16x16x32_bf16 v[76:79], v[132:135], v[214:217], 0
	v_mfma_f32_16x16x32_bf16 v[76:79], v[128:131], v[210:213], v[76:79]
	s_setprio 0
	s_setprio 1
	v_mfma_f32_16x16x32_bf16 v[116:119], v[170:173], v[186:189], 0
	v_mfma_f32_16x16x32_bf16 v[116:119], v[174:177], v[190:193], v[116:119]
	v_mfma_f32_16x16x32_bf16 v[108:111], v[182:185], v[190:193], 0
	v_mfma_f32_16x16x32_bf16 v[108:111], v[178:181], v[186:189], v[108:111]
	v_mfma_f32_16x16x32_bf16 v[96:99], v[178:181], v[194:197], 0
	v_mfma_f32_16x16x32_bf16 v[96:99], v[182:185], v[198:201], v[96:99]
	v_mfma_f32_16x16x32_bf16 v[100:103], v[174:177], v[198:201], 0
	v_mfma_f32_16x16x32_bf16 v[100:103], v[170:173], v[194:197], v[100:103]
	v_mfma_f32_16x16x32_bf16 v[84:87], v[170:173], v[202:205], 0
	v_mfma_f32_16x16x32_bf16 v[84:87], v[174:177], v[206:209], v[84:87]
	v_mfma_f32_16x16x32_bf16 v[80:83], v[182:185], v[206:209], 0
	v_mfma_f32_16x16x32_bf16 v[80:83], v[178:181], v[202:205], v[80:83]
	v_mfma_f32_16x16x32_bf16 v[64:67], v[178:181], v[210:213], 0
	v_mfma_f32_16x16x32_bf16 v[64:67], v[182:185], v[214:217], v[64:67]
	v_mfma_f32_16x16x32_bf16 v[68:71], v[174:177], v[214:217], 0
	v_mfma_f32_16x16x32_bf16 v[68:71], v[170:173], v[210:213], v[68:71]
	s_setprio 0
	s_barrier
	s_add_i32 s24, s39, s12
	s_add_u32 s98, s28, 0x80
	s_addc_u32 s99, s29, 0
	s_mov_b32 m0, s24
	ds_read_b128 v[186:189], v168 offset:16384
	ds_read_b128 v[190:193], v168 offset:17408
	ds_read_b128 v[194:197], v168 offset:18432
	ds_read_b128 v[198:201], v168 offset:19456
	ds_read_b128 v[202:205], v168 offset:20480
	ds_read_b128 v[206:209], v168 offset:21504
	ds_read_b128 v[210:213], v168 offset:22528
	ds_read_b128 v[214:217], v168 offset:23552
	global_load_lds_dwordx4 v142, s[28:29]
	s_add_i32 m0, s24, 0x2000
	s_add_u32 s24, s28, 0x160000
	s_addc_u32 s25, s29, 0
	s_add_i32 s54, s40, s12
	global_load_lds_dwordx4 v146, s[28:29]
	s_mov_b32 m0, s54
	s_nop 0
	global_load_lds_dwordx4 v142, s[24:25]
	s_add_i32 m0, s54, 0x2000
	s_nop 0
	global_load_lds_dwordx4 v146, s[24:25]
	s_add_u32 s100, s30, 0x80
	s_addc_u32 s101, s31, 0
	s_mov_b32 m0, s13
	s_nop 0
	global_load_lds_dwordx4 v140, s[30:31]
	s_mov_b32 m0, s33
	s_nop 0
	global_load_lds_dwordx4 v144, s[30:31]
	s_waitcnt vmcnt(8)
	s_waitcnt lgkmcnt(0)
	s_barrier
	s_setprio 1
	s_waitcnt lgkmcnt(0)
	v_mfma_f32_16x16x32_bf16 v[60:63], v[128:131], v[186:189], 0
	v_mfma_f32_16x16x32_bf16 v[60:63], v[132:135], v[190:193], v[60:63]
	v_mfma_f32_16x16x32_bf16 v[56:59], v[156:159], v[190:193], 0
	v_mfma_f32_16x16x32_bf16 v[56:59], v[136:139], v[186:189], v[56:59]
	v_mfma_f32_16x16x32_bf16 v[40:43], v[136:139], v[194:197], 0
	v_mfma_f32_16x16x32_bf16 v[40:43], v[156:159], v[198:201], v[40:43]
	v_mfma_f32_16x16x32_bf16 v[48:51], v[132:135], v[198:201], 0
	v_mfma_f32_16x16x32_bf16 v[48:51], v[128:131], v[194:197], v[48:51]
	v_mfma_f32_16x16x32_bf16 v[36:39], v[128:131], v[202:205], 0
	v_mfma_f32_16x16x32_bf16 v[36:39], v[132:135], v[206:209], v[36:39]
	v_mfma_f32_16x16x32_bf16 v[28:31], v[156:159], v[206:209], 0
	v_mfma_f32_16x16x32_bf16 v[28:31], v[136:139], v[202:205], v[28:31]
	v_mfma_f32_16x16x32_bf16 v[12:15], v[136:139], v[210:213], 0
	v_mfma_f32_16x16x32_bf16 v[12:15], v[156:159], v[214:217], v[12:15]
	v_mfma_f32_16x16x32_bf16 v[20:23], v[132:135], v[214:217], 0
	v_mfma_f32_16x16x32_bf16 v[20:23], v[128:131], v[210:213], v[20:23]
	s_setprio 0
	s_setprio 1
	v_mfma_f32_16x16x32_bf16 v[52:55], v[170:173], v[186:189], 0
	v_mfma_f32_16x16x32_bf16 v[52:55], v[174:177], v[190:193], v[52:55]
	v_mfma_f32_16x16x32_bf16 v[44:47], v[182:185], v[190:193], 0
	v_mfma_f32_16x16x32_bf16 v[44:47], v[178:181], v[186:189], v[44:47]
	v_mfma_f32_16x16x32_bf16 v[24:27], v[178:181], v[194:197], 0
	v_mfma_f32_16x16x32_bf16 v[24:27], v[182:185], v[198:201], v[24:27]
	v_mfma_f32_16x16x32_bf16 v[32:35], v[174:177], v[198:201], 0
	v_mfma_f32_16x16x32_bf16 v[32:35], v[170:173], v[194:197], v[32:35]
	v_mfma_f32_16x16x32_bf16 v[16:19], v[170:173], v[202:205], 0
	v_mfma_f32_16x16x32_bf16 v[16:19], v[174:177], v[206:209], v[16:19]
	v_mfma_f32_16x16x32_bf16 v[8:11], v[182:185], v[206:209], 0
	v_mfma_f32_16x16x32_bf16 v[8:11], v[178:181], v[202:205], v[8:11]
	v_mfma_f32_16x16x32_bf16 v[0:3], v[178:181], v[210:213], 0
	v_mfma_f32_16x16x32_bf16 v[0:3], v[182:185], v[214:217], v[0:3]
	v_mfma_f32_16x16x32_bf16 v[4:7], v[174:177], v[214:217], 0
	v_mfma_f32_16x16x32_bf16 v[4:7], v[170:173], v[210:213], v[4:7]
	s_setprio 0
	s_barrier
; #define PG8_STAGE(bufoff, gbase, voff) do { _Pragma("unroll") for (int _i = 0; _i < 2; ++_i) \
;         __builtin_amdgcn_global_load_lds((const unsigned*)((const char*)(gbase) + (voff)[_i]), (LAS unsigned*)(lds + (bufoff) + ldsw + _i * 8192), 16, 0, 0); } while (0)
; #define PG8_LDA(dst, b, h) do { _Pragma("unroll") for (int m = 0; m < 4; ++m) _Pragma("unroll") for (int k = 0; k < 2; ++k) dst[m][k] = *(const LAS bf16x8*)(lds + PG8_SA(b, h) + aoff + m * 2048 + k * 1024); } while (0)
; #define PG8_LDB(dst, b, h) do { _Pragma("unroll") for (int n = 0; n < 2; ++n) _Pragma("unroll") for (int k = 0; k < 2; ++k) dst[n][k] = *(const LAS bf16x8*)(lds + PG8_SB(b, h) + boff + n * 2048 + k * 1024); } while (0)
; #define PG8_MMA(ai, bj, At, Bt) do { __builtin_amdgcn_s_setprio(1); _Pragma("unroll") for (int m = 0; m < 4; ++m) _Pragma("unroll") for (int n = 0; n < 2; ++n) _Pragma("unroll") for (int k = 0; k < 2; ++k) \
;         acc[ai][bj][m][n] = __builtin_amdgcn_mfma_f32_16x16x32_bf16(Bt[n][k], At[m][k], acc[ai][bj][m][n], 0, 0, 0); __builtin_amdgcn_s_setprio(0); } while (0)
; #define PG8_WAIT_V(n) asm volatile("s_waitcnt vmcnt(" #n ")" ::: "memory")
; #define PG8_WAIT_L(n) asm volatile("s_waitcnt lgkmcnt(" #n ")" ::: "memory")
; #define PG8_BAR __builtin_amdgcn_s_barrier()
; #define PG8_SCHED __builtin_amdgcn_sched_barrier(0)
; DI void gemm_phase(LAS unsigned char* lds, const Gemm g, const StaticOrder& S, const Epi& E) {
;     ...
;             PG8_LDB(B0, 1, 0); PG8_LDB(B1, 1, 1); PG8_SCHED; PG8_LDA(At, 1, 0); PG8_STAGE(PG8_SA(0, 1), a2 + hsA, voffA);
;             PG8_WAIT_V(8); PG8_WAIT_L(0); PG8_BAR; PG8_MMA(0, 0, At, B0); PG8_MMA(0, 1, At, B1); PG8_BAR; PG8_SCHED;
;             PG8_LDA(At, 1, 1); PG8_STAGE(PG8_SB(1, 0), b3, voffB); PG8_STAGE(PG8_SB(1, 1), b3 + hsB, voffB); PG8_STAGE(PG8_SA(1, 0), a3, voffA);
;             PG8_WAIT_V(8); PG8_WAIT_L(0); PG8_BAR; PG8_MMA(1, 0, At, B0); PG8_MMA(1, 1, At, B1); PG8_BAR; PG8_SCHED;
;         }
	s_add_i32 s54, 0, 0x18000
	s_add_i32 s55, 0, 0x1c000
	v_add_u32_e32 v156, s54, v163
	v_add_u32_e32 v182, s55, v163
	ds_read_b128 v[128:131], v156
	ds_read_b128 v[132:135], v156 offset:1024
	ds_read_b128 v[136:139], v156 offset:2048
	ds_read_b128 v[156:159], v156 offset:3072
	ds_read_b128 v[170:173], v182
	ds_read_b128 v[174:177], v182 offset:1024
	ds_read_b128 v[178:181], v182 offset:2048
	ds_read_b128 v[182:185], v182 offset:3072
	s_add_u32 s24, s30, 0x160000
	s_addc_u32 s25, s31, 0
	s_mov_b32 m0, s34
	ds_read_b128 v[186:189], v168 offset:32768
	ds_read_b128 v[190:193], v168 offset:33792
	ds_read_b128 v[194:197], v168 offset:34816
	ds_read_b128 v[198:201], v168 offset:35840
	ds_read_b128 v[202:205], v168 offset:36864
	ds_read_b128 v[206:209], v168 offset:37888
	ds_read_b128 v[210:213], v168 offset:38912
	ds_read_b128 v[214:217], v168 offset:39936
	global_load_lds_dwordx4 v140, s[24:25]
	s_mov_b32 m0, s35
	s_nop 0
	global_load_lds_dwordx4 v144, s[24:25]
	s_waitcnt vmcnt(8)
	s_waitcnt lgkmcnt(0)
	s_barrier
	s_setprio 1
	s_waitcnt lgkmcnt(0)
	v_mfma_f32_16x16x32_bf16 v[124:127], v[128:131], v[186:189], v[124:127]
	v_mfma_f32_16x16x32_bf16 v[124:127], v[132:135], v[190:193], v[124:127]
	v_mfma_f32_16x16x32_bf16 v[120:123], v[156:159], v[190:193], v[120:123]
	v_mfma_f32_16x16x32_bf16 v[120:123], v[136:139], v[186:189], v[120:123]
	v_mfma_f32_16x16x32_bf16 v[104:107], v[136:139], v[194:197], v[104:107]
	v_mfma_f32_16x16x32_bf16 v[104:107], v[156:159], v[198:201], v[104:107]
	v_mfma_f32_16x16x32_bf16 v[112:115], v[132:135], v[198:201], v[112:115]
	v_mfma_f32_16x16x32_bf16 v[112:115], v[128:131], v[194:197], v[112:115]
	v_mfma_f32_16x16x32_bf16 v[92:95], v[128:131], v[202:205], v[92:95]
	v_mfma_f32_16x16x32_bf16 v[92:95], v[132:135], v[206:209], v[92:95]
	v_mfma_f32_16x16x32_bf16 v[88:91], v[156:159], v[206:209], v[88:91]
	v_mfma_f32_16x16x32_bf16 v[88:91], v[136:139], v[202:205], v[88:91]
	v_mfma_f32_16x16x32_bf16 v[72:75], v[136:139], v[210:213], v[72:75]
	v_mfma_f32_16x16x32_bf16 v[72:75], v[156:159], v[214:217], v[72:75]
	v_mfma_f32_16x16x32_bf16 v[76:79], v[132:135], v[214:217], v[76:79]
	v_mfma_f32_16x16x32_bf16 v[76:79], v[128:131], v[210:213], v[76:79]
	s_setprio 0
	s_setprio 1
	v_mfma_f32_16x16x32_bf16 v[116:119], v[170:173], v[186:189], v[116:119]
	v_mfma_f32_16x16x32_bf16 v[116:119], v[174:177], v[190:193], v[116:119]
	v_mfma_f32_16x16x32_bf16 v[108:111], v[182:185], v[190:193], v[108:111]
	v_mfma_f32_16x16x32_bf16 v[108:111], v[178:181], v[186:189], v[108:111]
	v_mfma_f32_16x16x32_bf16 v[96:99], v[178:181], v[194:197], v[96:99]
	v_mfma_f32_16x16x32_bf16 v[96:99], v[182:185], v[198:201], v[96:99]
	v_mfma_f32_16x16x32_bf16 v[100:103], v[174:177], v[198:201], v[100:103]
	v_mfma_f32_16x16x32_bf16 v[100:103], v[170:173], v[194:197], v[100:103]
	v_mfma_f32_16x16x32_bf16 v[84:87], v[170:173], v[202:205], v[84:87]
	v_mfma_f32_16x16x32_bf16 v[84:87], v[174:177], v[206:209], v[84:87]
	v_mfma_f32_16x16x32_bf16 v[80:83], v[182:185], v[206:209], v[80:83]
	v_mfma_f32_16x16x32_bf16 v[80:83], v[178:181], v[202:205], v[80:83]
	v_mfma_f32_16x16x32_bf16 v[64:67], v[178:181], v[210:213], v[64:67]
	v_mfma_f32_16x16x32_bf16 v[64:67], v[182:185], v[214:217], v[64:67]
	v_mfma_f32_16x16x32_bf16 v[68:71], v[174:177], v[214:217], v[68:71]
	v_mfma_f32_16x16x32_bf16 v[68:71], v[170:173], v[210:213], v[68:71]
	s_setprio 0
	s_barrier
	s_add_i32 s24, s54, s12
	s_mov_b32 m0, s24
	ds_read_b128 v[186:189], v168 offset:49152
	ds_read_b128 v[190:193], v168 offset:50176
	ds_read_b128 v[194:197], v168 offset:51200
	ds_read_b128 v[198:201], v168 offset:52224
	ds_read_b128 v[202:205], v168 offset:53248
	ds_read_b128 v[206:209], v168 offset:54272
	ds_read_b128 v[210:213], v168 offset:55296
	ds_read_b128 v[214:217], v168 offset:56320
	global_load_lds_dwordx4 v142, s[98:99]
	s_add_i32 m0, s24, 0x2000
	s_add_u32 s24, s28, 0x160080
	s_addc_u32 s25, s29, 0
	s_add_i32 s28, s55, s12
	global_load_lds_dwordx4 v146, s[98:99]
	s_mov_b32 m0, s28
	s_nop 0
	global_load_lds_dwordx4 v142, s[24:25]
	s_add_i32 m0, s28, 0x2000
	s_nop 0
	global_load_lds_dwordx4 v146, s[24:25]
	s_mov_b32 m0, s37
	s_nop 0
	global_load_lds_dwordx4 v140, s[100:101]
	s_mov_b32 m0, s38
	s_nop 0
	global_load_lds_dwordx4 v144, s[100:101]
	s_waitcnt vmcnt(8)
	s_waitcnt lgkmcnt(0)
	s_barrier
	s_setprio 1
	s_waitcnt lgkmcnt(0)
	v_mfma_f32_16x16x32_bf16 v[60:63], v[128:131], v[186:189], v[60:63]
	v_mfma_f32_16x16x32_bf16 v[60:63], v[132:135], v[190:193], v[60:63]
	v_mfma_f32_16x16x32_bf16 v[56:59], v[156:159], v[190:193], v[56:59]
	v_mfma_f32_16x16x32_bf16 v[56:59], v[136:139], v[186:189], v[56:59]
	v_mfma_f32_16x16x32_bf16 v[40:43], v[136:139], v[194:197], v[40:43]
	v_mfma_f32_16x16x32_bf16 v[40:43], v[156:159], v[198:201], v[40:43]
	v_mfma_f32_16x16x32_bf16 v[48:51], v[132:135], v[198:201], v[48:51]
	v_mfma_f32_16x16x32_bf16 v[48:51], v[128:131], v[194:197], v[48:51]
	v_mfma_f32_16x16x32_bf16 v[36:39], v[128:131], v[202:205], v[36:39]
	v_mfma_f32_16x16x32_bf16 v[36:39], v[132:135], v[206:209], v[36:39]
	v_mfma_f32_16x16x32_bf16 v[28:31], v[156:159], v[206:209], v[28:31]
	v_mfma_f32_16x16x32_bf16 v[28:31], v[136:139], v[202:205], v[28:31]
	v_mfma_f32_16x16x32_bf16 v[12:15], v[136:139], v[210:213], v[12:15]
	v_mfma_f32_16x16x32_bf16 v[12:15], v[156:159], v[214:217], v[12:15]
	v_mfma_f32_16x16x32_bf16 v[20:23], v[132:135], v[214:217], v[20:23]
	v_mfma_f32_16x16x32_bf16 v[20:23], v[128:131], v[210:213], v[20:23]
	s_setprio 0
	s_setprio 1
	v_mfma_f32_16x16x32_bf16 v[52:55], v[170:173], v[186:189], v[52:55]
	v_mfma_f32_16x16x32_bf16 v[52:55], v[174:177], v[190:193], v[52:55]
	v_mfma_f32_16x16x32_bf16 v[44:47], v[182:185], v[190:193], v[44:47]
	v_mfma_f32_16x16x32_bf16 v[44:47], v[178:181], v[186:189], v[44:47]
	v_mfma_f32_16x16x32_bf16 v[24:27], v[178:181], v[194:197], v[24:27]
	v_mfma_f32_16x16x32_bf16 v[24:27], v[182:185], v[198:201], v[24:27]
	v_mfma_f32_16x16x32_bf16 v[32:35], v[174:177], v[198:201], v[32:35]
	v_mfma_f32_16x16x32_bf16 v[32:35], v[170:173], v[194:197], v[32:35]
	v_mfma_f32_16x16x32_bf16 v[16:19], v[170:173], v[202:205], v[16:19]
	v_mfma_f32_16x16x32_bf16 v[16:19], v[174:177], v[206:209], v[16:19]
	v_mfma_f32_16x16x32_bf16 v[8:11], v[182:185], v[206:209], v[8:11]
	v_mfma_f32_16x16x32_bf16 v[8:11], v[178:181], v[202:205], v[8:11]
	v_mfma_f32_16x16x32_bf16 v[0:3], v[178:181], v[210:213], v[0:3]
	v_mfma_f32_16x16x32_bf16 v[0:3], v[182:185], v[214:217], v[0:3]
	v_mfma_f32_16x16x32_bf16 v[4:7], v[174:177], v[214:217], v[4:7]
	v_mfma_f32_16x16x32_bf16 v[4:7], v[170:173], v[210:213], v[4:7]
	s_setprio 0
	s_barrier
	s_add_i32 s53, s53, 2
	s_add_u32 s51, s51, 0x100
	s_addc_u32 s52, s52, 0
	s_cmpk_gt_u32 s53, 0x55
	s_mov_b64 s[24:25], s[26:27]
